# K-loops: lgkmcnt(0) for the MFMA operands waited before the pre-MFMA barrier instead of after it (plus earlier trims)
# baseline (speedup 1.0000x reference)
; #define PG8_STAGE(bufoff, gbase, voff) do { _Pragma("unroll") for (int _i = 0; _i < 2; ++_i) \
;         __builtin_amdgcn_global_load_lds((const unsigned*)((const char*)(gbase) + (voff)[_i]), (LAS unsigned*)(lds + (bufoff) + ldsw + _i * 8192), 16, 0, 0); } while (0)
; #define PG8_LDA(dst, b, h) do { _Pragma("unroll") for (int m = 0; m < 4; ++m) _Pragma("unroll") for (int k = 0; k < 2; ++k) dst[m][k] = *(const LAS bf16x8*)(lds + PG8_SA(b, h) + aoff + m * 2048 + k * 1024); } while (0)
; #define PG8_LDB(dst, b, h) do { _Pragma("unroll") for (int n = 0; n < 2; ++n) _Pragma("unroll") for (int k = 0; k < 2; ++k) dst[n][k] = *(const LAS bf16x8*)(lds + PG8_SB(b, h) + boff + n * 2048 + k * 1024); } while (0)
; #define PG8_MMA(ai, bj, At, Bt) do { __builtin_amdgcn_s_setprio(1); _Pragma("unroll") for (int m = 0; m < 4; ++m) _Pragma("unroll") for (int n = 0; n < 2; ++n) _Pragma("unroll") for (int k = 0; k < 2; ++k) \
;         acc[ai][bj][m][n] = __builtin_amdgcn_mfma_f32_16x16x32_bf16(Bt[n][k], At[m][k], acc[ai][bj][m][n], 0, 0, 0); __builtin_amdgcn_s_setprio(0); } while (0)
; #define PG8_WAIT_L(n) asm volatile("s_waitcnt lgkmcnt(" #n ")" ::: "memory")
; template <int MODE, class EpiT, class Sched>
; __device__ __forceinline__ void gemm_phase(LAS unsigned char* lds, const Gemm g, const Sched& S, const EpiT& E) {
;     ...
;         const bool has_next = S.next(ui + 1, nxt);
;         const char* nA = has_next ? (const char*)g.A + (size_t)nxt.pm * tstep : cA; const char* nB = has_next ? (const char*)g.Bt + (size_t)nxt.pn * tstep : cB;
;         for (int t = 0; t < nt; t += 2) {
;             const bool last = (t == nt - 2);
;             const char* a1 = cA + (size_t)(t + 1) * kstep;
;             const char* a2 = last ? nA : cA + (size_t)(t + 2) * kstep; const char* b2 = last ? nB : cB + (size_t)(t + 2) * kstep;
;             const char* a3 = a2 + kstep; const char* b3 = b2 + kstep;
;             PG8_LDB(B0, 0, 0); PG8_SCHED; PG8_LDA(At, 0, 0); PG8_STAGE(PG8_SA(1, 1), a1 + hstep, voffA);
;             PG8_WAIT_L(8); PG8_BAR; PG8_WAIT_L(0); PG8_MMA(0, 0, At, B0); PG8_BAR; PG8_SCHED;
;             PG8_LDB(B1, 0, 1); PG8_STAGE(PG8_SB(0, 0), b2, voffB);
;             PG8_BAR; PG8_WAIT_L(0); PG8_MMA(0, 1, At, B1); PG8_BAR;
;             PG8_LDA(At, 0, 1); PG8_STAGE(PG8_SA(0, 0), a2, voffA);
;             PG8_BAR; PG8_WAIT_L(0); PG8_MMA(1, 0, At, B0); PG8_BAR; PG8_SCHED;
.LBB0_115:
	s_add_i32 s58, s52, 2
	s_add_u32 s59, s44, 0x80
	s_addc_u32 s53, s45, 0
	s_add_i32 s91, 0, 0x10000
	v_add_u32_e32 v86, s91, v192
	ds_read_b128 v[70:73], v86
	ds_read_b128 v[74:77], v86 offset:1024
	ds_read_b128 v[82:85], v86 offset:2048
	ds_read_b128 v[86:89], v86 offset:3072
	s_cmp_eq_u32 s57, s52
	s_cselect_b32 s52, s4, s59
	s_cselect_b32 s53, s5, s53
	s_cselect_b32 s75, s47, vcc_hi
	s_cselect_b32 s74, s46, vcc_lo
	v_lshl_add_u64 v[188:189], s[44:45], 0, v[176:177]
	s_add_i32 m0, s20, 0xc000
	ds_read_b128 v[138:141], v194
	ds_read_b128 v[142:145], v194 offset:1024
	ds_read_b128 v[146:149], v194 offset:2048
	ds_read_b128 v[154:157], v194 offset:3072
	ds_read_b128 v[162:165], v194 offset:4096
	ds_read_b128 v[166:169], v194 offset:5120
	ds_read_b128 v[170:173], v194 offset:6144
	ds_read_b128 v[184:187], v194 offset:7168
	global_load_lds_dwordx4 v[188:189], off
	v_lshl_add_u64 v[188:189], s[44:45], 0, v[182:183]
	s_add_i32 m0, s20, 0xe000
	s_nop 0
	global_load_lds_dwordx4 v[188:189], off
	s_waitcnt lgkmcnt(0)
	s_barrier
	v_mfma_f32_16x16x32_bf16 v[158:161], v[70:73], v[138:141], v[158:161]
	v_mfma_f32_16x16x32_bf16 v[150:153], v[82:85], v[138:141], v[150:153]
	v_mfma_f32_16x16x32_bf16 v[126:129], v[70:73], v[146:149], v[126:129]
	v_mfma_f32_16x16x32_bf16 v[122:125], v[82:85], v[146:149], v[122:125]
	v_mfma_f32_16x16x32_bf16 v[110:113], v[70:73], v[162:165], v[110:113]
	v_mfma_f32_16x16x32_bf16 v[106:109], v[82:85], v[162:165], v[106:109]
	v_mfma_f32_16x16x32_bf16 v[94:97], v[70:73], v[170:173], v[94:97]
	v_mfma_f32_16x16x32_bf16 v[90:93], v[82:85], v[170:173], v[90:93]
	v_mfma_f32_16x16x32_bf16 v[158:161], v[74:77], v[142:145], v[158:161]
	v_mfma_f32_16x16x32_bf16 v[150:153], v[86:89], v[142:145], v[150:153]
	v_mfma_f32_16x16x32_bf16 v[126:129], v[74:77], v[154:157], v[126:129]
	v_mfma_f32_16x16x32_bf16 v[122:125], v[86:89], v[154:157], v[122:125]
	v_mfma_f32_16x16x32_bf16 v[110:113], v[74:77], v[166:169], v[110:113]
	v_mfma_f32_16x16x32_bf16 v[106:109], v[86:89], v[166:169], v[106:109]
	v_mfma_f32_16x16x32_bf16 v[94:97], v[74:77], v[184:187], v[94:97]
	v_mfma_f32_16x16x32_bf16 v[90:93], v[86:89], v[184:187], v[90:93]
	s_barrier
	s_add_i32 s59, 0, 0x14000
	s_add_i32 s91, s91, s9
	v_add_u32_e32 v195, s59, v192
	v_lshl_add_u64 v[228:229], s[74:75], 0, v[0:1]
	s_mov_b32 m0, s91
	ds_read_b128 v[188:191], v195
	ds_read_b128 v[196:199], v195 offset:1024
	ds_read_b128 v[220:223], v195 offset:2048
	ds_read_b128 v[224:227], v195 offset:3072
	global_load_lds_dwordx4 v[228:229], off
	v_lshl_add_u64 v[230:231], s[74:75], 0, v[174:175]
	s_add_i32 m0, s91, 0x2000
	s_nop 0
	global_load_lds_dwordx4 v[230:231], off
	s_waitcnt lgkmcnt(0)
	s_barrier
	v_mfma_f32_16x16x32_bf16 v[134:137], v[188:191], v[138:141], v[134:137]
	v_mfma_f32_16x16x32_bf16 v[130:133], v[220:223], v[138:141], v[130:133]
	v_mfma_f32_16x16x32_bf16 v[118:121], v[188:191], v[146:149], v[118:121]
	v_mfma_f32_16x16x32_bf16 v[114:117], v[220:223], v[146:149], v[114:117]
	v_mfma_f32_16x16x32_bf16 v[102:105], v[188:191], v[162:165], v[102:105]
	v_mfma_f32_16x16x32_bf16 v[98:101], v[220:223], v[162:165], v[98:101]
	v_mfma_f32_16x16x32_bf16 v[78:81], v[188:191], v[170:173], v[78:81]
	v_mfma_f32_16x16x32_bf16 v[66:69], v[220:223], v[170:173], v[66:69]
	v_mfma_f32_16x16x32_bf16 v[134:137], v[196:199], v[142:145], v[134:137]
	v_mfma_f32_16x16x32_bf16 v[130:133], v[224:227], v[142:145], v[130:133]
	v_mfma_f32_16x16x32_bf16 v[118:121], v[196:199], v[154:157], v[118:121]
	v_mfma_f32_16x16x32_bf16 v[114:117], v[224:227], v[154:157], v[114:117]
	v_mfma_f32_16x16x32_bf16 v[102:105], v[196:199], v[166:169], v[102:105]
	v_mfma_f32_16x16x32_bf16 v[98:101], v[224:227], v[166:169], v[98:101]
	v_mfma_f32_16x16x32_bf16 v[78:81], v[196:199], v[184:187], v[78:81]
	v_mfma_f32_16x16x32_bf16 v[66:69], v[224:227], v[184:187], v[66:69]
	s_barrier
	s_mov_b32 m0, s20
	v_lshl_add_u64 v[232:233], s[52:53], 0, v[0:1]
	ds_read_b128 v[138:141], v194 offset:16384
	ds_read_b128 v[142:145], v194 offset:17408
	ds_read_b128 v[146:149], v194 offset:18432
	ds_read_b128 v[154:157], v194 offset:19456
	ds_read_b128 v[162:165], v194 offset:20480
	ds_read_b128 v[166:169], v194 offset:21504
	ds_read_b128 v[170:173], v194 offset:22528
	ds_read_b128 v[184:187], v194 offset:23552
	global_load_lds_dwordx4 v[232:233], off
	v_lshl_add_u64 v[234:235], s[52:53], 0, v[174:175]
	s_mov_b32 m0, s21
	s_nop 0
	global_load_lds_dwordx4 v[234:235], off
	s_waitcnt lgkmcnt(0)
	s_barrier
	v_mfma_f32_16x16x32_bf16 v[62:65], v[70:73], v[138:141], v[62:65]
	v_mfma_f32_16x16x32_bf16 v[58:61], v[82:85], v[138:141], v[58:61]
	v_mfma_f32_16x16x32_bf16 v[46:49], v[70:73], v[146:149], v[46:49]
	v_mfma_f32_16x16x32_bf16 v[42:45], v[82:85], v[146:149], v[42:45]
	v_mfma_f32_16x16x32_bf16 v[30:33], v[70:73], v[162:165], v[30:33]
	v_mfma_f32_16x16x32_bf16 v[26:29], v[82:85], v[162:165], v[26:29]
	v_mfma_f32_16x16x32_bf16 v[14:17], v[70:73], v[170:173], v[14:17]
	v_mfma_f32_16x16x32_bf16 v[10:13], v[82:85], v[170:173], v[10:13]
	v_mfma_f32_16x16x32_bf16 v[62:65], v[74:77], v[142:145], v[62:65]
	v_mfma_f32_16x16x32_bf16 v[58:61], v[86:89], v[142:145], v[58:61]
	v_mfma_f32_16x16x32_bf16 v[46:49], v[74:77], v[154:157], v[46:49]
	v_mfma_f32_16x16x32_bf16 v[42:45], v[86:89], v[154:157], v[42:45]
	v_mfma_f32_16x16x32_bf16 v[30:33], v[74:77], v[166:169], v[30:33]
	v_mfma_f32_16x16x32_bf16 v[26:29], v[86:89], v[166:169], v[26:29]
	v_mfma_f32_16x16x32_bf16 v[14:17], v[74:77], v[184:187], v[14:17]
	v_mfma_f32_16x16x32_bf16 v[10:13], v[86:89], v[184:187], v[10:13]
	s_barrier
; #define PG8_STAGE(bufoff, gbase, voff) do { _Pragma("unroll") for (int _i = 0; _i < 2; ++_i) \
;         __builtin_amdgcn_global_load_lds((const unsigned*)((const char*)(gbase) + (voff)[_i]), (LAS unsigned*)(lds + (bufoff) + ldsw + _i * 8192), 16, 0, 0); } while (0)
; #define PG8_LDA(dst, b, h) do { _Pragma("unroll") for (int m = 0; m < 4; ++m) _Pragma("unroll") for (int k = 0; k < 2; ++k) dst[m][k] = *(const LAS bf16x8*)(lds + PG8_SA(b, h) + aoff + m * 2048 + k * 1024); } while (0)
; #define PG8_LDB(dst, b, h) do { _Pragma("unroll") for (int n = 0; n < 2; ++n) _Pragma("unroll") for (int k = 0; k < 2; ++k) dst[n][k] = *(const LAS bf16x8*)(lds + PG8_SB(b, h) + boff + n * 2048 + k * 1024); } while (0)
; #define PG8_MMA(ai, bj, At, Bt) do { __builtin_amdgcn_s_setprio(1); _Pragma("unroll") for (int m = 0; m < 4; ++m) _Pragma("unroll") for (int n = 0; n < 2; ++n) _Pragma("unroll") for (int k = 0; k < 2; ++k) \
;         acc[ai][bj][m][n] = __builtin_amdgcn_mfma_f32_16x16x32_bf16(Bt[n][k], At[m][k], acc[ai][bj][m][n], 0, 0, 0); __builtin_amdgcn_s_setprio(0); } while (0)
; #define PG8_WAIT_V(n) asm volatile("s_waitcnt vmcnt(" #n ")" ::: "memory")
; #define PG8_WAIT_L(n) asm volatile("s_waitcnt lgkmcnt(" #n ")" ::: "memory")
; #define PG8_BAR __builtin_amdgcn_s_barrier()
; #define PG8_SCHED __builtin_amdgcn_sched_barrier(0)
; template <int MODE, class EpiT, class Sched>
; __device__ __forceinline__ void gemm_phase(LAS unsigned char* lds, const Gemm g, const Sched& S, const EpiT& E) {
;     ...
;             PG8_STAGE(PG8_SB(0, 1), b2 + hstep, voffB);
;             PG8_WAIT_V(6); PG8_BAR; PG8_MMA(1, 1, At, B1); PG8_BAR;
;             PG8_LDB(B0, 1, 0); PG8_SCHED; PG8_LDA(At, 1, 0); PG8_STAGE(PG8_SA(0, 1), a2 + hstep, voffA);
;             PG8_WAIT_L(8); PG8_BAR; PG8_WAIT_L(0); PG8_MMA(0, 0, At, B0); PG8_BAR; PG8_SCHED;
;             PG8_LDB(B1, 1, 1); PG8_STAGE(PG8_SB(1, 0), b3, voffB);
;             PG8_BAR; PG8_WAIT_L(0); PG8_MMA(0, 1, At, B1); PG8_BAR;
;             PG8_LDA(At, 1, 1); PG8_STAGE(PG8_SA(1, 0), a3, voffA);
;             PG8_BAR; PG8_WAIT_L(0); PG8_MMA(1, 0, At, B0); PG8_BAR; PG8_SCHED;
	s_add_u32 s74, s74, s78
	s_addc_u32 s75, s75, 0
	s_add_i32 s59, s59, s9
	v_lshl_add_u64 v[236:237], s[74:75], 0, v[0:1]
	s_mov_b32 m0, s59
	v_lshl_add_u64 v[238:239], s[74:75], 0, v[174:175]
	global_load_lds_dwordx4 v[236:237], off
	s_add_i32 m0, s59, 0x2000
	s_nop 0
	global_load_lds_dwordx4 v[238:239], off
	s_waitcnt vmcnt(6)
	s_barrier
	v_mfma_f32_16x16x32_bf16 v[54:57], v[188:191], v[138:141], v[54:57]
	v_mfma_f32_16x16x32_bf16 v[50:53], v[220:223], v[138:141], v[50:53]
	v_mfma_f32_16x16x32_bf16 v[38:41], v[188:191], v[146:149], v[38:41]
	v_mfma_f32_16x16x32_bf16 v[34:37], v[220:223], v[146:149], v[34:37]
	v_mfma_f32_16x16x32_bf16 v[22:25], v[188:191], v[162:165], v[22:25]
	v_mfma_f32_16x16x32_bf16 v[18:21], v[220:223], v[162:165], v[18:21]
	v_mfma_f32_16x16x32_bf16 v[6:9], v[188:191], v[170:173], v[6:9]
	v_mfma_f32_16x16x32_bf16 v[2:5], v[220:223], v[170:173], v[2:5]
	v_mfma_f32_16x16x32_bf16 v[54:57], v[196:199], v[142:145], v[54:57]
	v_mfma_f32_16x16x32_bf16 v[50:53], v[224:227], v[142:145], v[50:53]
	v_mfma_f32_16x16x32_bf16 v[38:41], v[196:199], v[154:157], v[38:41]
	v_mfma_f32_16x16x32_bf16 v[34:37], v[224:227], v[154:157], v[34:37]
	v_mfma_f32_16x16x32_bf16 v[22:25], v[196:199], v[166:169], v[22:25]
	v_mfma_f32_16x16x32_bf16 v[18:21], v[224:227], v[166:169], v[18:21]
	v_mfma_f32_16x16x32_bf16 v[6:9], v[196:199], v[184:187], v[6:9]
	v_mfma_f32_16x16x32_bf16 v[2:5], v[224:227], v[184:187], v[2:5]
	s_barrier
	s_add_i32 s59, 0, 0x18000
	v_add_u32_e32 v86, s59, v192
	ds_read_b128 v[70:73], v86
	ds_read_b128 v[74:77], v86 offset:1024
	ds_read_b128 v[82:85], v86 offset:2048
	ds_read_b128 v[86:89], v86 offset:3072
	s_add_u32 s52, s52, s78
	s_addc_u32 s53, s53, 0
	s_mov_b32 m0, s22
	v_lshl_add_u64 v[188:189], s[52:53], 0, v[0:1]
	ds_read_b128 v[138:141], v194 offset:32768
	ds_read_b128 v[142:145], v194 offset:33792
	ds_read_b128 v[146:149], v194 offset:34816
	ds_read_b128 v[154:157], v194 offset:35840
	ds_read_b128 v[162:165], v194 offset:36864
	ds_read_b128 v[166:169], v194 offset:37888
	ds_read_b128 v[170:173], v194 offset:38912
	ds_read_b128 v[184:187], v194 offset:39936
	global_load_lds_dwordx4 v[188:189], off
	v_lshl_add_u64 v[188:189], s[52:53], 0, v[174:175]
	s_mov_b32 m0, s23
	s_nop 0
	global_load_lds_dwordx4 v[188:189], off
	s_waitcnt lgkmcnt(0)
	s_barrier
	v_mfma_f32_16x16x32_bf16 v[158:161], v[70:73], v[138:141], v[158:161]
	v_mfma_f32_16x16x32_bf16 v[150:153], v[82:85], v[138:141], v[150:153]
	v_mfma_f32_16x16x32_bf16 v[126:129], v[70:73], v[146:149], v[126:129]
	v_mfma_f32_16x16x32_bf16 v[122:125], v[82:85], v[146:149], v[122:125]
	v_mfma_f32_16x16x32_bf16 v[110:113], v[70:73], v[162:165], v[110:113]
	v_mfma_f32_16x16x32_bf16 v[106:109], v[82:85], v[162:165], v[106:109]
	v_mfma_f32_16x16x32_bf16 v[94:97], v[70:73], v[170:173], v[94:97]
	v_mfma_f32_16x16x32_bf16 v[90:93], v[82:85], v[170:173], v[90:93]
	v_mfma_f32_16x16x32_bf16 v[158:161], v[74:77], v[142:145], v[158:161]
	v_mfma_f32_16x16x32_bf16 v[150:153], v[86:89], v[142:145], v[150:153]
	v_mfma_f32_16x16x32_bf16 v[126:129], v[74:77], v[154:157], v[126:129]
	v_mfma_f32_16x16x32_bf16 v[122:125], v[86:89], v[154:157], v[122:125]
	v_mfma_f32_16x16x32_bf16 v[110:113], v[74:77], v[166:169], v[110:113]
	v_mfma_f32_16x16x32_bf16 v[106:109], v[86:89], v[166:169], v[106:109]
	v_mfma_f32_16x16x32_bf16 v[94:97], v[74:77], v[184:187], v[94:97]
	v_mfma_f32_16x16x32_bf16 v[90:93], v[86:89], v[184:187], v[90:93]
	s_barrier
	s_add_i32 s52, 0, 0x1c000
	s_add_i32 s53, s59, s9
	v_add_u32_e32 v195, s52, v192
	v_lshl_add_u64 v[228:229], v[228:229], 0, s[76:77]
	s_mov_b32 m0, s53
	ds_read_b128 v[188:191], v195
	ds_read_b128 v[196:199], v195 offset:1024
	ds_read_b128 v[220:223], v195 offset:2048
	ds_read_b128 v[224:227], v195 offset:3072
	global_load_lds_dwordx4 v[228:229], off
	v_lshl_add_u64 v[228:229], v[230:231], 0, s[76:77]
	s_add_i32 m0, s53, 0x2000
	s_nop 0
	global_load_lds_dwordx4 v[228:229], off
	s_waitcnt lgkmcnt(0)
	s_barrier
; #define PG8_STAGE(bufoff, gbase, voff) do { _Pragma("unroll") for (int _i = 0; _i < 2; ++_i) \
;         __builtin_amdgcn_global_load_lds((const unsigned*)((const char*)(gbase) + (voff)[_i]), (LAS unsigned*)(lds + (bufoff) + ldsw + _i * 8192), 16, 0, 0); } while (0)
; #define PG8_MMA(ai, bj, At, Bt) do { __builtin_amdgcn_s_setprio(1); _Pragma("unroll") for (int m = 0; m < 4; ++m) _Pragma("unroll") for (int n = 0; n < 2; ++n) _Pragma("unroll") for (int k = 0; k < 2; ++k) \
;         acc[ai][bj][m][n] = __builtin_amdgcn_mfma_f32_16x16x32_bf16(Bt[n][k], At[m][k], acc[ai][bj][m][n], 0, 0, 0); __builtin_amdgcn_s_setprio(0); } while (0)
; #define PG8_WAIT_V(n) asm volatile("s_waitcnt vmcnt(" #n ")" ::: "memory")
; #define PG8_WAIT_L(n) asm volatile("s_waitcnt lgkmcnt(" #n ")" ::: "memory")
; #define PG8_BAR __builtin_amdgcn_s_barrier()
; #define PG8_SCHED __builtin_amdgcn_sched_barrier(0)
;     template <int mode> __device__ __forceinline__ void run(const f32x4 (&acc)[2][2][4][2], const Unit& u, int wr, int wc, int fr, int fq, const LAS float* sc) const {
;     ...
;             const int col0 = u.pn * BM + wc * 32 + 8 * fq;
;             f32x4 bv[2][2];
; #pragma unroll
;             for (int bj = 0; bj < 2; ++bj)
; #pragma unroll
;                 for (int n = 0; n < 2; ++n) bv[bj][n] = bias ? *(const f32x4*)(bias + col0 + bj * HALF + 4 * n) : (f32x4){0.f, 0.f, 0.f, 0.f};
; template <int MODE, class EpiT, class Sched>
; __device__ __forceinline__ void gemm_phase(LAS unsigned char* lds, const Gemm g, const Sched& S, const EpiT& E) {
;     ...
;             PG8_BAR; PG8_WAIT_L(0); PG8_MMA(1, 0, At, B0); PG8_BAR; PG8_SCHED;
;             PG8_STAGE(PG8_SB(1, 1), b3 + hstep, voffB);
;             PG8_WAIT_V(6); PG8_BAR; PG8_MMA(1, 1, At, B1); PG8_BAR;
	v_mfma_f32_16x16x32_bf16 v[134:137], v[188:191], v[138:141], v[134:137]
	v_mfma_f32_16x16x32_bf16 v[130:133], v[220:223], v[138:141], v[130:133]
	v_mfma_f32_16x16x32_bf16 v[118:121], v[188:191], v[146:149], v[118:121]
	v_mfma_f32_16x16x32_bf16 v[114:117], v[220:223], v[146:149], v[114:117]
	v_mfma_f32_16x16x32_bf16 v[102:105], v[188:191], v[162:165], v[102:105]
	v_mfma_f32_16x16x32_bf16 v[98:101], v[220:223], v[162:165], v[98:101]
	v_mfma_f32_16x16x32_bf16 v[78:81], v[188:191], v[170:173], v[78:81]
	v_mfma_f32_16x16x32_bf16 v[66:69], v[220:223], v[170:173], v[66:69]
	v_mfma_f32_16x16x32_bf16 v[134:137], v[196:199], v[142:145], v[134:137]
	v_mfma_f32_16x16x32_bf16 v[130:133], v[224:227], v[142:145], v[130:133]
	v_mfma_f32_16x16x32_bf16 v[118:121], v[196:199], v[154:157], v[118:121]
	v_mfma_f32_16x16x32_bf16 v[114:117], v[224:227], v[154:157], v[114:117]
	v_mfma_f32_16x16x32_bf16 v[102:105], v[196:199], v[166:169], v[102:105]
	v_mfma_f32_16x16x32_bf16 v[98:101], v[224:227], v[166:169], v[98:101]
	v_mfma_f32_16x16x32_bf16 v[78:81], v[196:199], v[184:187], v[78:81]
	v_mfma_f32_16x16x32_bf16 v[66:69], v[224:227], v[184:187], v[66:69]
	s_barrier
	s_mov_b32 m0, s51
	v_lshl_add_u64 v[228:229], v[232:233], 0, s[76:77]
	ds_read_b128 v[138:141], v194 offset:49152
	ds_read_b128 v[142:145], v194 offset:50176
	ds_read_b128 v[146:149], v194 offset:51200
	ds_read_b128 v[154:157], v194 offset:52224
	ds_read_b128 v[162:165], v194 offset:53248
	ds_read_b128 v[166:169], v194 offset:54272
	ds_read_b128 v[170:173], v194 offset:55296
	ds_read_b128 v[184:187], v194 offset:56320
	global_load_lds_dwordx4 v[228:229], off
	v_lshl_add_u64 v[228:229], v[234:235], 0, s[76:77]
	s_mov_b32 m0, s56
	s_nop 0
	global_load_lds_dwordx4 v[228:229], off
	s_waitcnt lgkmcnt(0)
	s_barrier
	v_mfma_f32_16x16x32_bf16 v[62:65], v[70:73], v[138:141], v[62:65]
	v_mfma_f32_16x16x32_bf16 v[58:61], v[82:85], v[138:141], v[58:61]
	v_mfma_f32_16x16x32_bf16 v[46:49], v[70:73], v[146:149], v[46:49]
	v_mfma_f32_16x16x32_bf16 v[42:45], v[82:85], v[146:149], v[42:45]
	v_mfma_f32_16x16x32_bf16 v[30:33], v[70:73], v[162:165], v[30:33]
	v_mfma_f32_16x16x32_bf16 v[26:29], v[82:85], v[162:165], v[26:29]
	v_mfma_f32_16x16x32_bf16 v[14:17], v[70:73], v[170:173], v[14:17]
	v_mfma_f32_16x16x32_bf16 v[10:13], v[82:85], v[170:173], v[10:13]
	v_mfma_f32_16x16x32_bf16 v[62:65], v[74:77], v[142:145], v[62:65]
	v_mfma_f32_16x16x32_bf16 v[58:61], v[86:89], v[142:145], v[58:61]
	v_mfma_f32_16x16x32_bf16 v[46:49], v[74:77], v[154:157], v[46:49]
	v_mfma_f32_16x16x32_bf16 v[42:45], v[86:89], v[154:157], v[42:45]
	v_mfma_f32_16x16x32_bf16 v[30:33], v[74:77], v[166:169], v[30:33]
	v_mfma_f32_16x16x32_bf16 v[26:29], v[86:89], v[166:169], v[26:29]
	v_mfma_f32_16x16x32_bf16 v[14:17], v[74:77], v[184:187], v[14:17]
	v_mfma_f32_16x16x32_bf16 v[10:13], v[86:89], v[184:187], v[10:13]
	s_barrier
	s_add_i32 s52, s52, s9
	v_lshl_add_u64 v[70:71], v[236:237], 0, s[76:77]
	s_mov_b32 m0, s52
	s_nop 0
	global_load_lds_dwordx4 v[70:71], off
	v_lshl_add_u64 v[70:71], v[238:239], 0, s[76:77]
	s_add_i32 m0, s52, 0x2000
	s_nop 0
	global_load_lds_dwordx4 v[70:71], off
	s_waitcnt vmcnt(6)
	s_barrier
	v_mfma_f32_16x16x32_bf16 v[54:57], v[188:191], v[138:141], v[54:57]
	v_mfma_f32_16x16x32_bf16 v[50:53], v[220:223], v[138:141], v[50:53]
	v_mfma_f32_16x16x32_bf16 v[38:41], v[188:191], v[146:149], v[38:41]
	v_mfma_f32_16x16x32_bf16 v[34:37], v[220:223], v[146:149], v[34:37]
	v_mfma_f32_16x16x32_bf16 v[22:25], v[188:191], v[162:165], v[22:25]
	v_mfma_f32_16x16x32_bf16 v[18:21], v[220:223], v[162:165], v[18:21]
	v_mfma_f32_16x16x32_bf16 v[6:9], v[188:191], v[170:173], v[6:9]
	v_mfma_f32_16x16x32_bf16 v[2:5], v[220:223], v[170:173], v[2:5]
	v_mfma_f32_16x16x32_bf16 v[54:57], v[196:199], v[142:145], v[54:57]
	v_mfma_f32_16x16x32_bf16 v[50:53], v[224:227], v[142:145], v[50:53]
	v_mfma_f32_16x16x32_bf16 v[38:41], v[196:199], v[154:157], v[38:41]
	v_mfma_f32_16x16x32_bf16 v[34:37], v[224:227], v[154:157], v[34:37]
	v_mfma_f32_16x16x32_bf16 v[22:25], v[196:199], v[166:169], v[22:25]
	v_mfma_f32_16x16x32_bf16 v[18:21], v[224:227], v[166:169], v[18:21]
	v_mfma_f32_16x16x32_bf16 v[6:9], v[196:199], v[184:187], v[6:9]
	v_mfma_f32_16x16x32_bf16 v[2:5], v[224:227], v[184:187], v[2:5]
	s_barrier
	s_add_u32 s44, s44, 0x100
	s_addc_u32 s45, s45, 0
	s_add_u32 vcc_lo, vcc_lo, 0x100
	s_addc_u32 vcc_hi, vcc_hi, 0
	s_cmp_ge_u32 s58, s50
	s_mov_b32 s52, s58
	s_cbranch_scc0 .LBB0_115
	v_lshl_or_b32 v184, s24, 8, v193
	v_ashrrev_i32_e32 v185, 31, v184
	v_mov_b32_e32 v74, 0
	v_cndmask_b32_e64 v70, 0, 1, s[68:69]
	v_lshl_add_u64 v[138:139], v[184:185], 2, s[12:13]
	v_cmp_ne_u32_e64 s[44:45], 1, v70
	s_andn2_b64 vcc, exec, s[68:69]
	v_mov_b32_e32 v86, 0
	v_mov_b32_e32 v87, v74
	v_mov_b32_e32 v186, 0
	v_mov_b32_e32 v187, v74
	s_cbranch_vccnz .LBB0_118
	global_load_dwordx4 v[86:89], v[138:139], off
	s_waitcnt vmcnt(0)
	v_mov_b32_e32 v186, v88
	v_mov_b32_e32 v187, v89

; #define PG8_STAGE(bufoff, gbase, voff) do { _Pragma("unroll") for (int _i = 0; _i < 2; ++_i) \
;         __builtin_amdgcn_global_load_lds((const unsigned*)((const char*)(gbase) + (voff)[_i]), (LAS unsigned*)(lds + (bufoff) + ldsw + _i * 8192), 16, 0, 0); } while (0)
; #define PG8_LDA(dst, b, h) do { _Pragma("unroll") for (int m = 0; m < 4; ++m) _Pragma("unroll") for (int k = 0; k < 2; ++k) dst[m][k] = *(const LAS bf16x8*)(lds + PG8_SA(b, h) + aoff + m * 2048 + k * 1024); } while (0)
; #define PG8_LDB(dst, b, h) do { _Pragma("unroll") for (int n = 0; n < 2; ++n) _Pragma("unroll") for (int k = 0; k < 2; ++k) dst[n][k] = *(const LAS bf16x8*)(lds + PG8_SB(b, h) + boff + n * 2048 + k * 1024); } while (0)
; #define PG8_MMA(ai, bj, At, Bt) do { __builtin_amdgcn_s_setprio(1); _Pragma("unroll") for (int m = 0; m < 4; ++m) _Pragma("unroll") for (int n = 0; n < 2; ++n) _Pragma("unroll") for (int k = 0; k < 2; ++k) \
;         acc[ai][bj][m][n] = __builtin_amdgcn_mfma_f32_16x16x32_bf16(Bt[n][k], At[m][k], acc[ai][bj][m][n], 0, 0, 0); __builtin_amdgcn_s_setprio(0); } while (0)
; #define PG8_WAIT_L(n) asm volatile("s_waitcnt lgkmcnt(" #n ")" ::: "memory")
; template <int MODE, class EpiT, class Sched>
; __device__ __forceinline__ void gemm_phase(LAS unsigned char* lds, const Gemm g, const Sched& S, const EpiT& E) {
;     ...
;         const bool has_next = S.next(ui + 1, nxt);
;         const char* nA = has_next ? (const char*)g.A + (size_t)nxt.pm * tstep : cA; const char* nB = has_next ? (const char*)g.Bt + (size_t)nxt.pn * tstep : cB;
;         for (int t = 0; t < nt; t += 2) {
;             const bool last = (t == nt - 2);
;             const char* a1 = cA + (size_t)(t + 1) * kstep;
;             const char* a2 = last ? nA : cA + (size_t)(t + 2) * kstep; const char* b2 = last ? nB : cB + (size_t)(t + 2) * kstep;
;             const char* a3 = a2 + kstep; const char* b3 = b2 + kstep;
;             PG8_LDB(B0, 0, 0); PG8_SCHED; PG8_LDA(At, 0, 0); PG8_STAGE(PG8_SA(1, 1), a1 + hstep, voffA);
;             PG8_WAIT_L(8); PG8_BAR; PG8_WAIT_L(0); PG8_MMA(0, 0, At, B0); PG8_BAR; PG8_SCHED;
;             PG8_LDB(B1, 0, 1); PG8_STAGE(PG8_SB(0, 0), b2, voffB);
;             PG8_BAR; PG8_WAIT_L(0); PG8_MMA(0, 1, At, B1); PG8_BAR;
;             PG8_LDA(At, 0, 1); PG8_STAGE(PG8_SA(0, 0), a2, voffA);
;             PG8_BAR; PG8_WAIT_L(0); PG8_MMA(1, 0, At, B0); PG8_BAR; PG8_SCHED;
.LBB0_159:
	s_add_i32 s89, s30, 2
	s_add_u32 s44, s4, 0x80
	s_addc_u32 s45, s5, 0
	s_add_i32 s58, 0, 0x10000
	v_add_u32_e32 v142, s58, v220
	ds_read_b128 v[130:133], v142
	ds_read_b128 v[134:137], v142 offset:1024
	ds_read_b128 v[138:141], v142 offset:2048
	ds_read_b128 v[142:145], v142 offset:3072
	s_cmp_eq_u32 s61, s30
	s_cselect_b32 s45, s79, s45
	s_cselect_b32 s44, s78, s44
	s_cselect_b32 s53, s47, s24
	s_cselect_b32 s52, s46, s23
	v_lshl_add_u64 v[188:189], s[4:5], 0, v[184:185]
	s_add_i32 m0, s69, 0xc000
	ds_read_b128 v[146:149], v223
	ds_read_b128 v[150:153], v223 offset:1024
	ds_read_b128 v[154:157], v223 offset:2048
	ds_read_b128 v[158:161], v223 offset:3072
	ds_read_b128 v[162:165], v223 offset:4096
	ds_read_b128 v[166:169], v223 offset:5120
	ds_read_b128 v[170:173], v223 offset:6144
	ds_read_b128 v[174:177], v223 offset:7168
	global_load_lds_dwordx4 v[188:189], off
	v_lshl_add_u64 v[188:189], s[4:5], 0, v[186:187]
	s_add_i32 m0, s69, 0xe000
	s_nop 0
	global_load_lds_dwordx4 v[188:189], off
	s_waitcnt lgkmcnt(0)
	s_barrier
	v_mfma_f32_16x16x32_bf16 v[126:129], v[130:133], v[146:149], v[126:129]
	v_mfma_f32_16x16x32_bf16 v[122:125], v[138:141], v[146:149], v[122:125]
	v_mfma_f32_16x16x32_bf16 v[110:113], v[130:133], v[154:157], v[110:113]
	v_mfma_f32_16x16x32_bf16 v[106:109], v[138:141], v[154:157], v[106:109]
	v_mfma_f32_16x16x32_bf16 v[94:97], v[130:133], v[162:165], v[94:97]
	v_mfma_f32_16x16x32_bf16 v[90:93], v[138:141], v[162:165], v[90:93]
	v_mfma_f32_16x16x32_bf16 v[78:81], v[130:133], v[170:173], v[78:81]
	v_mfma_f32_16x16x32_bf16 v[74:77], v[138:141], v[170:173], v[74:77]
	v_mfma_f32_16x16x32_bf16 v[126:129], v[134:137], v[150:153], v[126:129]
	v_mfma_f32_16x16x32_bf16 v[122:125], v[142:145], v[150:153], v[122:125]
	v_mfma_f32_16x16x32_bf16 v[110:113], v[134:137], v[158:161], v[110:113]
	v_mfma_f32_16x16x32_bf16 v[106:109], v[142:145], v[158:161], v[106:109]
	v_mfma_f32_16x16x32_bf16 v[94:97], v[134:137], v[166:169], v[94:97]
	v_mfma_f32_16x16x32_bf16 v[90:93], v[142:145], v[166:169], v[90:93]
	v_mfma_f32_16x16x32_bf16 v[78:81], v[134:137], v[174:177], v[78:81]
	v_mfma_f32_16x16x32_bf16 v[74:77], v[142:145], v[174:177], v[74:77]
	s_barrier
	s_add_i32 s30, 0, 0x14000
	s_add_i32 s58, s58, s68
	v_add_u32_e32 v200, s30, v220
	v_lshl_add_u64 v[228:229], s[52:53], 0, v[0:1]
	s_mov_b32 m0, s58
	ds_read_b128 v[188:191], v200
	ds_read_b128 v[192:195], v200 offset:1024
	ds_read_b128 v[196:199], v200 offset:2048
	ds_read_b128 v[224:227], v200 offset:3072
	global_load_lds_dwordx4 v[228:229], off
	v_lshl_add_u64 v[230:231], s[52:53], 0, v[182:183]
	s_add_i32 m0, s58, 0x2000
	s_nop 0
	global_load_lds_dwordx4 v[230:231], off
	s_waitcnt lgkmcnt(0)
	s_barrier
	v_mfma_f32_16x16x32_bf16 v[118:121], v[188:191], v[146:149], v[118:121]
	v_mfma_f32_16x16x32_bf16 v[114:117], v[196:199], v[146:149], v[114:117]
	v_mfma_f32_16x16x32_bf16 v[102:105], v[188:191], v[154:157], v[102:105]
	v_mfma_f32_16x16x32_bf16 v[98:101], v[196:199], v[154:157], v[98:101]
	v_mfma_f32_16x16x32_bf16 v[86:89], v[188:191], v[162:165], v[86:89]
	v_mfma_f32_16x16x32_bf16 v[82:85], v[196:199], v[162:165], v[82:85]
	v_mfma_f32_16x16x32_bf16 v[70:73], v[188:191], v[170:173], v[70:73]
	v_mfma_f32_16x16x32_bf16 v[66:69], v[196:199], v[170:173], v[66:69]
	v_mfma_f32_16x16x32_bf16 v[118:121], v[192:195], v[150:153], v[118:121]
	v_mfma_f32_16x16x32_bf16 v[114:117], v[224:227], v[150:153], v[114:117]
	v_mfma_f32_16x16x32_bf16 v[102:105], v[192:195], v[158:161], v[102:105]
	v_mfma_f32_16x16x32_bf16 v[98:101], v[224:227], v[158:161], v[98:101]
	v_mfma_f32_16x16x32_bf16 v[86:89], v[192:195], v[166:169], v[86:89]
	v_mfma_f32_16x16x32_bf16 v[82:85], v[224:227], v[166:169], v[82:85]
	v_mfma_f32_16x16x32_bf16 v[70:73], v[192:195], v[174:177], v[70:73]
	v_mfma_f32_16x16x32_bf16 v[66:69], v[224:227], v[174:177], v[66:69]
	s_barrier
	s_mov_b32 m0, s69
	v_lshl_add_u64 v[232:233], s[44:45], 0, v[0:1]
	ds_read_b128 v[146:149], v223 offset:16384
	ds_read_b128 v[150:153], v223 offset:17408
	ds_read_b128 v[154:157], v223 offset:18432
	ds_read_b128 v[158:161], v223 offset:19456
	ds_read_b128 v[162:165], v223 offset:20480
	ds_read_b128 v[166:169], v223 offset:21504
	ds_read_b128 v[170:173], v223 offset:22528
	ds_read_b128 v[174:177], v223 offset:23552
	global_load_lds_dwordx4 v[232:233], off
	v_lshl_add_u64 v[234:235], s[44:45], 0, v[182:183]
	s_mov_b32 m0, s74
	s_nop 0
	global_load_lds_dwordx4 v[234:235], off
	s_waitcnt lgkmcnt(0)
	s_barrier
	v_mfma_f32_16x16x32_bf16 v[62:65], v[130:133], v[146:149], v[62:65]
	v_mfma_f32_16x16x32_bf16 v[58:61], v[138:141], v[146:149], v[58:61]
	v_mfma_f32_16x16x32_bf16 v[46:49], v[130:133], v[154:157], v[46:49]
	v_mfma_f32_16x16x32_bf16 v[42:45], v[138:141], v[154:157], v[42:45]
	v_mfma_f32_16x16x32_bf16 v[30:33], v[130:133], v[162:165], v[30:33]
	v_mfma_f32_16x16x32_bf16 v[26:29], v[138:141], v[162:165], v[26:29]
	v_mfma_f32_16x16x32_bf16 v[14:17], v[130:133], v[170:173], v[14:17]
	v_mfma_f32_16x16x32_bf16 v[10:13], v[138:141], v[170:173], v[10:13]
	v_mfma_f32_16x16x32_bf16 v[62:65], v[134:137], v[150:153], v[62:65]
	v_mfma_f32_16x16x32_bf16 v[58:61], v[142:145], v[150:153], v[58:61]
	v_mfma_f32_16x16x32_bf16 v[46:49], v[134:137], v[158:161], v[46:49]
	v_mfma_f32_16x16x32_bf16 v[42:45], v[142:145], v[158:161], v[42:45]
	v_mfma_f32_16x16x32_bf16 v[30:33], v[134:137], v[166:169], v[30:33]
	v_mfma_f32_16x16x32_bf16 v[26:29], v[142:145], v[166:169], v[26:29]
	v_mfma_f32_16x16x32_bf16 v[14:17], v[134:137], v[174:177], v[14:17]
	v_mfma_f32_16x16x32_bf16 v[10:13], v[142:145], v[174:177], v[10:13]
	s_barrier
; #define PG8_STAGE(bufoff, gbase, voff) do { _Pragma("unroll") for (int _i = 0; _i < 2; ++_i) \
;         __builtin_amdgcn_global_load_lds((const unsigned*)((const char*)(gbase) + (voff)[_i]), (LAS unsigned*)(lds + (bufoff) + ldsw + _i * 8192), 16, 0, 0); } while (0)
; #define PG8_LDA(dst, b, h) do { _Pragma("unroll") for (int m = 0; m < 4; ++m) _Pragma("unroll") for (int k = 0; k < 2; ++k) dst[m][k] = *(const LAS bf16x8*)(lds + PG8_SA(b, h) + aoff + m * 2048 + k * 1024); } while (0)
; #define PG8_LDB(dst, b, h) do { _Pragma("unroll") for (int n = 0; n < 2; ++n) _Pragma("unroll") for (int k = 0; k < 2; ++k) dst[n][k] = *(const LAS bf16x8*)(lds + PG8_SB(b, h) + boff + n * 2048 + k * 1024); } while (0)
; #define PG8_MMA(ai, bj, At, Bt) do { __builtin_amdgcn_s_setprio(1); _Pragma("unroll") for (int m = 0; m < 4; ++m) _Pragma("unroll") for (int n = 0; n < 2; ++n) _Pragma("unroll") for (int k = 0; k < 2; ++k) \
;         acc[ai][bj][m][n] = __builtin_amdgcn_mfma_f32_16x16x32_bf16(Bt[n][k], At[m][k], acc[ai][bj][m][n], 0, 0, 0); __builtin_amdgcn_s_setprio(0); } while (0)
; #define PG8_WAIT_V(n) asm volatile("s_waitcnt vmcnt(" #n ")" ::: "memory")
; #define PG8_WAIT_L(n) asm volatile("s_waitcnt lgkmcnt(" #n ")" ::: "memory")
; #define PG8_BAR __builtin_amdgcn_s_barrier()
; #define PG8_SCHED __builtin_amdgcn_sched_barrier(0)
; template <int MODE, class EpiT, class Sched>
; __device__ __forceinline__ void gemm_phase(LAS unsigned char* lds, const Gemm g, const Sched& S, const EpiT& E) {
;     ...
;             PG8_STAGE(PG8_SB(0, 1), b2 + hstep, voffB);
;             PG8_WAIT_V(6); PG8_BAR; PG8_MMA(1, 1, At, B1); PG8_BAR;
;             PG8_LDB(B0, 1, 0); PG8_SCHED; PG8_LDA(At, 1, 0); PG8_STAGE(PG8_SA(0, 1), a2 + hstep, voffA);
;             PG8_WAIT_L(8); PG8_BAR; PG8_WAIT_L(0); PG8_MMA(0, 0, At, B0); PG8_BAR; PG8_SCHED;
;             PG8_LDB(B1, 1, 1); PG8_STAGE(PG8_SB(1, 0), b3, voffB);
;             PG8_BAR; PG8_WAIT_L(0); PG8_MMA(0, 1, At, B1); PG8_BAR;
;             PG8_LDA(At, 1, 1); PG8_STAGE(PG8_SA(1, 0), a3, voffA);
;             PG8_BAR; PG8_WAIT_L(0); PG8_MMA(1, 0, At, B0); PG8_BAR; PG8_SCHED;
	s_add_u32 s52, s52, s38
	s_addc_u32 s53, s53, 0
	s_add_i32 s30, s30, s68
	v_lshl_add_u64 v[236:237], s[52:53], 0, v[0:1]
	s_mov_b32 m0, s30
	v_lshl_add_u64 v[238:239], s[52:53], 0, v[182:183]
	global_load_lds_dwordx4 v[236:237], off
	s_add_i32 m0, s30, 0x2000
	s_nop 0
	global_load_lds_dwordx4 v[238:239], off
	s_waitcnt vmcnt(6)
	s_barrier
	v_mfma_f32_16x16x32_bf16 v[54:57], v[188:191], v[146:149], v[54:57]
	v_mfma_f32_16x16x32_bf16 v[50:53], v[196:199], v[146:149], v[50:53]
	v_mfma_f32_16x16x32_bf16 v[38:41], v[188:191], v[154:157], v[38:41]
	v_mfma_f32_16x16x32_bf16 v[34:37], v[196:199], v[154:157], v[34:37]
	v_mfma_f32_16x16x32_bf16 v[22:25], v[188:191], v[162:165], v[22:25]
	v_mfma_f32_16x16x32_bf16 v[18:21], v[196:199], v[162:165], v[18:21]
	v_mfma_f32_16x16x32_bf16 v[6:9], v[188:191], v[170:173], v[6:9]
	v_mfma_f32_16x16x32_bf16 v[2:5], v[196:199], v[170:173], v[2:5]
	v_mfma_f32_16x16x32_bf16 v[54:57], v[192:195], v[150:153], v[54:57]
	v_mfma_f32_16x16x32_bf16 v[50:53], v[224:227], v[150:153], v[50:53]
	v_mfma_f32_16x16x32_bf16 v[38:41], v[192:195], v[158:161], v[38:41]
	v_mfma_f32_16x16x32_bf16 v[34:37], v[224:227], v[158:161], v[34:37]
	v_mfma_f32_16x16x32_bf16 v[22:25], v[192:195], v[166:169], v[22:25]
	v_mfma_f32_16x16x32_bf16 v[18:21], v[224:227], v[166:169], v[18:21]
	v_mfma_f32_16x16x32_bf16 v[6:9], v[192:195], v[174:177], v[6:9]
	v_mfma_f32_16x16x32_bf16 v[2:5], v[224:227], v[174:177], v[2:5]
	s_barrier
	s_add_i32 s30, 0, 0x18000
	v_add_u32_e32 v142, s30, v220
	ds_read_b128 v[130:133], v142
	ds_read_b128 v[134:137], v142 offset:1024
	ds_read_b128 v[138:141], v142 offset:2048
	ds_read_b128 v[142:145], v142 offset:3072
	s_add_u32 s44, s44, s38
	s_addc_u32 s45, s45, 0
	s_mov_b32 m0, s75
	v_lshl_add_u64 v[188:189], s[44:45], 0, v[0:1]
	ds_read_b128 v[146:149], v223 offset:32768
	ds_read_b128 v[150:153], v223 offset:33792
	ds_read_b128 v[154:157], v223 offset:34816
	ds_read_b128 v[158:161], v223 offset:35840
	ds_read_b128 v[162:165], v223 offset:36864
	ds_read_b128 v[166:169], v223 offset:37888
	ds_read_b128 v[170:173], v223 offset:38912
	ds_read_b128 v[174:177], v223 offset:39936
	global_load_lds_dwordx4 v[188:189], off
	v_lshl_add_u64 v[188:189], s[44:45], 0, v[182:183]
	s_mov_b32 m0, s9
	s_nop 0
	global_load_lds_dwordx4 v[188:189], off
	s_waitcnt lgkmcnt(0)
	s_barrier
	v_mfma_f32_16x16x32_bf16 v[126:129], v[130:133], v[146:149], v[126:129]
	v_mfma_f32_16x16x32_bf16 v[122:125], v[138:141], v[146:149], v[122:125]
	v_mfma_f32_16x16x32_bf16 v[110:113], v[130:133], v[154:157], v[110:113]
	v_mfma_f32_16x16x32_bf16 v[106:109], v[138:141], v[154:157], v[106:109]
	v_mfma_f32_16x16x32_bf16 v[94:97], v[130:133], v[162:165], v[94:97]
	v_mfma_f32_16x16x32_bf16 v[90:93], v[138:141], v[162:165], v[90:93]
	v_mfma_f32_16x16x32_bf16 v[78:81], v[130:133], v[170:173], v[78:81]
	v_mfma_f32_16x16x32_bf16 v[74:77], v[138:141], v[170:173], v[74:77]
	v_mfma_f32_16x16x32_bf16 v[126:129], v[134:137], v[150:153], v[126:129]
	v_mfma_f32_16x16x32_bf16 v[122:125], v[142:145], v[150:153], v[122:125]
	v_mfma_f32_16x16x32_bf16 v[110:113], v[134:137], v[158:161], v[110:113]
	v_mfma_f32_16x16x32_bf16 v[106:109], v[142:145], v[158:161], v[106:109]
	v_mfma_f32_16x16x32_bf16 v[94:97], v[134:137], v[166:169], v[94:97]
	v_mfma_f32_16x16x32_bf16 v[90:93], v[142:145], v[166:169], v[90:93]
	v_mfma_f32_16x16x32_bf16 v[78:81], v[134:137], v[174:177], v[78:81]
	v_mfma_f32_16x16x32_bf16 v[74:77], v[142:145], v[174:177], v[74:77]
	s_barrier
	s_add_i32 s44, 0, 0x1c000
	s_add_i32 s30, s30, s68
	v_add_u32_e32 v200, s44, v220
	v_lshl_add_u64 v[228:229], v[228:229], 0, s[76:77]
	s_mov_b32 m0, s30
	ds_read_b128 v[188:191], v200
	ds_read_b128 v[192:195], v200 offset:1024
	ds_read_b128 v[196:199], v200 offset:2048
	ds_read_b128 v[224:227], v200 offset:3072
	global_load_lds_dwordx4 v[228:229], off
	v_lshl_add_u64 v[228:229], v[230:231], 0, s[76:77]
	s_add_i32 m0, s30, 0x2000
	s_nop 0
	global_load_lds_dwordx4 v[228:229], off
	s_waitcnt lgkmcnt(0)
	s_barrier
	v_mfma_f32_16x16x32_bf16 v[118:121], v[188:191], v[146:149], v[118:121]
	v_mfma_f32_16x16x32_bf16 v[114:117], v[196:199], v[146:149], v[114:117]
	v_mfma_f32_16x16x32_bf16 v[102:105], v[188:191], v[154:157], v[102:105]
	v_mfma_f32_16x16x32_bf16 v[98:101], v[196:199], v[154:157], v[98:101]
	v_mfma_f32_16x16x32_bf16 v[86:89], v[188:191], v[162:165], v[86:89]
	v_mfma_f32_16x16x32_bf16 v[82:85], v[196:199], v[162:165], v[82:85]
	v_mfma_f32_16x16x32_bf16 v[70:73], v[188:191], v[170:173], v[70:73]
	v_mfma_f32_16x16x32_bf16 v[66:69], v[196:199], v[170:173], v[66:69]
	v_mfma_f32_16x16x32_bf16 v[118:121], v[192:195], v[150:153], v[118:121]
	v_mfma_f32_16x16x32_bf16 v[114:117], v[224:227], v[150:153], v[114:117]
	v_mfma_f32_16x16x32_bf16 v[102:105], v[192:195], v[158:161], v[102:105]
	v_mfma_f32_16x16x32_bf16 v[98:101], v[224:227], v[158:161], v[98:101]
	v_mfma_f32_16x16x32_bf16 v[86:89], v[192:195], v[166:169], v[86:89]
	v_mfma_f32_16x16x32_bf16 v[82:85], v[224:227], v[166:169], v[82:85]
	v_mfma_f32_16x16x32_bf16 v[70:73], v[192:195], v[174:177], v[70:73]
	v_mfma_f32_16x16x32_bf16 v[66:69], v[224:227], v[174:177], v[66:69]
	s_barrier
	s_mov_b32 m0, s57
	v_lshl_add_u64 v[228:229], v[232:233], 0, s[76:77]
	ds_read_b128 v[146:149], v223 offset:49152
	ds_read_b128 v[150:153], v223 offset:50176
	ds_read_b128 v[154:157], v223 offset:51200
	ds_read_b128 v[158:161], v223 offset:52224
	ds_read_b128 v[162:165], v223 offset:53248
	ds_read_b128 v[166:169], v223 offset:54272
	ds_read_b128 v[170:173], v223 offset:55296
	ds_read_b128 v[174:177], v223 offset:56320
	global_load_lds_dwordx4 v[228:229], off
	v_lshl_add_u64 v[228:229], v[234:235], 0, s[76:77]
	s_mov_b32 m0, s60
	s_nop 0
	global_load_lds_dwordx4 v[228:229], off
	s_waitcnt lgkmcnt(0)
	s_barrier
; #define PG8_STAGE(bufoff, gbase, voff) do { _Pragma("unroll") for (int _i = 0; _i < 2; ++_i) \
;         __builtin_amdgcn_global_load_lds((const unsigned*)((const char*)(gbase) + (voff)[_i]), (LAS unsigned*)(lds + (bufoff) + ldsw + _i * 8192), 16, 0, 0); } while (0)
; #define PG8_MMA(ai, bj, At, Bt) do { __builtin_amdgcn_s_setprio(1); _Pragma("unroll") for (int m = 0; m < 4; ++m) _Pragma("unroll") for (int n = 0; n < 2; ++n) _Pragma("unroll") for (int k = 0; k < 2; ++k) \
;         acc[ai][bj][m][n] = __builtin_amdgcn_mfma_f32_16x16x32_bf16(Bt[n][k], At[m][k], acc[ai][bj][m][n], 0, 0, 0); __builtin_amdgcn_s_setprio(0); } while (0)
; #define PG8_WAIT_V(n) asm volatile("s_waitcnt vmcnt(" #n ")" ::: "memory")
; #define PG8_WAIT_L(n) asm volatile("s_waitcnt lgkmcnt(" #n ")" ::: "memory")
; #define PG8_BAR __builtin_amdgcn_s_barrier()
; #define PG8_SCHED __builtin_amdgcn_sched_barrier(0)
;     __device__ __forceinline__ void scales2(const Unit& u, int wr, int fr, int fq, float& sA, float& sB) const {
;         const int rowA = u.pm * BM + wr * 64 + fq * 16 + fr;
;         const f32x4* pa = (const f32x4*)(ssq_in + (size_t)rowA * 16); const f32x4* pb = (const f32x4*)(ssq_in + (size_t)(rowA + HALF) * 16);
;         const f32x4 a0 = pa[0], a1 = pa[1], a2 = pa[2], a3 = pa[3], b0 = pb[0], b1 = pb[1], b2 = pb[2], b3 = pb[3];
;         const float ta = (((a0[0] + a0[1]) + (a0[2] + a0[3])) + ((a1[0] + a1[1]) + (a1[2] + a1[3]))) + (((a2[0] + a2[1]) + (a2[2] + a2[3])) + ((a3[0] + a3[1]) + (a3[2] + a3[3])));
;         const float tb = (((b0[0] + b0[1]) + (b0[2] + b0[3])) + ((b1[0] + b1[1]) + (b1[2] + b1[3]))) + (((b2[0] + b2[1]) + (b2[2] + b2[3])) + ((b3[0] + b3[1]) + (b3[2] + b3[3])));
;         sA = rsqrtf(ta * (1.0f / 1024.0f) + EPS); sB = rsqrtf(tb * (1.0f / 1024.0f) + EPS);
; template <int MODE, class EpiT, class Sched>
; __device__ __forceinline__ void gemm_phase(LAS unsigned char* lds, const Gemm g, const Sched& S, const EpiT& E) {
;     ...
;             PG8_BAR; PG8_WAIT_L(0); PG8_MMA(1, 0, At, B0); PG8_BAR; PG8_SCHED;
;             PG8_STAGE(PG8_SB(1, 1), b3 + hstep, voffB);
;             PG8_WAIT_V(6); PG8_BAR; PG8_MMA(1, 1, At, B1); PG8_BAR;
	v_mfma_f32_16x16x32_bf16 v[62:65], v[130:133], v[146:149], v[62:65]
	v_mfma_f32_16x16x32_bf16 v[58:61], v[138:141], v[146:149], v[58:61]
	v_mfma_f32_16x16x32_bf16 v[46:49], v[130:133], v[154:157], v[46:49]
	v_mfma_f32_16x16x32_bf16 v[42:45], v[138:141], v[154:157], v[42:45]
	v_mfma_f32_16x16x32_bf16 v[30:33], v[130:133], v[162:165], v[30:33]
	v_mfma_f32_16x16x32_bf16 v[26:29], v[138:141], v[162:165], v[26:29]
	v_mfma_f32_16x16x32_bf16 v[14:17], v[130:133], v[170:173], v[14:17]
	v_mfma_f32_16x16x32_bf16 v[10:13], v[138:141], v[170:173], v[10:13]
	v_mfma_f32_16x16x32_bf16 v[62:65], v[134:137], v[150:153], v[62:65]
	v_mfma_f32_16x16x32_bf16 v[58:61], v[142:145], v[150:153], v[58:61]
	v_mfma_f32_16x16x32_bf16 v[46:49], v[134:137], v[158:161], v[46:49]
	v_mfma_f32_16x16x32_bf16 v[42:45], v[142:145], v[158:161], v[42:45]
	v_mfma_f32_16x16x32_bf16 v[30:33], v[134:137], v[166:169], v[30:33]
	v_mfma_f32_16x16x32_bf16 v[26:29], v[142:145], v[166:169], v[26:29]
	v_mfma_f32_16x16x32_bf16 v[14:17], v[134:137], v[174:177], v[14:17]
	v_mfma_f32_16x16x32_bf16 v[10:13], v[142:145], v[174:177], v[10:13]
	s_barrier
	s_add_i32 s30, s44, s68
	v_lshl_add_u64 v[130:131], v[236:237], 0, s[76:77]
	s_mov_b32 m0, s30
	s_nop 0
	global_load_lds_dwordx4 v[130:131], off
	v_lshl_add_u64 v[130:131], v[238:239], 0, s[76:77]
	s_add_i32 m0, s30, 0x2000
	s_nop 0
	global_load_lds_dwordx4 v[130:131], off
	s_waitcnt vmcnt(6)
	s_barrier
	v_mfma_f32_16x16x32_bf16 v[54:57], v[188:191], v[146:149], v[54:57]
	v_mfma_f32_16x16x32_bf16 v[50:53], v[196:199], v[146:149], v[50:53]
	v_mfma_f32_16x16x32_bf16 v[38:41], v[188:191], v[154:157], v[38:41]
	v_mfma_f32_16x16x32_bf16 v[34:37], v[196:199], v[154:157], v[34:37]
	v_mfma_f32_16x16x32_bf16 v[22:25], v[188:191], v[162:165], v[22:25]
	v_mfma_f32_16x16x32_bf16 v[18:21], v[196:199], v[162:165], v[18:21]
	v_mfma_f32_16x16x32_bf16 v[6:9], v[188:191], v[170:173], v[6:9]
	v_mfma_f32_16x16x32_bf16 v[2:5], v[196:199], v[170:173], v[2:5]
	v_mfma_f32_16x16x32_bf16 v[54:57], v[192:195], v[150:153], v[54:57]
	v_mfma_f32_16x16x32_bf16 v[50:53], v[224:227], v[150:153], v[50:53]
	v_mfma_f32_16x16x32_bf16 v[38:41], v[192:195], v[158:161], v[38:41]
	v_mfma_f32_16x16x32_bf16 v[34:37], v[224:227], v[158:161], v[34:37]
	v_mfma_f32_16x16x32_bf16 v[22:25], v[192:195], v[166:169], v[22:25]
	v_mfma_f32_16x16x32_bf16 v[18:21], v[224:227], v[166:169], v[18:21]
	v_mfma_f32_16x16x32_bf16 v[6:9], v[192:195], v[174:177], v[6:9]
	v_mfma_f32_16x16x32_bf16 v[2:5], v[224:227], v[174:177], v[2:5]
	s_barrier
	s_add_u32 s4, s4, 0x100
	s_addc_u32 s5, s5, 0
	s_add_u32 s23, s23, 0x100
	s_addc_u32 s24, s24, 0
	s_cmp_ge_u32 s89, s21
	s_mov_b32 s30, s89
	s_cbranch_scc0 .LBB0_159
	s_lshl_b32 s4, s22, 8
	s_add_i32 s4, s4, s56
	v_or_b32_e32 v130, s4, v222
	v_ashrrev_i32_e32 v131, 31, v130
	v_lshlrev_b64 v[130:131], 6, v[130:131]
	v_lshl_add_u64 v[146:147], s[66:67], 0, v[130:131]
	global_load_dwordx4 v[130:133], v[146:147], off offset:16
	global_load_dwordx4 v[134:137], v[146:147], off offset:48
	global_load_dwordx4 v[138:141], v[146:147], off
	global_load_dwordx4 v[142:145], v[146:147], off offset:32
	v_or_b32_e32 v192, s4, v181
	s_mov_b64 s[4:5], 0x2000
	v_lshl_add_u64 v[158:159], v[146:147], 0, s[4:5]
	v_add_co_u32_e32 v146, vcc, 0x2000, v146
	s_mov_b32 s4, 0x3a800000
	s_nop 0
	v_addc_co_u32_e32 v147, vcc, 0, v147, vcc
	global_load_dwordx4 v[146:149], v[146:147], off
	s_nop 0
	global_load_dwordx4 v[150:153], v[158:159], off offset:16
	global_load_dwordx4 v[154:157], v[158:159], off offset:48
	s_nop 0
	global_load_dwordx4 v[158:161], v[158:159], off offset:32
	v_lshl_or_b32 v188, s2, 8, v221
	v_ashrrev_i32_e32 v193, 31, v192
	v_ashrrev_i32_e32 v189, 31, v188
	v_or_b32_e32 v194, 16, v192
	v_ashrrev_i32_e32 v195, 31, v194
	s_waitcnt vmcnt(0)
	v_mov_b32_e32 v162, v138
	v_mov_b32_e32 v163, v142
	v_mov_b32_e32 v142, v139
	v_pk_add_f32 v[138:139], v[162:163], v[142:143]
	v_mov_b32_e32 v142, v140
	v_mov_b32_e32 v143, v144
	v_mov_b32_e32 v144, v141
	v_pk_add_f32 v[140:141], v[142:143], v[144:145]
	s_nop 0
	v_pk_add_f32 v[138:139], v[138:139], v[140:141]
	v_mov_b32_e32 v140, v130
	v_mov_b32_e32 v141, v134
	v_mov_b32_e32 v134, v131
	v_pk_add_f32 v[130:131], v[140:141], v[134:135]
	v_mov_b32_e32 v134, v132
	v_mov_b32_e32 v135, v136
	v_mov_b32_e32 v136, v133
	v_pk_add_f32 v[132:133], v[134:135], v[136:137]
	v_mov_b32_e32 v134, v148
	v_pk_add_f32 v[130:131], v[130:131], v[132:133]
	v_mov_b32_e32 v132, v146
	v_mov_b32_e32 v133, v158
	v_mov_b32_e32 v158, v147
	v_mov_b32_e32 v135, v160
	v_mov_b32_e32 v160, v149
	v_pk_add_f32 v[132:133], v[132:133], v[158:159]
	v_pk_add_f32 v[134:135], v[134:135], v[160:161]
	v_mov_b32_e32 v136, v152
	v_pk_add_f32 v[132:133], v[132:133], v[134:135]
	v_mov_b32_e32 v134, v150
	v_mov_b32_e32 v135, v154
	v_mov_b32_e32 v154, v151
	v_mov_b32_e32 v137, v156
	v_mov_b32_e32 v156, v153
	v_pk_add_f32 v[134:135], v[134:135], v[154:155]
	v_pk_add_f32 v[136:137], v[136:137], v[156:157]
	v_pk_add_f32 v[130:131], v[138:139], v[130:131]
	v_pk_add_f32 v[134:135], v[134:135], v[136:137]
	s_nop 0
	v_pk_add_f32 v[132:133], v[132:133], v[134:135]
	v_mov_b32_e32 v135, v130
	v_mov_b32_e32 v134, v132
	v_mov_b32_e32 v130, v133
	v_pk_add_f32 v[130:131], v[134:135], v[130:131]
	s_nop 0
	v_pk_fma_f32 v[190:191], v[130:131], s[4:5], v[178:179] op_sel_hi:[1,0,0]
	s_mov_b32 s4, 0x800000
	v_mul_f32_e32 v130, 0x4b800000, v191
	v_cmp_gt_f32_e64 s[44:45], s4, v191
	v_cmp_gt_f32_e32 vcc, s4, v190
	s_nop 0
	v_cndmask_b32_e64 v130, v191, v130, s[44:45]
	v_rsq_f32_e32 v130, v130
	s_nop 0
	v_mul_f32_e32 v131, 0x45800000, v130
	v_cndmask_b32_e64 v226, v130, v131, s[44:45]
	v_lshlrev_b64 v[130:131], 10, v[192:193]
	v_lshl_add_u64 v[130:131], v[130:131], 0, v[188:189]
	v_lshlrev_b64 v[198:199], 1, v[130:131]
	v_lshl_add_u64 v[130:131], s[34:35], 0, v[198:199]
	v_lshl_add_u64 v[132:133], s[92:93], 0, v[198:199]
	global_load_dwordx4 v[170:173], v[130:131], off
	global_load_dwordx4 v[174:177], v[132:133], off
	v_lshl_add_u64 v[134:135], s[6:7], 0, v[198:199]
	global_load_dwordx4 v[166:169], v[134:135], off
	global_load_dwordx4 v[158:161], v[130:131], off offset:256
	global_load_dwordx4 v[162:165], v[132:133], off offset:256
	global_load_dwordx4 v[146:149], v[134:135], off offset:256
	v_and_b32_e32 v130, 64, v205
	v_or_b32_e32 v200, v130, v181
	v_lshlrev_b32_e32 v225, 2, v200
	ds_bpermute_b32 v200, v225, v226
	v_xor_b32_e32 v131, 16, v205
	v_add_u32_e32 v130, 64, v130
	v_cmp_lt_i32_e64 s[44:45], v131, v130
	s_waitcnt lgkmcnt(0)
; __device__ __forceinline__ float bf_lo(unsigned w) { return __uint_as_float(w << 16); }
; __device__ __forceinline__ float bf_hi(unsigned w) { return __uint_as_float(w & 0xffff0000u); }
;     template <int mode> __device__ __forceinline__ void run(const f32x4 (&acc)[2][2][4][2], const Unit& u, int wr, int wc, int fr, int fq, const LAS float* sc) const {
;     ...
;                 float s = 1.f;
;                 if (mode == 4) s = __shfl(ai ? sB : sA, m * 16 + fr);
;                 float ss = 0.f;
; #pragma unroll
;                 for (int bj = 0; bj < 2; ++bj) {
;                     u32x4 wh, wl;
; #pragma unroll
;                     for (int n = 0; n < 2; ++n) {
;                         const int q = 2 * bj + n;
;                         const unsigned h0 = n ? xh[cb][bj].z : xh[cb][bj].x, h1 = n ? xh[cb][bj].w : xh[cb][bj].y, l0 = n ? xl[cb][bj].z : xl[cb][bj].x, l1 = n ? xl[cb][bj].w : xl[cb][bj].y;
;                         f32x4 xo;
;                         if (mode == 5) xo = xi[cb][q];
;                         else { xo[0] = bf_lo(h0) + bf_lo(l0); xo[1] = bf_hi(h0) + bf_hi(l0); xo[2] = bf_lo(h1) + bf_lo(l1); xo[3] = bf_hi(h1) + bf_hi(l1); }
;                         f32x4 v;
;                         if (mode != 4) v = xo + acc[ai][bj][m][n] * alpha + bvv[q];
;                         else {
;                             const f32x4 a = acc[ai][bj][m][n] * s;
;                             const unsigned p0 = n ? pq[cb][bj].z : pq[cb][bj].x, p1 = n ? pq[cb][bj].w : pq[cb][bj].y;
;                             v[0] = xo[0] + sigmoidf_(a[0]) * bf_lo(p0); v[1] = xo[1] + sigmoidf_(a[1]) * bf_hi(p0);
;                             v[2] = xo[2] + sigmoidf_(a[2]) * bf_lo(p1); v[3] = xo[3] + sigmoidf_(a[3]) * bf_hi(p1);
;                         }
;                         const unsigned w0 = pk2(v[0], v[1]), w1 = pk2(v[2], v[3]);
;                         const unsigned m0 = pk2(v[0] - bf_lo(w0), v[1] - bf_hi(w0)), m1 = pk2(v[2] - bf_lo(w1), v[3] - bf_hi(w1));
;                         if (n == 0) { wh.x = w0; wh.y = w1; wl.x = m0; wl.y = m1; } else { wh.z = w0; wh.w = w1; wl.z = m0; wl.w = m1; }
;                         ss += (v[0] * v[0] + v[1] * v[1]) + (v[2] * v[2] + v[3] * v[3]);
;                     }
;                     *(u32x4*)(xb + off + bj * HALF) = wh;
;                     *(u32x4*)(lout + off + bj * HALF) = wl;
	v_pk_mul_f32 v[126:127], v[126:127], v[200:201] op_sel_hi:[1,0]
	v_cndmask_b32_e64 v131, v205, v131, s[44:45]
	v_lshlrev_b32_e32 v191, 2, v131
	v_xor_b32_e32 v131, 32, v205
	v_mul_f32_e32 v126, 0xbfb8aa3b, v126
	v_cmp_lt_i32_e64 s[44:45], v131, v130
	v_exp_f32_e32 v126, v126
	v_pk_mul_f32 v[128:129], v[128:129], v[200:201] op_sel_hi:[1,0]
	v_cndmask_b32_e64 v130, v205, v131, s[44:45]
	v_lshlrev_b32_e32 v224, 2, v130
	v_lshlrev_b64 v[130:131], 10, v[194:195]
	v_lshl_add_u64 v[130:131], v[130:131], 0, v[188:189]
	v_lshlrev_b64 v[196:197], 1, v[130:131]
	v_add_f32_e32 v126, 1.0, v126
	v_lshl_add_u64 v[130:131], s[34:35], 0, v[196:197]
	v_lshl_add_u64 v[132:133], s[92:93], 0, v[196:197]
	v_lshl_add_u64 v[228:229], s[6:7], 0, v[196:197]
	v_rcp_f32_e32 v126, v126
	global_load_dwordx4 v[150:153], v[130:131], off
	global_load_dwordx4 v[154:157], v[132:133], off
	global_load_dwordx4 v[142:145], v[228:229], off
	global_load_dwordx4 v[134:137], v[130:131], off offset:256
	global_load_dwordx4 v[138:141], v[132:133], off offset:256
	s_nop 0
	global_load_dwordx4 v[130:133], v[228:229], off offset:256
	v_pk_mul_f32 v[122:123], v[122:123], v[200:201] op_sel_hi:[1,0]
	v_pk_mul_f32 v[124:125], v[124:125], v[200:201] op_sel_hi:[1,0]
	v_mul_f32_e32 v122, 0xbfb8aa3b, v122
	v_exp_f32_e32 v122, v122
	v_pk_mul_f32 v[118:119], v[118:119], v[200:201] op_sel_hi:[1,0]
	v_pk_mul_f32 v[120:121], v[120:121], v[200:201] op_sel_hi:[1,0]
	v_mul_f32_e32 v118, 0xbfb8aa3b, v118
	v_add_f32_e32 v122, 1.0, v122
	v_rcp_f32_e32 v122, v122
	v_exp_f32_e32 v118, v118
	v_pk_mul_f32 v[114:115], v[114:115], v[200:201] op_sel_hi:[1,0]
	v_pk_mul_f32 v[116:117], v[116:117], v[200:201] op_sel_hi:[1,0]
	v_mul_f32_e32 v114, 0xbfb8aa3b, v114
	v_add_f32_e32 v118, 1.0, v118
	v_rcp_f32_e32 v118, v118
	v_exp_f32_e32 v114, v114
	s_lshl_b32 s44, s2, 2
	s_ashr_i32 s45, s44, 31
	v_add_f32_e32 v114, 1.0, v114
	v_rcp_f32_e32 v114, v114
	s_waitcnt vmcnt(11)
	v_lshlrev_b32_e32 v227, 16, v170
	s_waitcnt vmcnt(10)
	v_lshlrev_b32_e32 v228, 16, v174
	v_and_b32_e32 v174, 0xffff0000, v174
	v_and_b32_e32 v170, 0xffff0000, v170
	v_add_f32_e32 v227, v228, v227
	v_add_f32_e32 v170, v174, v170
	v_lshlrev_b32_e32 v174, 16, v171
	v_lshlrev_b32_e32 v228, 16, v175
	v_and_b32_e32 v175, 0xffff0000, v175
	v_and_b32_e32 v171, 0xffff0000, v171
	v_add_f32_e32 v171, v175, v171
	s_waitcnt vmcnt(9)
	v_lshlrev_b32_e32 v175, 16, v166
	v_fmac_f32_e32 v227, v126, v175
	v_mul_f32_e32 v126, 0xbfb8aa3b, v127
	v_exp_f32_e32 v126, v126
	v_and_b32_e32 v127, 0xffff0000, v166
	v_add_f32_e32 v174, v228, v174
	v_add_f32_e32 v126, 1.0, v126
	v_rcp_f32_e32 v126, v126
	s_nop 0
	v_fmac_f32_e32 v170, v126, v127
	v_mul_f32_e32 v126, 0xbfb8aa3b, v128
	v_exp_f32_e32 v126, v126
	v_lshlrev_b32_e32 v127, 16, v167
	v_add_f32_e32 v126, 1.0, v126
	v_rcp_f32_e32 v126, v126
	s_nop 0
	v_fmac_f32_e32 v174, v126, v127
	v_mul_f32_e32 v126, 0xbfb8aa3b, v129
	v_exp_f32_e32 v126, v126
	v_and_b32_e32 v127, 0xffff0000, v167
	v_add_f32_e32 v126, 1.0, v126
	v_rcp_f32_e32 v126, v126
	s_nop 0
	v_fmac_f32_e32 v171, v126, v127
	v_cvt_pk_bf16_f32 v126, v227, v170
	v_cvt_pk_bf16_f32 v127, v174, v171
	s_nop 0
	v_lshlrev_b32_e32 v128, 16, v126
	v_and_b32_e32 v129, 0xffff0000, v126
	v_sub_f32_e32 v128, v227, v128
	v_sub_f32_e32 v129, v170, v129
	v_cvt_pk_bf16_f32 v166, v128, v129
	v_lshlrev_b32_e32 v128, 16, v127
	v_and_b32_e32 v129, 0xffff0000, v127
	v_sub_f32_e32 v128, v174, v128
	v_sub_f32_e32 v129, v171, v129
	v_cvt_pk_bf16_f32 v167, v128, v129
	v_mul_f32_e32 v128, v170, v170
	v_mul_f32_e32 v129, v171, v171
	v_fmac_f32_e32 v128, v227, v227
	v_fmac_f32_e32 v129, v174, v174
	v_add_f32_e32 v170, v128, v129
	v_lshlrev_b32_e32 v128, 16, v172
	v_lshlrev_b32_e32 v129, 16, v176
	v_add_f32_e32 v171, v129, v128
	v_and_b32_e32 v128, 0xffff0000, v176
	v_and_b32_e32 v129, 0xffff0000, v172
	v_add_f32_e32 v172, v128, v129
	v_lshlrev_b32_e32 v128, 16, v173
	v_lshlrev_b32_e32 v129, 16, v177
	v_add_f32_e32 v174, v129, v128
	v_and_b32_e32 v128, 0xffff0000, v177
	v_and_b32_e32 v129, 0xffff0000, v173
	v_add_f32_e32 v173, v128, v129
	v_lshlrev_b32_e32 v128, 16, v168
	v_fmac_f32_e32 v171, v122, v128
	v_mul_f32_e32 v122, 0xbfb8aa3b, v123
	v_exp_f32_e32 v122, v122
	v_and_b32_e32 v123, 0xffff0000, v168
	v_add_f32_e32 v122, 1.0, v122
	v_rcp_f32_e32 v122, v122
	s_nop 0
	v_fmac_f32_e32 v172, v122, v123
	v_mul_f32_e32 v122, 0xbfb8aa3b, v124
	v_exp_f32_e32 v122, v122
	v_lshlrev_b32_e32 v123, 16, v169
	v_cvt_pk_bf16_f32 v128, v171, v172
	v_add_f32_e32 v122, 1.0, v122
	v_rcp_f32_e32 v122, v122
	s_nop 0
	v_fmac_f32_e32 v174, v122, v123
	v_mul_f32_e32 v122, 0xbfb8aa3b, v125
	v_exp_f32_e32 v122, v122
	v_and_b32_e32 v123, 0xffff0000, v169
	v_lshl_add_u64 v[124:125], s[28:29], 0, v[198:199]
	v_add_f32_e32 v122, 1.0, v122
	v_rcp_f32_e32 v122, v122
	s_nop 0
	v_fmac_f32_e32 v173, v122, v123
	v_lshlrev_b32_e32 v122, 16, v128
	v_and_b32_e32 v123, 0xffff0000, v128
	v_sub_f32_e32 v122, v171, v122
	v_sub_f32_e32 v123, v172, v123
	v_cvt_pk_bf16_f32 v129, v174, v173
	v_cvt_pk_bf16_f32 v168, v122, v123
	s_nop 0
	v_lshlrev_b32_e32 v122, 16, v129
	v_and_b32_e32 v123, 0xffff0000, v129
	v_sub_f32_e32 v122, v174, v122
	v_sub_f32_e32 v123, v173, v123
	v_cvt_pk_bf16_f32 v169, v122, v123
	v_mul_f32_e32 v122, v172, v172
	v_mul_f32_e32 v123, v173, v173
	v_fmac_f32_e32 v122, v171, v171
	v_fmac_f32_e32 v123, v174, v174
	v_add_f32_e32 v122, v122, v123
	v_add_f32_e32 v170, v170, v122
	v_lshl_add_u64 v[122:123], s[10:11], 0, v[198:199]
	global_store_dwordx4 v[122:123], v[126:129], off
	global_store_dwordx4 v[124:125], v[166:169], off
	s_waitcnt vmcnt(10)
; __device__ __forceinline__ float bf_lo(unsigned w) { return __uint_as_float(w << 16); }
; __device__ __forceinline__ float bf_hi(unsigned w) { return __uint_as_float(w & 0xffff0000u); }
;     template <int mode> __device__ __forceinline__ void run(const f32x4 (&acc)[2][2][4][2], const Unit& u, int wr, int wc, int fr, int fq, const LAS float* sc) const {
;     ...
;                 for (int bj = 0; bj < 2; ++bj) {
;                     u32x4 wh, wl;
; #pragma unroll
;                     for (int n = 0; n < 2; ++n) {
;                         const int q = 2 * bj + n;
;                         const unsigned h0 = n ? xh[cb][bj].z : xh[cb][bj].x, h1 = n ? xh[cb][bj].w : xh[cb][bj].y, l0 = n ? xl[cb][bj].z : xl[cb][bj].x, l1 = n ? xl[cb][bj].w : xl[cb][bj].y;
;                         f32x4 xo;
;                         if (mode == 5) xo = xi[cb][q];
;                         else { xo[0] = bf_lo(h0) + bf_lo(l0); xo[1] = bf_hi(h0) + bf_hi(l0); xo[2] = bf_lo(h1) + bf_lo(l1); xo[3] = bf_hi(h1) + bf_hi(l1); }
;                         f32x4 v;
;                         if (mode != 4) v = xo + acc[ai][bj][m][n] * alpha + bvv[q];
;                         else {
;                             const f32x4 a = acc[ai][bj][m][n] * s;
;                             const unsigned p0 = n ? pq[cb][bj].z : pq[cb][bj].x, p1 = n ? pq[cb][bj].w : pq[cb][bj].y;
;                             v[0] = xo[0] + sigmoidf_(a[0]) * bf_lo(p0); v[1] = xo[1] + sigmoidf_(a[1]) * bf_hi(p0);
;                             v[2] = xo[2] + sigmoidf_(a[2]) * bf_lo(p1); v[3] = xo[3] + sigmoidf_(a[3]) * bf_hi(p1);
;                         }
;                         const unsigned w0 = pk2(v[0], v[1]), w1 = pk2(v[2], v[3]);
;                         const unsigned m0 = pk2(v[0] - bf_lo(w0), v[1] - bf_hi(w0)), m1 = pk2(v[2] - bf_lo(w1), v[3] - bf_hi(w1));
;                         if (n == 0) { wh.x = w0; wh.y = w1; wl.x = m0; wl.y = m1; } else { wh.z = w0; wh.w = w1; wl.z = m0; wl.w = m1; }
;                         ss += (v[0] * v[0] + v[1] * v[1]) + (v[2] * v[2] + v[3] * v[3]);
;                     }
;                     *(u32x4*)(xb + off + bj * HALF) = wh;
;                     *(u32x4*)(lout + off + bj * HALF) = wl;
;                 }
;                 ss += __shfl_xor(ss, 16); ss += __shfl_xor(ss, 32);
;                 if (fq == 0) ssq_out[(size_t)row * 16 + u.pn * 4 + wc] = ss;
	v_lshlrev_b32_e32 v126, 16, v158
	s_waitcnt vmcnt(9)
	v_lshlrev_b32_e32 v127, 16, v162
	v_add_f32_e32 v128, v127, v126
	v_and_b32_e32 v126, 0xffff0000, v162
	v_and_b32_e32 v127, 0xffff0000, v158
	v_add_f32_e32 v129, v126, v127
	v_lshlrev_b32_e32 v126, 16, v159
	v_lshlrev_b32_e32 v127, 16, v163
	v_add_f32_e32 v158, v127, v126
	v_and_b32_e32 v126, 0xffff0000, v163
	v_and_b32_e32 v127, 0xffff0000, v159
	v_add_f32_e32 v159, v126, v127
	s_waitcnt vmcnt(8)
	v_lshlrev_b32_e32 v126, 16, v146
	v_fmac_f32_e32 v128, v118, v126
	v_mul_f32_e32 v118, 0xbfb8aa3b, v119
	v_exp_f32_e32 v118, v118
	v_and_b32_e32 v119, 0xffff0000, v146
	v_add_f32_e32 v118, 1.0, v118
	v_rcp_f32_e32 v118, v118
	s_nop 0
	v_fmac_f32_e32 v129, v118, v119
	v_mul_f32_e32 v118, 0xbfb8aa3b, v120
	v_exp_f32_e32 v118, v118
	v_lshlrev_b32_e32 v119, 16, v147
	v_add_f32_e32 v118, 1.0, v118
	v_rcp_f32_e32 v118, v118
	s_nop 0
	v_fmac_f32_e32 v158, v118, v119
	v_mul_f32_e32 v118, 0xbfb8aa3b, v121
	v_exp_f32_e32 v118, v118
	v_and_b32_e32 v119, 0xffff0000, v147
	v_add_f32_e32 v118, 1.0, v118
	v_rcp_f32_e32 v118, v118
	s_nop 0
	v_fmac_f32_e32 v159, v118, v119
	v_cvt_pk_bf16_f32 v118, v128, v129
	v_cvt_pk_bf16_f32 v119, v158, v159
	s_nop 0
	v_lshlrev_b32_e32 v120, 16, v118
	v_and_b32_e32 v121, 0xffff0000, v118
	v_sub_f32_e32 v120, v128, v120
	v_sub_f32_e32 v121, v129, v121
	v_cvt_pk_bf16_f32 v126, v120, v121
	v_lshlrev_b32_e32 v120, 16, v119
	v_and_b32_e32 v121, 0xffff0000, v119
	v_sub_f32_e32 v120, v158, v120
	v_sub_f32_e32 v121, v159, v121
	v_cvt_pk_bf16_f32 v127, v120, v121
	v_mul_f32_e32 v120, v129, v129
	v_mul_f32_e32 v121, v159, v159
	v_fmac_f32_e32 v120, v128, v128
	v_fmac_f32_e32 v121, v158, v158
	v_add_f32_e32 v120, v120, v121
	v_add_f32_e32 v146, v120, v170
	v_lshlrev_b32_e32 v120, 16, v160
	v_lshlrev_b32_e32 v121, 16, v164
	v_add_f32_e32 v147, v121, v120
	v_and_b32_e32 v120, 0xffff0000, v164
	v_and_b32_e32 v121, 0xffff0000, v160
	v_add_f32_e32 v158, v120, v121
	v_lshlrev_b32_e32 v120, 16, v161
	v_lshlrev_b32_e32 v121, 16, v165
	v_add_f32_e32 v159, v121, v120
	v_and_b32_e32 v120, 0xffff0000, v165
	v_and_b32_e32 v121, 0xffff0000, v161
	v_add_f32_e32 v160, v120, v121
	v_lshlrev_b32_e32 v120, 16, v148
	v_fmac_f32_e32 v147, v114, v120
	v_mul_f32_e32 v114, 0xbfb8aa3b, v115
	v_exp_f32_e32 v114, v114
	v_and_b32_e32 v115, 0xffff0000, v148
	v_add_f32_e32 v114, 1.0, v114
	v_rcp_f32_e32 v114, v114
	s_nop 0
	v_fmac_f32_e32 v158, v114, v115
	v_mul_f32_e32 v114, 0xbfb8aa3b, v116
	v_exp_f32_e32 v114, v114
	v_lshlrev_b32_e32 v115, 16, v149
	v_cvt_pk_bf16_f32 v120, v147, v158
	v_add_f32_e32 v114, 1.0, v114
	v_rcp_f32_e32 v114, v114
	s_nop 0
	v_fmac_f32_e32 v159, v114, v115
	v_mul_f32_e32 v114, 0xbfb8aa3b, v117
	v_exp_f32_e32 v114, v114
	v_and_b32_e32 v115, 0xffff0000, v149
	v_add_f32_e32 v114, 1.0, v114
	v_rcp_f32_e32 v114, v114
	s_nop 0
	v_fmac_f32_e32 v160, v114, v115
	v_lshlrev_b32_e32 v114, 16, v120
	v_and_b32_e32 v115, 0xffff0000, v120
	v_sub_f32_e32 v114, v147, v114
	v_sub_f32_e32 v115, v158, v115
	v_cvt_pk_bf16_f32 v121, v159, v160
	v_cvt_pk_bf16_f32 v128, v114, v115
	s_nop 0
	v_lshlrev_b32_e32 v114, 16, v121
	v_and_b32_e32 v115, 0xffff0000, v121
	v_sub_f32_e32 v114, v159, v114
	v_sub_f32_e32 v115, v160, v115
	v_cvt_pk_bf16_f32 v129, v114, v115
	v_mul_f32_e32 v114, v158, v158
	v_mul_f32_e32 v115, v160, v160
	v_fmac_f32_e32 v114, v147, v147
	v_fmac_f32_e32 v115, v159, v159
	v_add_f32_e32 v114, v114, v115
	v_add_f32_e32 v114, v114, v146
	ds_bpermute_b32 v115, v191, v114
	global_store_dwordx4 v[122:123], v[118:121], off offset:256
	global_store_dwordx4 v[124:125], v[126:129], off offset:256
	s_waitcnt lgkmcnt(0)
	v_add_f32_e32 v114, v114, v115
	ds_bpermute_b32 v115, v224, v114
	s_and_saveexec_b64 s[4:5], s[40:41]
	s_cbranch_execz .LBB0_162
	v_lshlrev_b64 v[116:117], 6, v[192:193]
	v_lshl_add_u64 v[116:117], s[62:63], 0, v[116:117]
	v_lshl_add_u64 v[116:117], s[44:45], 2, v[116:117]
	s_lshl_b32 s24, s20, 2
	v_lshl_add_u64 v[116:117], v[116:117], 0, s[24:25]
	s_waitcnt lgkmcnt(0)
	v_add_f32_e32 v114, v114, v115
	global_store_dword v[116:117], v114, off

; #define PG8_STAGE(bufoff, gbase, voff) do { _Pragma("unroll") for (int _i = 0; _i < 2; ++_i) \
;         __builtin_amdgcn_global_load_lds((const unsigned*)((const char*)(gbase) + (voff)[_i]), (LAS unsigned*)(lds + (bufoff) + ldsw + _i * 8192), 16, 0, 0); } while (0)
; #define PG8_LDA(dst, b, h) do { _Pragma("unroll") for (int m = 0; m < 4; ++m) _Pragma("unroll") for (int k = 0; k < 2; ++k) dst[m][k] = *(const LAS bf16x8*)(lds + PG8_SA(b, h) + aoff + m * 2048 + k * 1024); } while (0)
; #define PG8_LDB(dst, b, h) do { _Pragma("unroll") for (int n = 0; n < 2; ++n) _Pragma("unroll") for (int k = 0; k < 2; ++k) dst[n][k] = *(const LAS bf16x8*)(lds + PG8_SB(b, h) + boff + n * 2048 + k * 1024); } while (0)
; #define PG8_MMA(ai, bj, At, Bt) do { __builtin_amdgcn_s_setprio(1); _Pragma("unroll") for (int m = 0; m < 4; ++m) _Pragma("unroll") for (int n = 0; n < 2; ++n) _Pragma("unroll") for (int k = 0; k < 2; ++k) \
;         acc[ai][bj][m][n] = __builtin_amdgcn_mfma_f32_16x16x32_bf16(Bt[n][k], At[m][k], acc[ai][bj][m][n], 0, 0, 0); __builtin_amdgcn_s_setprio(0); } while (0)
; #define PG8_WAIT_L(n) asm volatile("s_waitcnt lgkmcnt(" #n ")" ::: "memory")
; template <int MODE, class EpiT, class Sched>
; __device__ __forceinline__ void gemm_phase(LAS unsigned char* lds, const Gemm g, const Sched& S, const EpiT& E) {
;     ...
;         const bool has_next = S.next(ui + 1, nxt);
;         const char* nA = has_next ? (const char*)g.A + (size_t)nxt.pm * tstep : cA; const char* nB = has_next ? (const char*)g.Bt + (size_t)nxt.pn * tstep : cB;
;         for (int t = 0; t < nt; t += 2) {
;             const bool last = (t == nt - 2);
;             const char* a1 = cA + (size_t)(t + 1) * kstep;
;             const char* a2 = last ? nA : cA + (size_t)(t + 2) * kstep; const char* b2 = last ? nB : cB + (size_t)(t + 2) * kstep;
;             const char* a3 = a2 + kstep; const char* b3 = b2 + kstep;
;             PG8_LDB(B0, 0, 0); PG8_SCHED; PG8_LDA(At, 0, 0); PG8_STAGE(PG8_SA(1, 1), a1 + hstep, voffA);
;             PG8_WAIT_L(8); PG8_BAR; PG8_WAIT_L(0); PG8_MMA(0, 0, At, B0); PG8_BAR; PG8_SCHED;
;             PG8_LDB(B1, 0, 1); PG8_STAGE(PG8_SB(0, 0), b2, voffB);
;             PG8_BAR; PG8_WAIT_L(0); PG8_MMA(0, 1, At, B1); PG8_BAR;
;             PG8_LDA(At, 0, 1); PG8_STAGE(PG8_SA(0, 0), a2, voffA);
;             PG8_BAR; PG8_WAIT_L(0); PG8_MMA(1, 0, At, B0); PG8_BAR; PG8_SCHED;
.LBB0_195:
	s_add_i32 vcc_lo, s44, 2
	s_add_u32 s52, s4, 0x80
	s_addc_u32 s45, s5, 0
	s_add_i32 s58, 0, 0x10000
	v_add_u32_e32 v74, s58, v194
	ds_read_b128 v[58:61], v74
	ds_read_b128 v[62:65], v74 offset:1024
	ds_read_b128 v[70:73], v74 offset:2048
	ds_read_b128 v[74:77], v74 offset:3072
	s_cmp_eq_u32 s75, s44
	s_cselect_b32 s44, s68, s52
	s_cselect_b32 s45, s69, s45
	s_cselect_b32 s53, s47, s90
	s_cselect_b32 s52, s46, s89
	v_lshl_add_u64 v[188:189], s[4:5], 0, v[176:177]
	s_add_i32 m0, s21, 0xc000
	ds_read_b128 v[138:141], v196
	ds_read_b128 v[142:145], v196 offset:1024
	ds_read_b128 v[146:149], v196 offset:2048
	ds_read_b128 v[150:153], v196 offset:3072
	ds_read_b128 v[162:165], v196 offset:4096
	ds_read_b128 v[166:169], v196 offset:5120
	ds_read_b128 v[170:173], v196 offset:6144
	ds_read_b128 v[184:187], v196 offset:7168
	global_load_lds_dwordx4 v[188:189], off
	v_lshl_add_u64 v[188:189], s[4:5], 0, v[182:183]
	s_add_i32 m0, s21, 0xe000
	s_nop 0
	global_load_lds_dwordx4 v[188:189], off
	s_waitcnt lgkmcnt(0)
	s_barrier
	v_mfma_f32_16x16x32_bf16 v[158:161], v[58:61], v[138:141], v[158:161]
	v_mfma_f32_16x16x32_bf16 v[154:157], v[70:73], v[138:141], v[154:157]
	v_mfma_f32_16x16x32_bf16 v[126:129], v[58:61], v[146:149], v[126:129]
	v_mfma_f32_16x16x32_bf16 v[122:125], v[70:73], v[146:149], v[122:125]
	v_mfma_f32_16x16x32_bf16 v[110:113], v[58:61], v[162:165], v[110:113]
	v_mfma_f32_16x16x32_bf16 v[106:109], v[70:73], v[162:165], v[106:109]
	v_mfma_f32_16x16x32_bf16 v[94:97], v[58:61], v[170:173], v[94:97]
	v_mfma_f32_16x16x32_bf16 v[90:93], v[70:73], v[170:173], v[90:93]
	v_mfma_f32_16x16x32_bf16 v[158:161], v[62:65], v[142:145], v[158:161]
	v_mfma_f32_16x16x32_bf16 v[154:157], v[74:77], v[142:145], v[154:157]
	v_mfma_f32_16x16x32_bf16 v[126:129], v[62:65], v[150:153], v[126:129]
	v_mfma_f32_16x16x32_bf16 v[122:125], v[74:77], v[150:153], v[122:125]
	v_mfma_f32_16x16x32_bf16 v[110:113], v[62:65], v[166:169], v[110:113]
	v_mfma_f32_16x16x32_bf16 v[106:109], v[74:77], v[166:169], v[106:109]
	v_mfma_f32_16x16x32_bf16 v[94:97], v[62:65], v[184:187], v[94:97]
	v_mfma_f32_16x16x32_bf16 v[90:93], v[74:77], v[184:187], v[90:93]
	s_barrier
	s_add_i32 s59, 0, 0x14000
	v_add_u32_e32 v192, s59, v194
	s_add_i32 s58, s58, s20
	ds_read_b128 v[188:191], v192
	ds_read_b128 v[220:223], v192 offset:1024
	ds_read_b128 v[224:227], v192 offset:2048
	ds_read_b128 v[228:231], v192 offset:3072
	v_lshl_add_u64 v[192:193], s[52:53], 0, v[0:1]
	s_mov_b32 m0, s58
	v_lshl_add_u64 v[198:199], s[52:53], 0, v[174:175]
	global_load_lds_dwordx4 v[192:193], off
	s_add_i32 m0, s58, 0x2000
	s_nop 0
	global_load_lds_dwordx4 v[198:199], off
	s_waitcnt lgkmcnt(0)
	s_barrier
	v_mfma_f32_16x16x32_bf16 v[134:137], v[188:191], v[138:141], v[134:137]
	v_mfma_f32_16x16x32_bf16 v[130:133], v[224:227], v[138:141], v[130:133]
	v_mfma_f32_16x16x32_bf16 v[118:121], v[188:191], v[146:149], v[118:121]
	v_mfma_f32_16x16x32_bf16 v[114:117], v[224:227], v[146:149], v[114:117]
	v_mfma_f32_16x16x32_bf16 v[102:105], v[188:191], v[162:165], v[102:105]
	v_mfma_f32_16x16x32_bf16 v[98:101], v[224:227], v[162:165], v[98:101]
	v_mfma_f32_16x16x32_bf16 v[86:89], v[188:191], v[170:173], v[86:89]
	v_mfma_f32_16x16x32_bf16 v[82:85], v[224:227], v[170:173], v[82:85]
	v_mfma_f32_16x16x32_bf16 v[134:137], v[220:223], v[142:145], v[134:137]
	v_mfma_f32_16x16x32_bf16 v[130:133], v[228:231], v[142:145], v[130:133]
	v_mfma_f32_16x16x32_bf16 v[118:121], v[220:223], v[150:153], v[118:121]
	v_mfma_f32_16x16x32_bf16 v[114:117], v[228:231], v[150:153], v[114:117]
	v_mfma_f32_16x16x32_bf16 v[102:105], v[220:223], v[166:169], v[102:105]
	v_mfma_f32_16x16x32_bf16 v[98:101], v[228:231], v[166:169], v[98:101]
	v_mfma_f32_16x16x32_bf16 v[86:89], v[220:223], v[184:187], v[86:89]
	v_mfma_f32_16x16x32_bf16 v[82:85], v[228:231], v[184:187], v[82:85]
	s_barrier
	s_mov_b32 m0, s21
	v_lshl_add_u64 v[232:233], s[44:45], 0, v[0:1]
	ds_read_b128 v[138:141], v196 offset:16384
	ds_read_b128 v[142:145], v196 offset:17408
	ds_read_b128 v[146:149], v196 offset:18432
	ds_read_b128 v[150:153], v196 offset:19456
	ds_read_b128 v[162:165], v196 offset:20480
	ds_read_b128 v[166:169], v196 offset:21504
	ds_read_b128 v[170:173], v196 offset:22528
	ds_read_b128 v[184:187], v196 offset:23552
	global_load_lds_dwordx4 v[232:233], off
	v_lshl_add_u64 v[234:235], s[44:45], 0, v[174:175]
	s_mov_b32 m0, s50
	s_nop 0
	global_load_lds_dwordx4 v[234:235], off
	s_waitcnt lgkmcnt(0)
	s_barrier
	v_mfma_f32_16x16x32_bf16 v[78:81], v[58:61], v[138:141], v[78:81]
	v_mfma_f32_16x16x32_bf16 v[66:69], v[70:73], v[138:141], v[66:69]
	v_mfma_f32_16x16x32_bf16 v[46:49], v[58:61], v[146:149], v[46:49]
	v_mfma_f32_16x16x32_bf16 v[42:45], v[70:73], v[146:149], v[42:45]
	v_mfma_f32_16x16x32_bf16 v[30:33], v[58:61], v[162:165], v[30:33]
	v_mfma_f32_16x16x32_bf16 v[26:29], v[70:73], v[162:165], v[26:29]
	v_mfma_f32_16x16x32_bf16 v[14:17], v[58:61], v[170:173], v[14:17]
	v_mfma_f32_16x16x32_bf16 v[10:13], v[70:73], v[170:173], v[10:13]
	v_mfma_f32_16x16x32_bf16 v[78:81], v[62:65], v[142:145], v[78:81]
	v_mfma_f32_16x16x32_bf16 v[66:69], v[74:77], v[142:145], v[66:69]
	v_mfma_f32_16x16x32_bf16 v[46:49], v[62:65], v[150:153], v[46:49]
	v_mfma_f32_16x16x32_bf16 v[42:45], v[74:77], v[150:153], v[42:45]
	v_mfma_f32_16x16x32_bf16 v[30:33], v[62:65], v[166:169], v[30:33]
	v_mfma_f32_16x16x32_bf16 v[26:29], v[74:77], v[166:169], v[26:29]
	v_mfma_f32_16x16x32_bf16 v[14:17], v[62:65], v[184:187], v[14:17]
	v_mfma_f32_16x16x32_bf16 v[10:13], v[74:77], v[184:187], v[10:13]
	s_barrier
; #define PG8_STAGE(bufoff, gbase, voff) do { _Pragma("unroll") for (int _i = 0; _i < 2; ++_i) \
;         __builtin_amdgcn_global_load_lds((const unsigned*)((const char*)(gbase) + (voff)[_i]), (LAS unsigned*)(lds + (bufoff) + ldsw + _i * 8192), 16, 0, 0); } while (0)
; #define PG8_LDA(dst, b, h) do { _Pragma("unroll") for (int m = 0; m < 4; ++m) _Pragma("unroll") for (int k = 0; k < 2; ++k) dst[m][k] = *(const LAS bf16x8*)(lds + PG8_SA(b, h) + aoff + m * 2048 + k * 1024); } while (0)
; #define PG8_LDB(dst, b, h) do { _Pragma("unroll") for (int n = 0; n < 2; ++n) _Pragma("unroll") for (int k = 0; k < 2; ++k) dst[n][k] = *(const LAS bf16x8*)(lds + PG8_SB(b, h) + boff + n * 2048 + k * 1024); } while (0)
; #define PG8_MMA(ai, bj, At, Bt) do { __builtin_amdgcn_s_setprio(1); _Pragma("unroll") for (int m = 0; m < 4; ++m) _Pragma("unroll") for (int n = 0; n < 2; ++n) _Pragma("unroll") for (int k = 0; k < 2; ++k) \
;         acc[ai][bj][m][n] = __builtin_amdgcn_mfma_f32_16x16x32_bf16(Bt[n][k], At[m][k], acc[ai][bj][m][n], 0, 0, 0); __builtin_amdgcn_s_setprio(0); } while (0)
; #define PG8_WAIT_V(n) asm volatile("s_waitcnt vmcnt(" #n ")" ::: "memory")
; #define PG8_WAIT_L(n) asm volatile("s_waitcnt lgkmcnt(" #n ")" ::: "memory")
; #define PG8_BAR __builtin_amdgcn_s_barrier()
; #define PG8_SCHED __builtin_amdgcn_sched_barrier(0)
; template <int MODE, class EpiT, class Sched>
; __device__ __forceinline__ void gemm_phase(LAS unsigned char* lds, const Gemm g, const Sched& S, const EpiT& E) {
;     ...
;             PG8_STAGE(PG8_SB(0, 1), b2 + hstep, voffB);
;             PG8_WAIT_V(6); PG8_BAR; PG8_MMA(1, 1, At, B1); PG8_BAR;
;             PG8_LDB(B0, 1, 0); PG8_SCHED; PG8_LDA(At, 1, 0); PG8_STAGE(PG8_SA(0, 1), a2 + hstep, voffA);
;             PG8_WAIT_L(8); PG8_BAR; PG8_WAIT_L(0); PG8_MMA(0, 0, At, B0); PG8_BAR; PG8_SCHED;
;             PG8_LDB(B1, 1, 1); PG8_STAGE(PG8_SB(1, 0), b3, voffB);
;             PG8_BAR; PG8_WAIT_L(0); PG8_MMA(0, 1, At, B1); PG8_BAR;
;             PG8_LDA(At, 1, 1); PG8_STAGE(PG8_SA(1, 0), a3, voffA);
;             PG8_BAR; PG8_WAIT_L(0); PG8_MMA(1, 0, At, B0); PG8_BAR; PG8_SCHED;
	s_add_u32 s52, s52, s38
	s_addc_u32 s53, s53, 0
	s_add_i32 s58, s59, s20
	v_lshl_add_u64 v[236:237], s[52:53], 0, v[0:1]
	s_mov_b32 m0, s58
	v_lshl_add_u64 v[238:239], s[52:53], 0, v[174:175]
	global_load_lds_dwordx4 v[236:237], off
	s_add_i32 m0, s58, 0x2000
	s_nop 0
	global_load_lds_dwordx4 v[238:239], off
	s_waitcnt vmcnt(6)
	s_barrier
	v_mfma_f32_16x16x32_bf16 v[54:57], v[188:191], v[138:141], v[54:57]
	v_mfma_f32_16x16x32_bf16 v[50:53], v[224:227], v[138:141], v[50:53]
	v_mfma_f32_16x16x32_bf16 v[38:41], v[188:191], v[146:149], v[38:41]
	v_mfma_f32_16x16x32_bf16 v[34:37], v[224:227], v[146:149], v[34:37]
	v_mfma_f32_16x16x32_bf16 v[22:25], v[188:191], v[162:165], v[22:25]
	v_mfma_f32_16x16x32_bf16 v[18:21], v[224:227], v[162:165], v[18:21]
	v_mfma_f32_16x16x32_bf16 v[6:9], v[188:191], v[170:173], v[6:9]
	v_mfma_f32_16x16x32_bf16 v[2:5], v[224:227], v[170:173], v[2:5]
	v_mfma_f32_16x16x32_bf16 v[54:57], v[220:223], v[142:145], v[54:57]
	v_mfma_f32_16x16x32_bf16 v[50:53], v[228:231], v[142:145], v[50:53]
	v_mfma_f32_16x16x32_bf16 v[38:41], v[220:223], v[150:153], v[38:41]
	v_mfma_f32_16x16x32_bf16 v[34:37], v[228:231], v[150:153], v[34:37]
	v_mfma_f32_16x16x32_bf16 v[22:25], v[220:223], v[166:169], v[22:25]
	v_mfma_f32_16x16x32_bf16 v[18:21], v[228:231], v[166:169], v[18:21]
	v_mfma_f32_16x16x32_bf16 v[6:9], v[220:223], v[184:187], v[6:9]
	v_mfma_f32_16x16x32_bf16 v[2:5], v[228:231], v[184:187], v[2:5]
	s_barrier
	s_add_i32 s52, 0, 0x18000
	v_add_u32_e32 v74, s52, v194
	ds_read_b128 v[58:61], v74
	ds_read_b128 v[62:65], v74 offset:1024
	ds_read_b128 v[70:73], v74 offset:2048
	ds_read_b128 v[74:77], v74 offset:3072
	s_add_u32 s44, s44, s38
	s_addc_u32 s45, s45, 0
	s_mov_b32 m0, s51
	v_lshl_add_u64 v[188:189], s[44:45], 0, v[0:1]
	ds_read_b128 v[138:141], v196 offset:32768
	ds_read_b128 v[142:145], v196 offset:33792
	ds_read_b128 v[146:149], v196 offset:34816
	ds_read_b128 v[150:153], v196 offset:35840
	ds_read_b128 v[162:165], v196 offset:36864
	ds_read_b128 v[166:169], v196 offset:37888
	ds_read_b128 v[170:173], v196 offset:38912
	ds_read_b128 v[184:187], v196 offset:39936
	global_load_lds_dwordx4 v[188:189], off
	v_lshl_add_u64 v[188:189], s[44:45], 0, v[174:175]
	s_mov_b32 m0, s56
	s_nop 0
	global_load_lds_dwordx4 v[188:189], off
	s_waitcnt lgkmcnt(0)
	s_barrier
	v_mfma_f32_16x16x32_bf16 v[158:161], v[58:61], v[138:141], v[158:161]
	v_mfma_f32_16x16x32_bf16 v[154:157], v[70:73], v[138:141], v[154:157]
	v_mfma_f32_16x16x32_bf16 v[126:129], v[58:61], v[146:149], v[126:129]
	v_mfma_f32_16x16x32_bf16 v[122:125], v[70:73], v[146:149], v[122:125]
	v_mfma_f32_16x16x32_bf16 v[110:113], v[58:61], v[162:165], v[110:113]
	v_mfma_f32_16x16x32_bf16 v[106:109], v[70:73], v[162:165], v[106:109]
	v_mfma_f32_16x16x32_bf16 v[94:97], v[58:61], v[170:173], v[94:97]
	v_mfma_f32_16x16x32_bf16 v[90:93], v[70:73], v[170:173], v[90:93]
	v_mfma_f32_16x16x32_bf16 v[158:161], v[62:65], v[142:145], v[158:161]
	v_mfma_f32_16x16x32_bf16 v[154:157], v[74:77], v[142:145], v[154:157]
	v_mfma_f32_16x16x32_bf16 v[126:129], v[62:65], v[150:153], v[126:129]
	v_mfma_f32_16x16x32_bf16 v[122:125], v[74:77], v[150:153], v[122:125]
	v_mfma_f32_16x16x32_bf16 v[110:113], v[62:65], v[166:169], v[110:113]
	v_mfma_f32_16x16x32_bf16 v[106:109], v[74:77], v[166:169], v[106:109]
	v_mfma_f32_16x16x32_bf16 v[94:97], v[62:65], v[184:187], v[94:97]
	v_mfma_f32_16x16x32_bf16 v[90:93], v[74:77], v[184:187], v[90:93]
	s_barrier
	s_add_i32 s44, 0, 0x1c000
	s_add_i32 s45, s52, s20
	v_add_u32_e32 v197, s44, v194
	v_lshl_add_u64 v[192:193], v[192:193], 0, s[76:77]
	s_mov_b32 m0, s45
	ds_read_b128 v[188:191], v197
	ds_read_b128 v[220:223], v197 offset:1024
	ds_read_b128 v[224:227], v197 offset:2048
	ds_read_b128 v[228:231], v197 offset:3072
	global_load_lds_dwordx4 v[192:193], off
	v_lshl_add_u64 v[192:193], v[198:199], 0, s[76:77]
	s_add_i32 m0, s45, 0x2000
	s_nop 0
	global_load_lds_dwordx4 v[192:193], off
	s_waitcnt lgkmcnt(0)
	s_barrier
; #define PG8_STAGE(bufoff, gbase, voff) do { _Pragma("unroll") for (int _i = 0; _i < 2; ++_i) \
;         __builtin_amdgcn_global_load_lds((const unsigned*)((const char*)(gbase) + (voff)[_i]), (LAS unsigned*)(lds + (bufoff) + ldsw + _i * 8192), 16, 0, 0); } while (0)
; #define PG8_MMA(ai, bj, At, Bt) do { __builtin_amdgcn_s_setprio(1); _Pragma("unroll") for (int m = 0; m < 4; ++m) _Pragma("unroll") for (int n = 0; n < 2; ++n) _Pragma("unroll") for (int k = 0; k < 2; ++k) \
;         acc[ai][bj][m][n] = __builtin_amdgcn_mfma_f32_16x16x32_bf16(Bt[n][k], At[m][k], acc[ai][bj][m][n], 0, 0, 0); __builtin_amdgcn_s_setprio(0); } while (0)
; #define PG8_WAIT_V(n) asm volatile("s_waitcnt vmcnt(" #n ")" ::: "memory")
; #define PG8_WAIT_L(n) asm volatile("s_waitcnt lgkmcnt(" #n ")" ::: "memory")
; #define PG8_BAR __builtin_amdgcn_s_barrier()
; #define PG8_SCHED __builtin_amdgcn_sched_barrier(0)
;     template <int mode> __device__ __forceinline__ void run(const f32x4 (&acc)[2][2][4][2], const Unit& u, int wr, int wc, int fr, int fq, const LAS float* sc) const {
;     ...
;             const int col0 = u.pn * BM + wc * 32 + 8 * fq;
;             f32x4 bv[2][2];
; #pragma unroll
;             for (int bj = 0; bj < 2; ++bj)
; #pragma unroll
;                 for (int n = 0; n < 2; ++n) bv[bj][n] = bias ? *(const f32x4*)(bias + col0 + bj * HALF + 4 * n) : (f32x4){0.f, 0.f, 0.f, 0.f};
; template <int MODE, class EpiT, class Sched>
; __device__ __forceinline__ void gemm_phase(LAS unsigned char* lds, const Gemm g, const Sched& S, const EpiT& E) {
;     ...
;             PG8_BAR; PG8_WAIT_L(0); PG8_MMA(1, 0, At, B0); PG8_BAR; PG8_SCHED;
;             PG8_STAGE(PG8_SB(1, 1), b3 + hstep, voffB);
;             PG8_WAIT_V(6); PG8_BAR; PG8_MMA(1, 1, At, B1); PG8_BAR;
	v_mfma_f32_16x16x32_bf16 v[134:137], v[188:191], v[138:141], v[134:137]
	v_mfma_f32_16x16x32_bf16 v[130:133], v[224:227], v[138:141], v[130:133]
	v_mfma_f32_16x16x32_bf16 v[118:121], v[188:191], v[146:149], v[118:121]
	v_mfma_f32_16x16x32_bf16 v[114:117], v[224:227], v[146:149], v[114:117]
	v_mfma_f32_16x16x32_bf16 v[102:105], v[188:191], v[162:165], v[102:105]
	v_mfma_f32_16x16x32_bf16 v[98:101], v[224:227], v[162:165], v[98:101]
	v_mfma_f32_16x16x32_bf16 v[86:89], v[188:191], v[170:173], v[86:89]
	v_mfma_f32_16x16x32_bf16 v[82:85], v[224:227], v[170:173], v[82:85]
	v_mfma_f32_16x16x32_bf16 v[134:137], v[220:223], v[142:145], v[134:137]
	v_mfma_f32_16x16x32_bf16 v[130:133], v[228:231], v[142:145], v[130:133]
	v_mfma_f32_16x16x32_bf16 v[118:121], v[220:223], v[150:153], v[118:121]
	v_mfma_f32_16x16x32_bf16 v[114:117], v[228:231], v[150:153], v[114:117]
	v_mfma_f32_16x16x32_bf16 v[102:105], v[220:223], v[166:169], v[102:105]
	v_mfma_f32_16x16x32_bf16 v[98:101], v[228:231], v[166:169], v[98:101]
	v_mfma_f32_16x16x32_bf16 v[86:89], v[220:223], v[184:187], v[86:89]
	v_mfma_f32_16x16x32_bf16 v[82:85], v[228:231], v[184:187], v[82:85]
	s_barrier
	s_mov_b32 m0, s61
	v_lshl_add_u64 v[192:193], v[232:233], 0, s[76:77]
	ds_read_b128 v[138:141], v196 offset:49152
	ds_read_b128 v[142:145], v196 offset:50176
	ds_read_b128 v[146:149], v196 offset:51200
	ds_read_b128 v[150:153], v196 offset:52224
	ds_read_b128 v[162:165], v196 offset:53248
	ds_read_b128 v[166:169], v196 offset:54272
	ds_read_b128 v[170:173], v196 offset:55296
	ds_read_b128 v[184:187], v196 offset:56320
	global_load_lds_dwordx4 v[192:193], off
	v_lshl_add_u64 v[192:193], v[234:235], 0, s[76:77]
	s_mov_b32 m0, s74
	s_nop 0
	global_load_lds_dwordx4 v[192:193], off
	s_waitcnt lgkmcnt(0)
	s_barrier
	v_mfma_f32_16x16x32_bf16 v[78:81], v[58:61], v[138:141], v[78:81]
	v_mfma_f32_16x16x32_bf16 v[66:69], v[70:73], v[138:141], v[66:69]
	v_mfma_f32_16x16x32_bf16 v[46:49], v[58:61], v[146:149], v[46:49]
	v_mfma_f32_16x16x32_bf16 v[42:45], v[70:73], v[146:149], v[42:45]
	v_mfma_f32_16x16x32_bf16 v[30:33], v[58:61], v[162:165], v[30:33]
	v_mfma_f32_16x16x32_bf16 v[26:29], v[70:73], v[162:165], v[26:29]
	v_mfma_f32_16x16x32_bf16 v[14:17], v[58:61], v[170:173], v[14:17]
	v_mfma_f32_16x16x32_bf16 v[10:13], v[70:73], v[170:173], v[10:13]
	v_mfma_f32_16x16x32_bf16 v[78:81], v[62:65], v[142:145], v[78:81]
	v_mfma_f32_16x16x32_bf16 v[66:69], v[74:77], v[142:145], v[66:69]
	v_mfma_f32_16x16x32_bf16 v[46:49], v[62:65], v[150:153], v[46:49]
	v_mfma_f32_16x16x32_bf16 v[42:45], v[74:77], v[150:153], v[42:45]
	v_mfma_f32_16x16x32_bf16 v[30:33], v[62:65], v[166:169], v[30:33]
	v_mfma_f32_16x16x32_bf16 v[26:29], v[74:77], v[166:169], v[26:29]
	v_mfma_f32_16x16x32_bf16 v[14:17], v[62:65], v[184:187], v[14:17]
	v_mfma_f32_16x16x32_bf16 v[10:13], v[74:77], v[184:187], v[10:13]
	s_barrier
	s_add_i32 s44, s44, s20
	v_lshl_add_u64 v[58:59], v[236:237], 0, s[76:77]
	s_mov_b32 m0, s44
	s_nop 0
	global_load_lds_dwordx4 v[58:59], off
	v_lshl_add_u64 v[58:59], v[238:239], 0, s[76:77]
	s_add_i32 m0, s44, 0x2000
	s_nop 0
	global_load_lds_dwordx4 v[58:59], off
	s_waitcnt vmcnt(6)
	s_barrier
	v_mfma_f32_16x16x32_bf16 v[54:57], v[188:191], v[138:141], v[54:57]
	v_mfma_f32_16x16x32_bf16 v[50:53], v[224:227], v[138:141], v[50:53]
	v_mfma_f32_16x16x32_bf16 v[38:41], v[188:191], v[146:149], v[38:41]
	v_mfma_f32_16x16x32_bf16 v[34:37], v[224:227], v[146:149], v[34:37]
	v_mfma_f32_16x16x32_bf16 v[22:25], v[188:191], v[162:165], v[22:25]
	v_mfma_f32_16x16x32_bf16 v[18:21], v[224:227], v[162:165], v[18:21]
	v_mfma_f32_16x16x32_bf16 v[6:9], v[188:191], v[170:173], v[6:9]
	v_mfma_f32_16x16x32_bf16 v[2:5], v[224:227], v[170:173], v[2:5]
	v_mfma_f32_16x16x32_bf16 v[54:57], v[220:223], v[142:145], v[54:57]
	v_mfma_f32_16x16x32_bf16 v[50:53], v[228:231], v[142:145], v[50:53]
	v_mfma_f32_16x16x32_bf16 v[38:41], v[220:223], v[150:153], v[38:41]
	v_mfma_f32_16x16x32_bf16 v[34:37], v[228:231], v[150:153], v[34:37]
	v_mfma_f32_16x16x32_bf16 v[22:25], v[220:223], v[166:169], v[22:25]
	v_mfma_f32_16x16x32_bf16 v[18:21], v[228:231], v[166:169], v[18:21]
	v_mfma_f32_16x16x32_bf16 v[6:9], v[220:223], v[184:187], v[6:9]
	v_mfma_f32_16x16x32_bf16 v[2:5], v[228:231], v[184:187], v[2:5]
	s_barrier
	s_add_u32 s4, s4, 0x100
	s_addc_u32 s5, s5, 0
	s_add_u32 s89, s89, 0x100
	s_addc_u32 s90, s90, 0
	s_cmp_ge_u32 vcc_lo, s60
	s_mov_b32 s44, vcc_lo
	s_cbranch_scc0 .LBB0_195
	v_lshl_or_b32 v186, s24, 8, v195
	v_ashrrev_i32_e32 v187, 31, v186
	v_mov_b32_e32 v70, 0
	v_cndmask_b32_e64 v58, 0, 1, s[78:79]
	v_lshl_add_u64 v[138:139], v[186:187], 2, s[12:13]
	v_cmp_ne_u32_e64 s[44:45], 1, v58
	s_andn2_b64 vcc, exec, s[78:79]
	v_mov_b32_e32 v74, 0
	v_mov_b32_e32 v75, v70
	v_mov_b32_e32 v184, 0
	v_mov_b32_e32 v185, v70
	s_cbranch_vccnz .LBB0_198
	global_load_dwordx4 v[74:77], v[138:139], off
	s_waitcnt vmcnt(0)
	v_mov_b32_e32 v184, v76
	v_mov_b32_e32 v185, v77

; #define PG8_STAGE(bufoff, gbase, voff) do { _Pragma("unroll") for (int _i = 0; _i < 2; ++_i) \
;         __builtin_amdgcn_global_load_lds((const unsigned*)((const char*)(gbase) + (voff)[_i]), (LAS unsigned*)(lds + (bufoff) + ldsw + _i * 8192), 16, 0, 0); } while (0)
; #define PG8_LDA(dst, b, h) do { _Pragma("unroll") for (int m = 0; m < 4; ++m) _Pragma("unroll") for (int k = 0; k < 2; ++k) dst[m][k] = *(const LAS bf16x8*)(lds + PG8_SA(b, h) + aoff + m * 2048 + k * 1024); } while (0)
; #define PG8_LDB(dst, b, h) do { _Pragma("unroll") for (int n = 0; n < 2; ++n) _Pragma("unroll") for (int k = 0; k < 2; ++k) dst[n][k] = *(const LAS bf16x8*)(lds + PG8_SB(b, h) + boff + n * 2048 + k * 1024); } while (0)
; #define PG8_MMA(ai, bj, At, Bt) do { __builtin_amdgcn_s_setprio(1); _Pragma("unroll") for (int m = 0; m < 4; ++m) _Pragma("unroll") for (int n = 0; n < 2; ++n) _Pragma("unroll") for (int k = 0; k < 2; ++k) \
;         acc[ai][bj][m][n] = __builtin_amdgcn_mfma_f32_16x16x32_bf16(Bt[n][k], At[m][k], acc[ai][bj][m][n], 0, 0, 0); __builtin_amdgcn_s_setprio(0); } while (0)
; #define PG8_WAIT_L(n) asm volatile("s_waitcnt lgkmcnt(" #n ")" ::: "memory")
; template <int MODE, class EpiT, class Sched>
; __device__ __forceinline__ void gemm_phase(LAS unsigned char* lds, const Gemm g, const Sched& S, const EpiT& E) {
;     ...
;         const bool has_next = S.next(ui + 1, nxt);
;         const char* nA = has_next ? (const char*)g.A + (size_t)nxt.pm * tstep : cA; const char* nB = has_next ? (const char*)g.Bt + (size_t)nxt.pn * tstep : cB;
;         for (int t = 0; t < nt; t += 2) {
;             const bool last = (t == nt - 2);
;             const char* a1 = cA + (size_t)(t + 1) * kstep;
;             const char* a2 = last ? nA : cA + (size_t)(t + 2) * kstep; const char* b2 = last ? nB : cB + (size_t)(t + 2) * kstep;
;             const char* a3 = a2 + kstep; const char* b3 = b2 + kstep;
;             PG8_LDB(B0, 0, 0); PG8_SCHED; PG8_LDA(At, 0, 0); PG8_STAGE(PG8_SA(1, 1), a1 + hstep, voffA);
;             PG8_WAIT_L(8); PG8_BAR; PG8_WAIT_L(0); PG8_MMA(0, 0, At, B0); PG8_BAR; PG8_SCHED;
;             PG8_LDB(B1, 0, 1); PG8_STAGE(PG8_SB(0, 0), b2, voffB);
;             PG8_BAR; PG8_WAIT_L(0); PG8_MMA(0, 1, At, B1); PG8_BAR;
;             PG8_LDA(At, 0, 1); PG8_STAGE(PG8_SA(0, 0), a2, voffA);
;             PG8_BAR; PG8_WAIT_L(0); PG8_MMA(1, 0, At, B0); PG8_BAR; PG8_SCHED;
.LBB0_236:
	s_add_i32 s44, s34, 2
	s_add_u32 s38, s28, 0x80
	s_addc_u32 s35, s29, 0
	s_add_i32 s45, 0, 0x10000
	v_add_u32_e32 v136, s45, v139
	ds_read_b128 v[142:145], v136
	ds_read_b128 v[146:149], v136 offset:1024
	ds_read_b128 v[150:153], v136 offset:2048
	ds_read_b128 v[154:157], v136 offset:3072
	s_cmp_eq_u32 s52, s34
	s_cselect_b32 s34, s4, s38
	s_cselect_b32 s35, s5, s35
	s_cselect_b32 s39, s11, s43
	s_cselect_b32 s38, s10, s42
	v_lshl_add_u64 v[136:137], s[28:29], 0, v[132:133]
	s_add_i32 m0, s22, 0xc000
	ds_read_b128 v[158:161], v141
	ds_read_b128 v[162:165], v141 offset:1024
	ds_read_b128 v[166:169], v141 offset:2048
	ds_read_b128 v[170:173], v141 offset:3072
	ds_read_b128 v[174:177], v141 offset:4096
	ds_read_b128 v[182:185], v141 offset:5120
	ds_read_b128 v[186:189], v141 offset:6144
	ds_read_b128 v[190:193], v141 offset:7168
	global_load_lds_dwordx4 v[136:137], off
	v_lshl_add_u64 v[136:137], s[28:29], 0, v[134:135]
	s_add_i32 m0, s22, 0xe000
	s_nop 0
	global_load_lds_dwordx4 v[136:137], off
	s_waitcnt lgkmcnt(0)
	s_barrier
	v_mfma_f32_16x16x32_bf16 v[126:129], v[142:145], v[158:161], v[126:129]
	v_mfma_f32_16x16x32_bf16 v[122:125], v[150:153], v[158:161], v[122:125]
	v_mfma_f32_16x16x32_bf16 v[118:121], v[142:145], v[166:169], v[118:121]
	v_mfma_f32_16x16x32_bf16 v[110:113], v[150:153], v[166:169], v[110:113]
	v_mfma_f32_16x16x32_bf16 v[102:105], v[142:145], v[174:177], v[102:105]
	v_mfma_f32_16x16x32_bf16 v[94:97], v[150:153], v[174:177], v[94:97]
	v_mfma_f32_16x16x32_bf16 v[86:89], v[142:145], v[186:189], v[86:89]
	v_mfma_f32_16x16x32_bf16 v[78:81], v[150:153], v[186:189], v[78:81]
	v_mfma_f32_16x16x32_bf16 v[126:129], v[146:149], v[162:165], v[126:129]
	v_mfma_f32_16x16x32_bf16 v[122:125], v[154:157], v[162:165], v[122:125]
	v_mfma_f32_16x16x32_bf16 v[118:121], v[146:149], v[170:173], v[118:121]
	v_mfma_f32_16x16x32_bf16 v[110:113], v[154:157], v[170:173], v[110:113]
	v_mfma_f32_16x16x32_bf16 v[102:105], v[146:149], v[182:185], v[102:105]
	v_mfma_f32_16x16x32_bf16 v[94:97], v[154:157], v[182:185], v[94:97]
	v_mfma_f32_16x16x32_bf16 v[86:89], v[146:149], v[190:193], v[86:89]
	v_mfma_f32_16x16x32_bf16 v[78:81], v[154:157], v[190:193], v[78:81]
	s_barrier
	s_add_i32 s58, 0, 0x14000
	v_add_u32_e32 v136, s58, v139
	s_add_i32 s45, s45, s9
	ds_read_b128 v[194:197], v136
	ds_read_b128 v[220:223], v136 offset:1024
	ds_read_b128 v[224:227], v136 offset:2048
	ds_read_b128 v[228:231], v136 offset:3072
	v_lshl_add_u64 v[136:137], s[38:39], 0, v[0:1]
	s_mov_b32 m0, s45
	v_lshl_add_u64 v[198:199], s[38:39], 0, v[130:131]
	global_load_lds_dwordx4 v[136:137], off
	s_add_i32 m0, s45, 0x2000
	s_nop 0
	global_load_lds_dwordx4 v[198:199], off
	s_waitcnt lgkmcnt(0)
	s_barrier
	v_mfma_f32_16x16x32_bf16 v[114:117], v[194:197], v[158:161], v[114:117]
	v_mfma_f32_16x16x32_bf16 v[106:109], v[224:227], v[158:161], v[106:109]
	v_mfma_f32_16x16x32_bf16 v[98:101], v[194:197], v[166:169], v[98:101]
	v_mfma_f32_16x16x32_bf16 v[90:93], v[224:227], v[166:169], v[90:93]
	v_mfma_f32_16x16x32_bf16 v[82:85], v[194:197], v[174:177], v[82:85]
	v_mfma_f32_16x16x32_bf16 v[74:77], v[224:227], v[174:177], v[74:77]
	v_mfma_f32_16x16x32_bf16 v[70:73], v[194:197], v[186:189], v[70:73]
	v_mfma_f32_16x16x32_bf16 v[66:69], v[224:227], v[186:189], v[66:69]
	v_mfma_f32_16x16x32_bf16 v[114:117], v[220:223], v[162:165], v[114:117]
	v_mfma_f32_16x16x32_bf16 v[106:109], v[228:231], v[162:165], v[106:109]
	v_mfma_f32_16x16x32_bf16 v[98:101], v[220:223], v[170:173], v[98:101]
	v_mfma_f32_16x16x32_bf16 v[90:93], v[228:231], v[170:173], v[90:93]
	v_mfma_f32_16x16x32_bf16 v[82:85], v[220:223], v[182:185], v[82:85]
	v_mfma_f32_16x16x32_bf16 v[74:77], v[228:231], v[182:185], v[74:77]
	v_mfma_f32_16x16x32_bf16 v[70:73], v[220:223], v[190:193], v[70:73]
	v_mfma_f32_16x16x32_bf16 v[66:69], v[228:231], v[190:193], v[66:69]
	s_barrier
	s_mov_b32 m0, s22
	v_lshl_add_u64 v[232:233], s[34:35], 0, v[0:1]
	ds_read_b128 v[158:161], v141 offset:16384
	ds_read_b128 v[162:165], v141 offset:17408
	ds_read_b128 v[166:169], v141 offset:18432
	ds_read_b128 v[170:173], v141 offset:19456
	ds_read_b128 v[174:177], v141 offset:20480
	ds_read_b128 v[182:185], v141 offset:21504
	ds_read_b128 v[186:189], v141 offset:22528
	ds_read_b128 v[190:193], v141 offset:23552
	global_load_lds_dwordx4 v[232:233], off
	v_lshl_add_u64 v[234:235], s[34:35], 0, v[130:131]
	s_mov_b32 m0, s23
	s_nop 0
	global_load_lds_dwordx4 v[234:235], off
	s_waitcnt lgkmcnt(0)
	s_barrier
	v_mfma_f32_16x16x32_bf16 v[62:65], v[142:145], v[158:161], v[62:65]
	v_mfma_f32_16x16x32_bf16 v[58:61], v[150:153], v[158:161], v[58:61]
	v_mfma_f32_16x16x32_bf16 v[54:57], v[142:145], v[166:169], v[54:57]
	v_mfma_f32_16x16x32_bf16 v[46:49], v[150:153], v[166:169], v[46:49]
	v_mfma_f32_16x16x32_bf16 v[38:41], v[142:145], v[174:177], v[38:41]
	v_mfma_f32_16x16x32_bf16 v[30:33], v[150:153], v[174:177], v[30:33]
	v_mfma_f32_16x16x32_bf16 v[22:25], v[142:145], v[186:189], v[22:25]
	v_mfma_f32_16x16x32_bf16 v[14:17], v[150:153], v[186:189], v[14:17]
	v_mfma_f32_16x16x32_bf16 v[62:65], v[146:149], v[162:165], v[62:65]
	v_mfma_f32_16x16x32_bf16 v[58:61], v[154:157], v[162:165], v[58:61]
	v_mfma_f32_16x16x32_bf16 v[54:57], v[146:149], v[170:173], v[54:57]
	v_mfma_f32_16x16x32_bf16 v[46:49], v[154:157], v[170:173], v[46:49]
	v_mfma_f32_16x16x32_bf16 v[38:41], v[146:149], v[182:185], v[38:41]
	v_mfma_f32_16x16x32_bf16 v[30:33], v[154:157], v[182:185], v[30:33]
	v_mfma_f32_16x16x32_bf16 v[22:25], v[146:149], v[190:193], v[22:25]
	v_mfma_f32_16x16x32_bf16 v[14:17], v[154:157], v[190:193], v[14:17]
	s_barrier
; #define PG8_STAGE(bufoff, gbase, voff) do { _Pragma("unroll") for (int _i = 0; _i < 2; ++_i) \
;         __builtin_amdgcn_global_load_lds((const unsigned*)((const char*)(gbase) + (voff)[_i]), (LAS unsigned*)(lds + (bufoff) + ldsw + _i * 8192), 16, 0, 0); } while (0)
; #define PG8_LDA(dst, b, h) do { _Pragma("unroll") for (int m = 0; m < 4; ++m) _Pragma("unroll") for (int k = 0; k < 2; ++k) dst[m][k] = *(const LAS bf16x8*)(lds + PG8_SA(b, h) + aoff + m * 2048 + k * 1024); } while (0)
; #define PG8_LDB(dst, b, h) do { _Pragma("unroll") for (int n = 0; n < 2; ++n) _Pragma("unroll") for (int k = 0; k < 2; ++k) dst[n][k] = *(const LAS bf16x8*)(lds + PG8_SB(b, h) + boff + n * 2048 + k * 1024); } while (0)
; #define PG8_MMA(ai, bj, At, Bt) do { __builtin_amdgcn_s_setprio(1); _Pragma("unroll") for (int m = 0; m < 4; ++m) _Pragma("unroll") for (int n = 0; n < 2; ++n) _Pragma("unroll") for (int k = 0; k < 2; ++k) \
;         acc[ai][bj][m][n] = __builtin_amdgcn_mfma_f32_16x16x32_bf16(Bt[n][k], At[m][k], acc[ai][bj][m][n], 0, 0, 0); __builtin_amdgcn_s_setprio(0); } while (0)
; #define PG8_WAIT_V(n) asm volatile("s_waitcnt vmcnt(" #n ")" ::: "memory")
; #define PG8_WAIT_L(n) asm volatile("s_waitcnt lgkmcnt(" #n ")" ::: "memory")
; #define PG8_BAR __builtin_amdgcn_s_barrier()
; #define PG8_SCHED __builtin_amdgcn_sched_barrier(0)
; template <int MODE, class EpiT, class Sched>
; __device__ __forceinline__ void gemm_phase(LAS unsigned char* lds, const Gemm g, const Sched& S, const EpiT& E) {
;     ...
;             PG8_STAGE(PG8_SB(0, 1), b2 + hstep, voffB);
;             PG8_WAIT_V(6); PG8_BAR; PG8_MMA(1, 1, At, B1); PG8_BAR;
;             PG8_LDB(B0, 1, 0); PG8_SCHED; PG8_LDA(At, 1, 0); PG8_STAGE(PG8_SA(0, 1), a2 + hstep, voffA);
;             PG8_WAIT_L(8); PG8_BAR; PG8_WAIT_L(0); PG8_MMA(0, 0, At, B0); PG8_BAR; PG8_SCHED;
;             PG8_LDB(B1, 1, 1); PG8_STAGE(PG8_SB(1, 0), b3, voffB);
;             PG8_BAR; PG8_WAIT_L(0); PG8_MMA(0, 1, At, B1); PG8_BAR;
;             PG8_LDA(At, 1, 1); PG8_STAGE(PG8_SA(1, 0), a3, voffA);
;             PG8_BAR; PG8_WAIT_L(0); PG8_MMA(1, 0, At, B0); PG8_BAR; PG8_SCHED;
	s_add_u32 s38, s38, s24
	s_addc_u32 s39, s39, 0
	s_add_i32 s45, s58, s9
	v_lshl_add_u64 v[236:237], s[38:39], 0, v[0:1]
	s_mov_b32 m0, s45
	v_lshl_add_u64 v[238:239], s[38:39], 0, v[130:131]
	global_load_lds_dwordx4 v[236:237], off
	s_add_i32 m0, s45, 0x2000
	s_nop 0
	global_load_lds_dwordx4 v[238:239], off
	s_waitcnt vmcnt(6)
	s_barrier
	v_mfma_f32_16x16x32_bf16 v[50:53], v[194:197], v[158:161], v[50:53]
	v_mfma_f32_16x16x32_bf16 v[42:45], v[224:227], v[158:161], v[42:45]
	v_mfma_f32_16x16x32_bf16 v[34:37], v[194:197], v[166:169], v[34:37]
	v_mfma_f32_16x16x32_bf16 v[26:29], v[224:227], v[166:169], v[26:29]
	v_mfma_f32_16x16x32_bf16 v[18:21], v[194:197], v[174:177], v[18:21]
	v_mfma_f32_16x16x32_bf16 v[10:13], v[224:227], v[174:177], v[10:13]
	v_mfma_f32_16x16x32_bf16 v[6:9], v[194:197], v[186:189], v[6:9]
	v_mfma_f32_16x16x32_bf16 v[2:5], v[224:227], v[186:189], v[2:5]
	v_mfma_f32_16x16x32_bf16 v[50:53], v[220:223], v[162:165], v[50:53]
	v_mfma_f32_16x16x32_bf16 v[42:45], v[228:231], v[162:165], v[42:45]
	v_mfma_f32_16x16x32_bf16 v[34:37], v[220:223], v[170:173], v[34:37]
	v_mfma_f32_16x16x32_bf16 v[26:29], v[228:231], v[170:173], v[26:29]
	v_mfma_f32_16x16x32_bf16 v[18:21], v[220:223], v[182:185], v[18:21]
	v_mfma_f32_16x16x32_bf16 v[10:13], v[228:231], v[182:185], v[10:13]
	v_mfma_f32_16x16x32_bf16 v[6:9], v[220:223], v[190:193], v[6:9]
	v_mfma_f32_16x16x32_bf16 v[2:5], v[228:231], v[190:193], v[2:5]
	s_barrier
	s_add_i32 s38, 0, 0x18000
	v_add_u32_e32 v154, s38, v139
	ds_read_b128 v[142:145], v154
	ds_read_b128 v[146:149], v154 offset:1024
	ds_read_b128 v[150:153], v154 offset:2048
	ds_read_b128 v[154:157], v154 offset:3072
	s_add_u32 s34, s34, s24
	s_addc_u32 s35, s35, 0
	s_mov_b32 m0, s30
	v_lshl_add_u64 v[194:195], s[34:35], 0, v[0:1]
	ds_read_b128 v[158:161], v141 offset:32768
	ds_read_b128 v[162:165], v141 offset:33792
	ds_read_b128 v[166:169], v141 offset:34816
	ds_read_b128 v[170:173], v141 offset:35840
	ds_read_b128 v[174:177], v141 offset:36864
	ds_read_b128 v[182:185], v141 offset:37888
	ds_read_b128 v[186:189], v141 offset:38912
	ds_read_b128 v[190:193], v141 offset:39936
	global_load_lds_dwordx4 v[194:195], off
	v_lshl_add_u64 v[194:195], s[34:35], 0, v[130:131]
	s_mov_b32 m0, s46
	s_nop 0
	global_load_lds_dwordx4 v[194:195], off
	s_waitcnt lgkmcnt(0)
	s_barrier
	v_mfma_f32_16x16x32_bf16 v[126:129], v[142:145], v[158:161], v[126:129]
	v_mfma_f32_16x16x32_bf16 v[122:125], v[150:153], v[158:161], v[122:125]
	v_mfma_f32_16x16x32_bf16 v[118:121], v[142:145], v[166:169], v[118:121]
	v_mfma_f32_16x16x32_bf16 v[110:113], v[150:153], v[166:169], v[110:113]
	v_mfma_f32_16x16x32_bf16 v[102:105], v[142:145], v[174:177], v[102:105]
	v_mfma_f32_16x16x32_bf16 v[94:97], v[150:153], v[174:177], v[94:97]
	v_mfma_f32_16x16x32_bf16 v[86:89], v[142:145], v[186:189], v[86:89]
	v_mfma_f32_16x16x32_bf16 v[78:81], v[150:153], v[186:189], v[78:81]
	v_mfma_f32_16x16x32_bf16 v[126:129], v[146:149], v[162:165], v[126:129]
	v_mfma_f32_16x16x32_bf16 v[122:125], v[154:157], v[162:165], v[122:125]
	v_mfma_f32_16x16x32_bf16 v[118:121], v[146:149], v[170:173], v[118:121]
	v_mfma_f32_16x16x32_bf16 v[110:113], v[154:157], v[170:173], v[110:113]
	v_mfma_f32_16x16x32_bf16 v[102:105], v[146:149], v[182:185], v[102:105]
	v_mfma_f32_16x16x32_bf16 v[94:97], v[154:157], v[182:185], v[94:97]
	v_mfma_f32_16x16x32_bf16 v[86:89], v[146:149], v[190:193], v[86:89]
	v_mfma_f32_16x16x32_bf16 v[78:81], v[154:157], v[190:193], v[78:81]
	s_barrier
	s_add_i32 s34, 0, 0x1c000
	s_add_i32 s35, s38, s9
	v_add_u32_e32 v181, s34, v139
	v_lshl_add_u64 v[136:137], v[136:137], 0, s[76:77]
	s_mov_b32 m0, s35
	ds_read_b128 v[194:197], v181
	ds_read_b128 v[220:223], v181 offset:1024
	ds_read_b128 v[224:227], v181 offset:2048
	ds_read_b128 v[228:231], v181 offset:3072
	global_load_lds_dwordx4 v[136:137], off
	v_lshl_add_u64 v[136:137], v[198:199], 0, s[76:77]
	s_add_i32 m0, s35, 0x2000
	s_nop 0
	global_load_lds_dwordx4 v[136:137], off
	s_waitcnt lgkmcnt(0)
	s_barrier
	v_mfma_f32_16x16x32_bf16 v[114:117], v[194:197], v[158:161], v[114:117]
	v_mfma_f32_16x16x32_bf16 v[106:109], v[224:227], v[158:161], v[106:109]
	v_mfma_f32_16x16x32_bf16 v[98:101], v[194:197], v[166:169], v[98:101]
	v_mfma_f32_16x16x32_bf16 v[90:93], v[224:227], v[166:169], v[90:93]
	v_mfma_f32_16x16x32_bf16 v[82:85], v[194:197], v[174:177], v[82:85]
	v_mfma_f32_16x16x32_bf16 v[74:77], v[224:227], v[174:177], v[74:77]
	v_mfma_f32_16x16x32_bf16 v[70:73], v[194:197], v[186:189], v[70:73]
	v_mfma_f32_16x16x32_bf16 v[66:69], v[224:227], v[186:189], v[66:69]
	v_mfma_f32_16x16x32_bf16 v[114:117], v[220:223], v[162:165], v[114:117]
	v_mfma_f32_16x16x32_bf16 v[106:109], v[228:231], v[162:165], v[106:109]
	v_mfma_f32_16x16x32_bf16 v[98:101], v[220:223], v[170:173], v[98:101]
	v_mfma_f32_16x16x32_bf16 v[90:93], v[228:231], v[170:173], v[90:93]
	v_mfma_f32_16x16x32_bf16 v[82:85], v[220:223], v[182:185], v[82:85]
	v_mfma_f32_16x16x32_bf16 v[74:77], v[228:231], v[182:185], v[74:77]
	v_mfma_f32_16x16x32_bf16 v[70:73], v[220:223], v[190:193], v[70:73]
	v_mfma_f32_16x16x32_bf16 v[66:69], v[228:231], v[190:193], v[66:69]
	s_barrier
	s_mov_b32 m0, s50
	v_lshl_add_u64 v[136:137], v[232:233], 0, s[76:77]
	ds_read_b128 v[158:161], v141 offset:49152
	ds_read_b128 v[162:165], v141 offset:50176
	ds_read_b128 v[166:169], v141 offset:51200
	ds_read_b128 v[170:173], v141 offset:52224
	ds_read_b128 v[174:177], v141 offset:53248
	ds_read_b128 v[182:185], v141 offset:54272
	ds_read_b128 v[186:189], v141 offset:55296
	ds_read_b128 v[190:193], v141 offset:56320
	global_load_lds_dwordx4 v[136:137], off
	v_lshl_add_u64 v[136:137], v[234:235], 0, s[76:77]
	s_mov_b32 m0, s51
	s_nop 0
	global_load_lds_dwordx4 v[136:137], off
	s_waitcnt lgkmcnt(0)
	s_barrier
; #define PG8_STAGE(bufoff, gbase, voff) do { _Pragma("unroll") for (int _i = 0; _i < 2; ++_i) \
;         __builtin_amdgcn_global_load_lds((const unsigned*)((const char*)(gbase) + (voff)[_i]), (LAS unsigned*)(lds + (bufoff) + ldsw + _i * 8192), 16, 0, 0); } while (0)
; #define PG8_MMA(ai, bj, At, Bt) do { __builtin_amdgcn_s_setprio(1); _Pragma("unroll") for (int m = 0; m < 4; ++m) _Pragma("unroll") for (int n = 0; n < 2; ++n) _Pragma("unroll") for (int k = 0; k < 2; ++k) \
;         acc[ai][bj][m][n] = __builtin_amdgcn_mfma_f32_16x16x32_bf16(Bt[n][k], At[m][k], acc[ai][bj][m][n], 0, 0, 0); __builtin_amdgcn_s_setprio(0); } while (0)
; #define PG8_WAIT_V(n) asm volatile("s_waitcnt vmcnt(" #n ")" ::: "memory")
; #define PG8_WAIT_L(n) asm volatile("s_waitcnt lgkmcnt(" #n ")" ::: "memory")
; #define PG8_BAR __builtin_amdgcn_s_barrier()
; #define PG8_SCHED __builtin_amdgcn_sched_barrier(0)
; template <int MODE, class EpiT, class Sched>
; __device__ __forceinline__ void gemm_phase(LAS unsigned char* lds, const Gemm g, const Sched& S, const EpiT& E) {
;     ...
;             PG8_BAR; PG8_WAIT_L(0); PG8_MMA(1, 0, At, B0); PG8_BAR; PG8_SCHED;
;             PG8_STAGE(PG8_SB(1, 1), b3 + hstep, voffB);
;             PG8_WAIT_V(6); PG8_BAR; PG8_MMA(1, 1, At, B1); PG8_BAR;
;         }
	v_mfma_f32_16x16x32_bf16 v[62:65], v[142:145], v[158:161], v[62:65]
	v_mfma_f32_16x16x32_bf16 v[58:61], v[150:153], v[158:161], v[58:61]
	v_mfma_f32_16x16x32_bf16 v[54:57], v[142:145], v[166:169], v[54:57]
	v_mfma_f32_16x16x32_bf16 v[46:49], v[150:153], v[166:169], v[46:49]
	v_mfma_f32_16x16x32_bf16 v[38:41], v[142:145], v[174:177], v[38:41]
	v_mfma_f32_16x16x32_bf16 v[30:33], v[150:153], v[174:177], v[30:33]
	v_mfma_f32_16x16x32_bf16 v[22:25], v[142:145], v[186:189], v[22:25]
	v_mfma_f32_16x16x32_bf16 v[14:17], v[150:153], v[186:189], v[14:17]
	v_mfma_f32_16x16x32_bf16 v[62:65], v[146:149], v[162:165], v[62:65]
	v_mfma_f32_16x16x32_bf16 v[58:61], v[154:157], v[162:165], v[58:61]
	v_mfma_f32_16x16x32_bf16 v[54:57], v[146:149], v[170:173], v[54:57]
	v_mfma_f32_16x16x32_bf16 v[46:49], v[154:157], v[170:173], v[46:49]
	v_mfma_f32_16x16x32_bf16 v[38:41], v[146:149], v[182:185], v[38:41]
	v_mfma_f32_16x16x32_bf16 v[30:33], v[154:157], v[182:185], v[30:33]
	v_mfma_f32_16x16x32_bf16 v[22:25], v[146:149], v[190:193], v[22:25]
	v_mfma_f32_16x16x32_bf16 v[14:17], v[154:157], v[190:193], v[14:17]
	s_barrier
	s_add_i32 s34, s34, s9
	v_lshl_add_u64 v[136:137], v[236:237], 0, s[76:77]
	s_mov_b32 m0, s34
	s_nop 0
	global_load_lds_dwordx4 v[136:137], off
	v_lshl_add_u64 v[136:137], v[238:239], 0, s[76:77]
	s_add_i32 m0, s34, 0x2000
	s_nop 0
	global_load_lds_dwordx4 v[136:137], off
	s_waitcnt vmcnt(6)
	s_barrier
	v_mfma_f32_16x16x32_bf16 v[50:53], v[194:197], v[158:161], v[50:53]
	v_mfma_f32_16x16x32_bf16 v[42:45], v[224:227], v[158:161], v[42:45]
	v_mfma_f32_16x16x32_bf16 v[34:37], v[194:197], v[166:169], v[34:37]
	v_mfma_f32_16x16x32_bf16 v[26:29], v[224:227], v[166:169], v[26:29]
	v_mfma_f32_16x16x32_bf16 v[18:21], v[194:197], v[174:177], v[18:21]
	v_mfma_f32_16x16x32_bf16 v[10:13], v[224:227], v[174:177], v[10:13]
	v_mfma_f32_16x16x32_bf16 v[6:9], v[194:197], v[186:189], v[6:9]
	v_mfma_f32_16x16x32_bf16 v[2:5], v[224:227], v[186:189], v[2:5]
	v_mfma_f32_16x16x32_bf16 v[50:53], v[220:223], v[162:165], v[50:53]
	v_mfma_f32_16x16x32_bf16 v[42:45], v[228:231], v[162:165], v[42:45]
	v_mfma_f32_16x16x32_bf16 v[34:37], v[220:223], v[170:173], v[34:37]
	v_mfma_f32_16x16x32_bf16 v[26:29], v[228:231], v[170:173], v[26:29]
	v_mfma_f32_16x16x32_bf16 v[18:21], v[220:223], v[182:185], v[18:21]
	v_mfma_f32_16x16x32_bf16 v[10:13], v[228:231], v[182:185], v[10:13]
	v_mfma_f32_16x16x32_bf16 v[6:9], v[220:223], v[190:193], v[6:9]
	v_mfma_f32_16x16x32_bf16 v[2:5], v[228:231], v[190:193], v[2:5]
	s_barrier
	s_add_u32 s28, s28, 0x100
	s_addc_u32 s29, s29, 0
	s_add_u32 s42, s42, 0x100
	s_addc_u32 s43, s43, 0
	s_cmp_ge_u32 s44, s47
	s_mov_b32 s34, s44
	s_cbranch_scc0 .LBB0_236
; __device__ __forceinline__ unsigned pk2(float lo, float hi) { unsigned r; asm volatile("v_cvt_pk_bf16_f32 %0, %1, %2" : "=v"(r) : "v"(lo), "v"(hi)); return r; }
; #define PG8_WAIT_V(n) asm volatile("s_waitcnt vmcnt(" #n ")" ::: "memory")
; #define PG8_BAR __builtin_amdgcn_s_barrier()
;     template <int mode> __device__ __forceinline__ void run(const f32x4 (&acc)[2][2][4][2], const Unit& u, int wr, int wc, int fr, int fq, const LAS float* sc) const {
;     ...
;         } else if (mode == 2) {
;             const int col0 = u.pn * BM + wc * 32 + 8 * fq;
; #pragma unroll
;             for (int ai = 0; ai < 2; ++ai)
; #pragma unroll
;                 for (int m = 0; m < 4; ++m) {
;                     bf16_t* rowp = ob + (size_t)(row0 + ai * HALF + m * 16) * D + col0;
; #pragma unroll
;                     for (int bj = 0; bj < 2; ++bj) {
;                         const f32x4 v0 = acc[ai][bj][m][0], v1 = acc[ai][bj][m][1];
;                         u32x4 w; w.x = pk2(v0[0], v0[1]); w.y = pk2(v0[2], v0[3]); w.z = pk2(v1[0], v1[1]); w.w = pk2(v1[2], v1[3]);
;                         *(u32x4*)(rowp + bj * HALF) = w;
;                     }
;                 }
; template <int MODE, class EpiT, class Sched>
; __device__ __forceinline__ void gemm_phase(LAS unsigned char* lds, const Gemm g, const Sched& S, const EpiT& E) {
;     ...
;         if (!has_next) break;
; #pragma unroll
;         for (int a = 0; a < 2; ++a)
; #pragma unroll
;             for (int b = 0; b < 2; ++b)
; #pragma unroll
;                 for (int m = 0; m < 4; ++m)
; #pragma unroll
;                     for (int n = 0; n < 2; ++n) acc[a][b][m][n] = (f32x4){0.f, 0.f, 0.f, 0.f};
;         cur = nxt; cA = nA; cB = nB; ++ui;
;     }
;     PG8_WAIT_V(0);
;     if (wr == 0) PG8_BAR;
;     PG8_BAR;
	v_lshl_add_u32 v142, s56, 8, v138
	v_lshl_or_b32 v136, s61, 8, v140
	v_ashrrev_i32_e32 v143, 31, v142
	v_ashrrev_i32_e32 v137, 31, v136
	v_lshlrev_b64 v[144:145], 11, v[142:143]
	v_lshl_add_u64 v[144:145], s[6:7], 0, v[144:145]
	v_lshlrev_b64 v[146:147], 1, v[136:137]
	v_lshl_add_u64 v[136:137], v[144:145], 0, v[146:147]
	v_cvt_pk_bf16_f32 v126, v126, v127
	v_cvt_pk_bf16_f32 v127, v128, v129
	v_cvt_pk_bf16_f32 v128, v122, v123
	v_cvt_pk_bf16_f32 v129, v124, v125
	global_store_dwordx4 v[136:137], v[126:129], off
	v_cvt_pk_bf16_f32 v114, v114, v115
	v_cvt_pk_bf16_f32 v115, v116, v117
	v_cvt_pk_bf16_f32 v116, v106, v107
	v_or_b32_e32 v106, 16, v142
	v_ashrrev_i32_e32 v107, 31, v106
	v_lshlrev_b64 v[106:107], 11, v[106:107]
	v_lshl_add_u64 v[106:107], s[6:7], 0, v[106:107]
	v_cvt_pk_bf16_f32 v117, v108, v109
	global_store_dwordx4 v[136:137], v[114:117], off offset:256
	s_mov_b64 s[28:29], 0x40000
	s_mov_b32 s61, s57
	v_lshl_add_u64 v[114:115], v[106:107], 0, v[146:147]
	v_cvt_pk_bf16_f32 v106, v118, v119
	v_cvt_pk_bf16_f32 v107, v120, v121
	v_cvt_pk_bf16_f32 v108, v110, v111
	v_cvt_pk_bf16_f32 v109, v112, v113
	global_store_dwordx4 v[114:115], v[106:109], off
	v_cvt_pk_bf16_f32 v98, v98, v99
	v_cvt_pk_bf16_f32 v99, v100, v101
	v_cvt_pk_bf16_f32 v100, v90, v91
	v_or_b32_e32 v90, 32, v142
	v_ashrrev_i32_e32 v91, 31, v90
	v_lshlrev_b64 v[90:91], 11, v[90:91]
	v_lshl_add_u64 v[90:91], s[6:7], 0, v[90:91]
	v_cvt_pk_bf16_f32 v101, v92, v93
	global_store_dwordx4 v[114:115], v[98:101], off offset:256
	s_mov_b32 s56, s60
	s_mov_b64 s[34:35], s[10:11]
	v_lshl_add_u64 v[98:99], v[90:91], 0, v[146:147]
	v_cvt_pk_bf16_f32 v90, v102, v103
	v_cvt_pk_bf16_f32 v91, v104, v105
	v_cvt_pk_bf16_f32 v92, v94, v95
	v_cvt_pk_bf16_f32 v93, v96, v97
	global_store_dwordx4 v[98:99], v[90:93], off
	v_cvt_pk_bf16_f32 v82, v82, v83
	v_cvt_pk_bf16_f32 v83, v84, v85
	v_cvt_pk_bf16_f32 v84, v74, v75
	v_or_b32_e32 v74, 48, v142
	v_ashrrev_i32_e32 v75, 31, v74
	v_lshlrev_b64 v[74:75], 11, v[74:75]
	v_lshl_add_u64 v[74:75], s[6:7], 0, v[74:75]
	v_cvt_pk_bf16_f32 v85, v76, v77
	global_store_dwordx4 v[98:99], v[82:85], off offset:256
	s_nop 1
	v_lshl_add_u64 v[82:83], v[74:75], 0, v[146:147]
	v_cvt_pk_bf16_f32 v74, v86, v87
	v_cvt_pk_bf16_f32 v75, v88, v89
	v_cvt_pk_bf16_f32 v76, v78, v79
	v_cvt_pk_bf16_f32 v77, v80, v81
	global_store_dwordx4 v[82:83], v[74:77], off
	v_cvt_pk_bf16_f32 v70, v70, v71
	v_cvt_pk_bf16_f32 v71, v72, v73
	v_cvt_pk_bf16_f32 v72, v66, v67
	v_cvt_pk_bf16_f32 v73, v68, v69
	global_store_dwordx4 v[82:83], v[70:73], off offset:256
	v_cvt_pk_bf16_f32 v62, v62, v63
	v_cvt_pk_bf16_f32 v63, v64, v65
	v_cvt_pk_bf16_f32 v64, v58, v59
	v_add_co_u32_e32 v58, vcc, s91, v136
	v_lshl_add_u64 v[66:67], v[136:137], 0, s[28:29]
	s_nop 0
	v_addc_co_u32_e32 v59, vcc, 0, v137, vcc
	v_cvt_pk_bf16_f32 v65, v60, v61
	global_store_dwordx4 v[58:59], v[62:65], off
	v_cvt_pk_bf16_f32 v50, v50, v51
	v_cvt_pk_bf16_f32 v51, v52, v53
	s_mov_b64 s[28:29], 0x48000
	v_cvt_pk_bf16_f32 v52, v42, v43
	v_cvt_pk_bf16_f32 v53, v44, v45
	global_store_dwordx4 v[66:67], v[50:53], off offset:256
	v_cvt_pk_bf16_f32 v42, v54, v55
	v_cvt_pk_bf16_f32 v43, v56, v57
	v_cvt_pk_bf16_f32 v44, v46, v47
	v_cvt_pk_bf16_f32 v45, v48, v49
	s_nop 1
	v_lshl_add_u64 v[50:51], v[136:137], 0, s[28:29]
	s_mov_b32 s28, 0x48000
	v_add_co_u32_e32 v46, vcc, s28, v136
	s_mov_b64 s[28:29], 0x50000
	s_nop 0
	v_addc_co_u32_e32 v47, vcc, 0, v137, vcc
	global_store_dwordx4 v[46:47], v[42:45], off
	v_cvt_pk_bf16_f32 v34, v34, v35
	v_cvt_pk_bf16_f32 v35, v36, v37
	v_cvt_pk_bf16_f32 v36, v26, v27
	v_cvt_pk_bf16_f32 v37, v28, v29
	global_store_dwordx4 v[50:51], v[34:37], off offset:256
	v_cvt_pk_bf16_f32 v26, v38, v39
	v_cvt_pk_bf16_f32 v27, v40, v41
	v_cvt_pk_bf16_f32 v28, v30, v31
	v_cvt_pk_bf16_f32 v29, v32, v33
	s_nop 1
	v_lshl_add_u64 v[34:35], v[136:137], 0, s[28:29]
	s_mov_b32 s28, 0x50000
	v_add_co_u32_e32 v30, vcc, s28, v136
	s_mov_b64 s[28:29], 0x58000
	s_nop 0
	v_addc_co_u32_e32 v31, vcc, 0, v137, vcc
	global_store_dwordx4 v[30:31], v[26:29], off
	v_cvt_pk_bf16_f32 v18, v18, v19
	v_cvt_pk_bf16_f32 v19, v20, v21
	v_cvt_pk_bf16_f32 v20, v10, v11
	v_cvt_pk_bf16_f32 v21, v12, v13
	global_store_dwordx4 v[34:35], v[18:21], off offset:256
	v_cvt_pk_bf16_f32 v10, v22, v23
	v_cvt_pk_bf16_f32 v11, v24, v25
	v_cvt_pk_bf16_f32 v12, v14, v15
	v_cvt_pk_bf16_f32 v13, v16, v17
	s_nop 1
	v_lshl_add_u64 v[18:19], v[136:137], 0, s[28:29]
	s_mov_b32 s28, 0x58000
	v_add_co_u32_e32 v14, vcc, s28, v136
	s_mov_b64 s[28:29], s[4:5]
	s_nop 0
	v_addc_co_u32_e32 v15, vcc, 0, v137, vcc
	s_and_b64 vcc, exec, s[40:41]
	global_store_dwordx4 v[14:15], v[10:13], off
	v_cvt_pk_bf16_f32 v6, v6, v7
	v_cvt_pk_bf16_f32 v7, v8, v9
	v_cvt_pk_bf16_f32 v8, v2, v3
	v_cvt_pk_bf16_f32 v9, v4, v5
	global_store_dwordx4 v[18:19], v[6:9], off offset:256
	s_cbranch_vccz .LBB0_229
	s_waitcnt vmcnt(0)
	v_readlane_b32 s46, v247, 49
	v_readlane_b32 s50, v246, 29
	v_readlane_b32 s56, v246, 31
	v_readlane_b32 s58, v246, 33
	v_readlane_b32 s60, v246, 35
	s_cmpk_gt_u32 s2, 0xff
	s_mov_b32 s52, 0x800000
	s_movk_i32 s53, 0x1000
	s_movk_i32 s23, 0x2000
	s_movk_i32 s30, 0x2840
	s_movk_i32 s42, 0x3000
	s_mov_b64 s[44:45], 0x1800
	v_readlane_b32 s47, v247, 50
	v_readlane_b32 s43, v247, 51
	v_readlane_b32 s51, v246, 30
	v_readlane_b32 s57, v246, 32
	v_readlane_b32 s59, v246, 34
	v_readlane_b32 s61, v246, 36
	s_cbranch_scc1 .LBB0_240
	s_barrier

; #define PG8_STAGE(bufoff, gbase, voff) do { _Pragma("unroll") for (int _i = 0; _i < 2; ++_i) \
;         __builtin_amdgcn_global_load_lds((const unsigned*)((const char*)(gbase) + (voff)[_i]), (LAS unsigned*)(lds + (bufoff) + ldsw + _i * 8192), 16, 0, 0); } while (0)
; #define PG8_LDA(dst, b, h) do { _Pragma("unroll") for (int m = 0; m < 4; ++m) _Pragma("unroll") for (int k = 0; k < 2; ++k) dst[m][k] = *(const LAS bf16x8*)(lds + PG8_SA(b, h) + aoff + m * 2048 + k * 1024); } while (0)
; #define PG8_LDB(dst, b, h) do { _Pragma("unroll") for (int n = 0; n < 2; ++n) _Pragma("unroll") for (int k = 0; k < 2; ++k) dst[n][k] = *(const LAS bf16x8*)(lds + PG8_SB(b, h) + boff + n * 2048 + k * 1024); } while (0)
; #define PG8_MMA(ai, bj, At, Bt) do { __builtin_amdgcn_s_setprio(1); _Pragma("unroll") for (int m = 0; m < 4; ++m) _Pragma("unroll") for (int n = 0; n < 2; ++n) _Pragma("unroll") for (int k = 0; k < 2; ++k) \
;         acc[ai][bj][m][n] = __builtin_amdgcn_mfma_f32_16x16x32_bf16(Bt[n][k], At[m][k], acc[ai][bj][m][n], 0, 0, 0); __builtin_amdgcn_s_setprio(0); } while (0)
; #define PG8_WAIT_L(n) asm volatile("s_waitcnt lgkmcnt(" #n ")" ::: "memory")
; template <int MODE, class EpiT, class Sched>
; __device__ __forceinline__ void gemm_phase(LAS unsigned char* lds, const Gemm g, const Sched& S, const EpiT& E) {
;     ...
;         const bool has_next = S.next(ui + 1, nxt);
;         const char* nA = has_next ? (const char*)g.A + (size_t)nxt.pm * tstep : cA; const char* nB = has_next ? (const char*)g.Bt + (size_t)nxt.pn * tstep : cB;
;         for (int t = 0; t < nt; t += 2) {
;             const bool last = (t == nt - 2);
;             const char* a1 = cA + (size_t)(t + 1) * kstep;
;             const char* a2 = last ? nA : cA + (size_t)(t + 2) * kstep; const char* b2 = last ? nB : cB + (size_t)(t + 2) * kstep;
;             const char* a3 = a2 + kstep; const char* b3 = b2 + kstep;
;             PG8_LDB(B0, 0, 0); PG8_SCHED; PG8_LDA(At, 0, 0); PG8_STAGE(PG8_SA(1, 1), a1 + hstep, voffA);
;             PG8_WAIT_L(8); PG8_BAR; PG8_WAIT_L(0); PG8_MMA(0, 0, At, B0); PG8_BAR; PG8_SCHED;
;             PG8_LDB(B1, 0, 1); PG8_STAGE(PG8_SB(0, 0), b2, voffB);
;             PG8_BAR; PG8_WAIT_L(0); PG8_MMA(0, 1, At, B1); PG8_BAR;
;             PG8_LDA(At, 0, 1); PG8_STAGE(PG8_SA(0, 0), a2, voffA);
;             PG8_BAR; PG8_WAIT_L(0); PG8_MMA(1, 0, At, B0); PG8_BAR; PG8_SCHED;
.LBB0_280:
	s_add_i32 s68, s46, 2
	s_add_u32 s52, s10, s44
	s_addc_u32 s47, s11, s45
	s_add_u32 s58, s4, s44
	s_addc_u32 s53, s5, s45
	s_add_i32 s59, 0, 0x10000
	v_add_u32_e32 v152, s59, v157
	ds_read_b128 v[134:137], v152
	ds_read_b128 v[138:141], v152 offset:1024
	ds_read_b128 v[142:145], v152 offset:2048
	ds_read_b128 v[152:155], v152 offset:3072
	s_cmp_eq_u32 s60, s46
	s_cselect_b32 s46, s34, s52
	s_cselect_b32 s47, s35, s47
	s_cselect_b32 s53, s39, s53
	s_cselect_b32 s52, s38, s58
	v_lshl_add_u64 v[198:199], s[10:11], 0, v[132:133]
	s_add_i32 m0, s30, 0xc000
	ds_read_b128 v[162:165], v160
	ds_read_b128 v[166:169], v160 offset:1024
	ds_read_b128 v[170:173], v160 offset:2048
	ds_read_b128 v[174:177], v160 offset:3072
	ds_read_b128 v[182:185], v160 offset:4096
	ds_read_b128 v[186:189], v160 offset:5120
	ds_read_b128 v[190:193], v160 offset:6144
	ds_read_b128 v[194:197], v160 offset:7168
	global_load_lds_dwordx4 v[198:199], off
	v_lshl_add_u64 v[198:199], s[10:11], 0, v[130:131]
	s_add_i32 m0, s30, 0xe000
	s_nop 0
	global_load_lds_dwordx4 v[198:199], off
	s_waitcnt lgkmcnt(0)
	s_barrier
	v_mfma_f32_16x16x32_bf16 v[126:129], v[134:137], v[162:165], v[126:129]
	v_mfma_f32_16x16x32_bf16 v[122:125], v[142:145], v[162:165], v[122:125]
	v_mfma_f32_16x16x32_bf16 v[118:121], v[134:137], v[170:173], v[118:121]
	v_mfma_f32_16x16x32_bf16 v[114:117], v[142:145], v[170:173], v[114:117]
	v_mfma_f32_16x16x32_bf16 v[110:113], v[134:137], v[182:185], v[110:113]
	v_mfma_f32_16x16x32_bf16 v[106:109], v[142:145], v[182:185], v[106:109]
	v_mfma_f32_16x16x32_bf16 v[102:105], v[134:137], v[190:193], v[102:105]
	v_mfma_f32_16x16x32_bf16 v[98:101], v[142:145], v[190:193], v[98:101]
	v_mfma_f32_16x16x32_bf16 v[126:129], v[138:141], v[166:169], v[126:129]
	v_mfma_f32_16x16x32_bf16 v[122:125], v[152:155], v[166:169], v[122:125]
	v_mfma_f32_16x16x32_bf16 v[118:121], v[138:141], v[174:177], v[118:121]
	v_mfma_f32_16x16x32_bf16 v[114:117], v[152:155], v[174:177], v[114:117]
	v_mfma_f32_16x16x32_bf16 v[110:113], v[138:141], v[186:189], v[110:113]
	v_mfma_f32_16x16x32_bf16 v[106:109], v[152:155], v[186:189], v[106:109]
	v_mfma_f32_16x16x32_bf16 v[102:105], v[138:141], v[194:197], v[102:105]
	v_mfma_f32_16x16x32_bf16 v[98:101], v[152:155], v[194:197], v[98:101]
	s_barrier
	s_add_i32 s58, 0, 0x14000
	s_add_i32 s59, s59, s24
	v_add_u32_e32 v161, s58, v157
	v_lshl_add_u64 v[198:199], s[52:53], 0, v[0:1]
	s_mov_b32 m0, s59
	ds_read_b128 v[220:223], v161
	ds_read_b128 v[224:227], v161 offset:1024
	ds_read_b128 v[228:231], v161 offset:2048
	ds_read_b128 v[232:235], v161 offset:3072
	global_load_lds_dwordx4 v[198:199], off
	v_lshl_add_u64 v[236:237], s[52:53], 0, v[146:147]
	s_add_i32 m0, s59, 0x2000
	s_nop 0
	global_load_lds_dwordx4 v[236:237], off
	s_waitcnt lgkmcnt(0)
	s_barrier
	v_mfma_f32_16x16x32_bf16 v[94:97], v[220:223], v[162:165], v[94:97]
	v_mfma_f32_16x16x32_bf16 v[90:93], v[228:231], v[162:165], v[90:93]
	v_mfma_f32_16x16x32_bf16 v[86:89], v[220:223], v[170:173], v[86:89]
	v_mfma_f32_16x16x32_bf16 v[82:85], v[228:231], v[170:173], v[82:85]
	v_mfma_f32_16x16x32_bf16 v[78:81], v[220:223], v[182:185], v[78:81]
	v_mfma_f32_16x16x32_bf16 v[74:77], v[228:231], v[182:185], v[74:77]
	v_mfma_f32_16x16x32_bf16 v[70:73], v[220:223], v[190:193], v[70:73]
	v_mfma_f32_16x16x32_bf16 v[66:69], v[228:231], v[190:193], v[66:69]
	v_mfma_f32_16x16x32_bf16 v[94:97], v[224:227], v[166:169], v[94:97]
	v_mfma_f32_16x16x32_bf16 v[90:93], v[232:235], v[166:169], v[90:93]
	v_mfma_f32_16x16x32_bf16 v[86:89], v[224:227], v[174:177], v[86:89]
	v_mfma_f32_16x16x32_bf16 v[82:85], v[232:235], v[174:177], v[82:85]
	v_mfma_f32_16x16x32_bf16 v[78:81], v[224:227], v[186:189], v[78:81]
	v_mfma_f32_16x16x32_bf16 v[74:77], v[232:235], v[186:189], v[74:77]
	v_mfma_f32_16x16x32_bf16 v[70:73], v[224:227], v[194:197], v[70:73]
	v_mfma_f32_16x16x32_bf16 v[66:69], v[232:235], v[194:197], v[66:69]
	s_barrier
	s_mov_b32 m0, s30
	v_lshl_add_u64 v[238:239], s[46:47], 0, v[0:1]
	ds_read_b128 v[162:165], v160 offset:16384
	ds_read_b128 v[166:169], v160 offset:17408
	ds_read_b128 v[170:173], v160 offset:18432
	ds_read_b128 v[174:177], v160 offset:19456
	ds_read_b128 v[182:185], v160 offset:20480
	ds_read_b128 v[186:189], v160 offset:21504
	ds_read_b128 v[190:193], v160 offset:22528
	ds_read_b128 v[194:197], v160 offset:23552
	global_load_lds_dwordx4 v[238:239], off
	v_lshl_add_u64 v[240:241], s[46:47], 0, v[146:147]
	s_mov_b32 m0, s50
	s_nop 0
	global_load_lds_dwordx4 v[240:241], off
	s_waitcnt lgkmcnt(0)
	s_barrier
	v_mfma_f32_16x16x32_bf16 v[62:65], v[134:137], v[162:165], v[62:65]
	v_mfma_f32_16x16x32_bf16 v[58:61], v[142:145], v[162:165], v[58:61]
	v_mfma_f32_16x16x32_bf16 v[54:57], v[134:137], v[170:173], v[54:57]
	v_mfma_f32_16x16x32_bf16 v[50:53], v[142:145], v[170:173], v[50:53]
	v_mfma_f32_16x16x32_bf16 v[46:49], v[134:137], v[182:185], v[46:49]
	v_mfma_f32_16x16x32_bf16 v[42:45], v[142:145], v[182:185], v[42:45]
	v_mfma_f32_16x16x32_bf16 v[38:41], v[134:137], v[190:193], v[38:41]
	v_mfma_f32_16x16x32_bf16 v[34:37], v[142:145], v[190:193], v[34:37]
	v_mfma_f32_16x16x32_bf16 v[62:65], v[138:141], v[166:169], v[62:65]
	v_mfma_f32_16x16x32_bf16 v[58:61], v[152:155], v[166:169], v[58:61]
	v_mfma_f32_16x16x32_bf16 v[54:57], v[138:141], v[174:177], v[54:57]
	v_mfma_f32_16x16x32_bf16 v[50:53], v[152:155], v[174:177], v[50:53]
	v_mfma_f32_16x16x32_bf16 v[46:49], v[138:141], v[186:189], v[46:49]
	v_mfma_f32_16x16x32_bf16 v[42:45], v[152:155], v[186:189], v[42:45]
	v_mfma_f32_16x16x32_bf16 v[38:41], v[138:141], v[194:197], v[38:41]
	v_mfma_f32_16x16x32_bf16 v[34:37], v[152:155], v[194:197], v[34:37]
	s_barrier
; #define PG8_STAGE(bufoff, gbase, voff) do { _Pragma("unroll") for (int _i = 0; _i < 2; ++_i) \
;         __builtin_amdgcn_global_load_lds((const unsigned*)((const char*)(gbase) + (voff)[_i]), (LAS unsigned*)(lds + (bufoff) + ldsw + _i * 8192), 16, 0, 0); } while (0)
; #define PG8_LDA(dst, b, h) do { _Pragma("unroll") for (int m = 0; m < 4; ++m) _Pragma("unroll") for (int k = 0; k < 2; ++k) dst[m][k] = *(const LAS bf16x8*)(lds + PG8_SA(b, h) + aoff + m * 2048 + k * 1024); } while (0)
; #define PG8_LDB(dst, b, h) do { _Pragma("unroll") for (int n = 0; n < 2; ++n) _Pragma("unroll") for (int k = 0; k < 2; ++k) dst[n][k] = *(const LAS bf16x8*)(lds + PG8_SB(b, h) + boff + n * 2048 + k * 1024); } while (0)
; #define PG8_MMA(ai, bj, At, Bt) do { __builtin_amdgcn_s_setprio(1); _Pragma("unroll") for (int m = 0; m < 4; ++m) _Pragma("unroll") for (int n = 0; n < 2; ++n) _Pragma("unroll") for (int k = 0; k < 2; ++k) \
;         acc[ai][bj][m][n] = __builtin_amdgcn_mfma_f32_16x16x32_bf16(Bt[n][k], At[m][k], acc[ai][bj][m][n], 0, 0, 0); __builtin_amdgcn_s_setprio(0); } while (0)
; #define PG8_WAIT_V(n) asm volatile("s_waitcnt vmcnt(" #n ")" ::: "memory")
; #define PG8_WAIT_L(n) asm volatile("s_waitcnt lgkmcnt(" #n ")" ::: "memory")
; #define PG8_BAR __builtin_amdgcn_s_barrier()
; #define PG8_SCHED __builtin_amdgcn_sched_barrier(0)
; template <int MODE, class EpiT, class Sched>
; __device__ __forceinline__ void gemm_phase(LAS unsigned char* lds, const Gemm g, const Sched& S, const EpiT& E) {
;     ...
;             PG8_STAGE(PG8_SB(0, 1), b2 + hstep, voffB);
;             PG8_WAIT_V(6); PG8_BAR; PG8_MMA(1, 1, At, B1); PG8_BAR;
;             PG8_LDB(B0, 1, 0); PG8_SCHED; PG8_LDA(At, 1, 0); PG8_STAGE(PG8_SA(0, 1), a2 + hstep, voffA);
;             PG8_WAIT_L(8); PG8_BAR; PG8_WAIT_L(0); PG8_MMA(0, 0, At, B0); PG8_BAR; PG8_SCHED;
;             PG8_LDB(B1, 1, 1); PG8_STAGE(PG8_SB(1, 0), b3, voffB);
;             PG8_BAR; PG8_WAIT_L(0); PG8_MMA(0, 1, At, B1); PG8_BAR;
;             PG8_LDA(At, 1, 1); PG8_STAGE(PG8_SA(1, 0), a3, voffA);
	s_add_u32 s52, s52, s22
	s_addc_u32 s53, s53, 0
	s_add_i32 s58, s58, s24
	v_lshl_add_u64 v[242:243], s[52:53], 0, v[0:1]
	s_mov_b32 m0, s58
	v_lshl_add_u64 v[244:245], s[52:53], 0, v[146:147]
	global_load_lds_dwordx4 v[242:243], off
	s_add_i32 m0, s58, 0x2000
	s_nop 0
	global_load_lds_dwordx4 v[244:245], off
	s_waitcnt vmcnt(6)
	s_barrier
	v_mfma_f32_16x16x32_bf16 v[30:33], v[220:223], v[162:165], v[30:33]
	v_mfma_f32_16x16x32_bf16 v[26:29], v[228:231], v[162:165], v[26:29]
	v_mfma_f32_16x16x32_bf16 v[22:25], v[220:223], v[170:173], v[22:25]
	v_mfma_f32_16x16x32_bf16 v[18:21], v[228:231], v[170:173], v[18:21]
	v_mfma_f32_16x16x32_bf16 v[14:17], v[220:223], v[182:185], v[14:17]
	v_mfma_f32_16x16x32_bf16 v[10:13], v[228:231], v[182:185], v[10:13]
	v_mfma_f32_16x16x32_bf16 v[6:9], v[220:223], v[190:193], v[6:9]
	v_mfma_f32_16x16x32_bf16 v[2:5], v[228:231], v[190:193], v[2:5]
	v_mfma_f32_16x16x32_bf16 v[30:33], v[224:227], v[166:169], v[30:33]
	v_mfma_f32_16x16x32_bf16 v[26:29], v[232:235], v[166:169], v[26:29]
	v_mfma_f32_16x16x32_bf16 v[22:25], v[224:227], v[174:177], v[22:25]
	v_mfma_f32_16x16x32_bf16 v[18:21], v[232:235], v[174:177], v[18:21]
	v_mfma_f32_16x16x32_bf16 v[14:17], v[224:227], v[186:189], v[14:17]
	v_mfma_f32_16x16x32_bf16 v[10:13], v[232:235], v[186:189], v[10:13]
	v_mfma_f32_16x16x32_bf16 v[6:9], v[224:227], v[194:197], v[6:9]
	v_mfma_f32_16x16x32_bf16 v[2:5], v[232:235], v[194:197], v[2:5]
	s_barrier
	s_add_i32 s52, 0, 0x18000
	v_add_u32_e32 v152, s52, v157
	ds_read_b128 v[134:137], v152
	ds_read_b128 v[138:141], v152 offset:1024
	ds_read_b128 v[142:145], v152 offset:2048
	ds_read_b128 v[152:155], v152 offset:3072
	s_add_u32 s46, s46, s22
	s_addc_u32 s47, s47, 0
	s_mov_b32 m0, s51
	v_lshl_add_u64 v[220:221], s[46:47], 0, v[0:1]
	ds_read_b128 v[162:165], v160 offset:32768
	ds_read_b128 v[166:169], v160 offset:33792
	ds_read_b128 v[170:173], v160 offset:34816
	ds_read_b128 v[174:177], v160 offset:35840
	ds_read_b128 v[182:185], v160 offset:36864
	ds_read_b128 v[186:189], v160 offset:37888
	ds_read_b128 v[190:193], v160 offset:38912
	ds_read_b128 v[194:197], v160 offset:39936
	global_load_lds_dwordx4 v[220:221], off
	v_lshl_add_u64 v[220:221], s[46:47], 0, v[146:147]
	s_mov_b32 m0, s54
	s_nop 0
	global_load_lds_dwordx4 v[220:221], off
	s_waitcnt lgkmcnt(0)
	s_barrier
	v_mfma_f32_16x16x32_bf16 v[126:129], v[134:137], v[162:165], v[126:129]
	v_mfma_f32_16x16x32_bf16 v[122:125], v[142:145], v[162:165], v[122:125]
	v_mfma_f32_16x16x32_bf16 v[118:121], v[134:137], v[170:173], v[118:121]
	v_mfma_f32_16x16x32_bf16 v[114:117], v[142:145], v[170:173], v[114:117]
	v_mfma_f32_16x16x32_bf16 v[110:113], v[134:137], v[182:185], v[110:113]
	v_mfma_f32_16x16x32_bf16 v[106:109], v[142:145], v[182:185], v[106:109]
	v_mfma_f32_16x16x32_bf16 v[102:105], v[134:137], v[190:193], v[102:105]
	v_mfma_f32_16x16x32_bf16 v[98:101], v[142:145], v[190:193], v[98:101]
	v_mfma_f32_16x16x32_bf16 v[126:129], v[138:141], v[166:169], v[126:129]
	v_mfma_f32_16x16x32_bf16 v[122:125], v[152:155], v[166:169], v[122:125]
	v_mfma_f32_16x16x32_bf16 v[118:121], v[138:141], v[174:177], v[118:121]
	v_mfma_f32_16x16x32_bf16 v[114:117], v[152:155], v[174:177], v[114:117]
	v_mfma_f32_16x16x32_bf16 v[110:113], v[138:141], v[186:189], v[110:113]
	v_mfma_f32_16x16x32_bf16 v[106:109], v[152:155], v[186:189], v[106:109]
	v_mfma_f32_16x16x32_bf16 v[102:105], v[138:141], v[194:197], v[102:105]
	v_mfma_f32_16x16x32_bf16 v[98:101], v[152:155], v[194:197], v[98:101]
	s_barrier
	s_add_i32 s46, 0, 0x1c000
	s_add_i32 s47, s52, s24
	v_add_u32_e32 v161, s46, v157
	v_lshl_add_u64 v[198:199], v[198:199], 0, s[76:77]
	s_mov_b32 m0, s47
	ds_read_b128 v[220:223], v161
	ds_read_b128 v[224:227], v161 offset:1024
	ds_read_b128 v[228:231], v161 offset:2048
	ds_read_b128 v[232:235], v161 offset:3072
	global_load_lds_dwordx4 v[198:199], off
	v_lshl_add_u64 v[198:199], v[236:237], 0, s[76:77]
	s_add_i32 m0, s47, 0x2000
	s_nop 0
	global_load_lds_dwordx4 v[198:199], off
	s_waitcnt lgkmcnt(0)
	s_barrier
; #define PG8_STAGE(bufoff, gbase, voff) do { _Pragma("unroll") for (int _i = 0; _i < 2; ++_i) \
;         __builtin_amdgcn_global_load_lds((const unsigned*)((const char*)(gbase) + (voff)[_i]), (LAS unsigned*)(lds + (bufoff) + ldsw + _i * 8192), 16, 0, 0); } while (0)
; #define PG8_MMA(ai, bj, At, Bt) do { __builtin_amdgcn_s_setprio(1); _Pragma("unroll") for (int m = 0; m < 4; ++m) _Pragma("unroll") for (int n = 0; n < 2; ++n) _Pragma("unroll") for (int k = 0; k < 2; ++k) \
;         acc[ai][bj][m][n] = __builtin_amdgcn_mfma_f32_16x16x32_bf16(Bt[n][k], At[m][k], acc[ai][bj][m][n], 0, 0, 0); __builtin_amdgcn_s_setprio(0); } while (0)
; #define PG8_WAIT_V(n) asm volatile("s_waitcnt vmcnt(" #n ")" ::: "memory")
; #define PG8_WAIT_L(n) asm volatile("s_waitcnt lgkmcnt(" #n ")" ::: "memory")
; #define PG8_BAR __builtin_amdgcn_s_barrier()
; #define PG8_SCHED __builtin_amdgcn_sched_barrier(0)
;     template <int mode> __device__ __forceinline__ void run(const f32x4 (&acc)[2][2][4][2], const Unit& u, int wr, int wc, int fr, int fq, const LAS float* sc) const {
;     ...
;             const int col0 = u.pn * BM + wc * 32 + 8 * fq;
;             f32x4 bv[2][2];
; #pragma unroll
;             for (int bj = 0; bj < 2; ++bj)
; #pragma unroll
;                 for (int n = 0; n < 2; ++n) bv[bj][n] = bias ? *(const f32x4*)(bias + col0 + bj * HALF + 4 * n) : (f32x4){0.f, 0.f, 0.f, 0.f};
; template <int MODE, class EpiT, class Sched>
; __device__ __forceinline__ void gemm_phase(LAS unsigned char* lds, const Gemm g, const Sched& S, const EpiT& E) {
;     ...
;             PG8_BAR; PG8_WAIT_L(0); PG8_MMA(1, 0, At, B0); PG8_BAR; PG8_SCHED;
;             PG8_STAGE(PG8_SB(1, 1), b3 + hstep, voffB);
;             PG8_WAIT_V(6); PG8_BAR; PG8_MMA(1, 1, At, B1); PG8_BAR;
;         }
	v_mfma_f32_16x16x32_bf16 v[94:97], v[220:223], v[162:165], v[94:97]
	v_mfma_f32_16x16x32_bf16 v[90:93], v[228:231], v[162:165], v[90:93]
	v_mfma_f32_16x16x32_bf16 v[86:89], v[220:223], v[170:173], v[86:89]
	v_mfma_f32_16x16x32_bf16 v[82:85], v[228:231], v[170:173], v[82:85]
	v_mfma_f32_16x16x32_bf16 v[78:81], v[220:223], v[182:185], v[78:81]
	v_mfma_f32_16x16x32_bf16 v[74:77], v[228:231], v[182:185], v[74:77]
	v_mfma_f32_16x16x32_bf16 v[70:73], v[220:223], v[190:193], v[70:73]
	v_mfma_f32_16x16x32_bf16 v[66:69], v[228:231], v[190:193], v[66:69]
	v_mfma_f32_16x16x32_bf16 v[94:97], v[224:227], v[166:169], v[94:97]
	v_mfma_f32_16x16x32_bf16 v[90:93], v[232:235], v[166:169], v[90:93]
	v_mfma_f32_16x16x32_bf16 v[86:89], v[224:227], v[174:177], v[86:89]
	v_mfma_f32_16x16x32_bf16 v[82:85], v[232:235], v[174:177], v[82:85]
	v_mfma_f32_16x16x32_bf16 v[78:81], v[224:227], v[186:189], v[78:81]
	v_mfma_f32_16x16x32_bf16 v[74:77], v[232:235], v[186:189], v[74:77]
	v_mfma_f32_16x16x32_bf16 v[70:73], v[224:227], v[194:197], v[70:73]
	v_mfma_f32_16x16x32_bf16 v[66:69], v[232:235], v[194:197], v[66:69]
	s_barrier
	s_mov_b32 m0, s56
	v_lshl_add_u64 v[198:199], v[238:239], 0, s[76:77]
	ds_read_b128 v[162:165], v160 offset:49152
	ds_read_b128 v[166:169], v160 offset:50176
	ds_read_b128 v[170:173], v160 offset:51200
	ds_read_b128 v[174:177], v160 offset:52224
	ds_read_b128 v[182:185], v160 offset:53248
	ds_read_b128 v[186:189], v160 offset:54272
	ds_read_b128 v[190:193], v160 offset:55296
	ds_read_b128 v[194:197], v160 offset:56320
	global_load_lds_dwordx4 v[198:199], off
	v_lshl_add_u64 v[198:199], v[240:241], 0, s[76:77]
	s_mov_b32 m0, s57
	s_nop 0
	global_load_lds_dwordx4 v[198:199], off
	s_waitcnt lgkmcnt(0)
	s_barrier
	v_mfma_f32_16x16x32_bf16 v[62:65], v[134:137], v[162:165], v[62:65]
	v_mfma_f32_16x16x32_bf16 v[58:61], v[142:145], v[162:165], v[58:61]
	v_mfma_f32_16x16x32_bf16 v[54:57], v[134:137], v[170:173], v[54:57]
	v_mfma_f32_16x16x32_bf16 v[50:53], v[142:145], v[170:173], v[50:53]
	v_mfma_f32_16x16x32_bf16 v[46:49], v[134:137], v[182:185], v[46:49]
	v_mfma_f32_16x16x32_bf16 v[42:45], v[142:145], v[182:185], v[42:45]
	v_mfma_f32_16x16x32_bf16 v[38:41], v[134:137], v[190:193], v[38:41]
	v_mfma_f32_16x16x32_bf16 v[34:37], v[142:145], v[190:193], v[34:37]
	v_mfma_f32_16x16x32_bf16 v[62:65], v[138:141], v[166:169], v[62:65]
	v_mfma_f32_16x16x32_bf16 v[58:61], v[152:155], v[166:169], v[58:61]
	v_mfma_f32_16x16x32_bf16 v[54:57], v[138:141], v[174:177], v[54:57]
	v_mfma_f32_16x16x32_bf16 v[50:53], v[152:155], v[174:177], v[50:53]
	v_mfma_f32_16x16x32_bf16 v[46:49], v[138:141], v[186:189], v[46:49]
	v_mfma_f32_16x16x32_bf16 v[42:45], v[152:155], v[186:189], v[42:45]
	v_mfma_f32_16x16x32_bf16 v[38:41], v[138:141], v[194:197], v[38:41]
	v_mfma_f32_16x16x32_bf16 v[34:37], v[152:155], v[194:197], v[34:37]
	s_barrier
	s_add_i32 s46, s46, s24
	v_lshl_add_u64 v[134:135], v[242:243], 0, s[76:77]
	s_mov_b32 m0, s46
	s_nop 0
	global_load_lds_dwordx4 v[134:135], off
	v_lshl_add_u64 v[134:135], v[244:245], 0, s[76:77]
	s_add_i32 m0, s46, 0x2000
	s_nop 0
	global_load_lds_dwordx4 v[134:135], off
	s_waitcnt vmcnt(6)
	s_barrier
	v_mfma_f32_16x16x32_bf16 v[30:33], v[220:223], v[162:165], v[30:33]
	v_mfma_f32_16x16x32_bf16 v[26:29], v[228:231], v[162:165], v[26:29]
	v_mfma_f32_16x16x32_bf16 v[22:25], v[220:223], v[170:173], v[22:25]
	v_mfma_f32_16x16x32_bf16 v[18:21], v[228:231], v[170:173], v[18:21]
	v_mfma_f32_16x16x32_bf16 v[14:17], v[220:223], v[182:185], v[14:17]
	v_mfma_f32_16x16x32_bf16 v[10:13], v[228:231], v[182:185], v[10:13]
	v_mfma_f32_16x16x32_bf16 v[6:9], v[220:223], v[190:193], v[6:9]
	v_mfma_f32_16x16x32_bf16 v[2:5], v[228:231], v[190:193], v[2:5]
	v_mfma_f32_16x16x32_bf16 v[30:33], v[224:227], v[166:169], v[30:33]
	v_mfma_f32_16x16x32_bf16 v[26:29], v[232:235], v[166:169], v[26:29]
	v_mfma_f32_16x16x32_bf16 v[22:25], v[224:227], v[174:177], v[22:25]
	v_mfma_f32_16x16x32_bf16 v[18:21], v[232:235], v[174:177], v[18:21]
	v_mfma_f32_16x16x32_bf16 v[14:17], v[224:227], v[186:189], v[14:17]
	v_mfma_f32_16x16x32_bf16 v[10:13], v[232:235], v[186:189], v[10:13]
	v_mfma_f32_16x16x32_bf16 v[6:9], v[224:227], v[194:197], v[6:9]
	v_mfma_f32_16x16x32_bf16 v[2:5], v[232:235], v[194:197], v[2:5]
	s_barrier
	s_add_u32 s44, s44, 0x100
	s_addc_u32 s45, s45, 0
	v_lshl_add_u64 v[132:133], v[132:133], 0, s[80:81]
	v_lshl_add_u64 v[130:131], v[130:131], 0, s[80:81]
	s_cmp_ge_u32 s68, s55
	s_mov_b32 s46, s68
	s_cbranch_scc0 .LBB0_280
	v_lshl_or_b32 v152, s3, 8, v159
	v_ashrrev_i32_e32 v153, 31, v152
	v_cndmask_b32_e64 v131, 0, 1, s[28:29]
	v_lshl_add_u64 v[154:155], v[152:153], 2, s[12:13]
	v_mov_b32_e32 v130, 0
	v_cmp_ne_u32_e64 s[44:45], 1, v131
	s_andn2_b64 vcc, exec, s[28:29]
	v_mov_b32_e32 v134, 0
	v_mov_b32_e32 v135, 0
	v_mov_b32_e32 v136, 0
	v_mov_b32_e32 v137, 0
	s_cbranch_vccnz .LBB0_283
	global_load_dwordx4 v[134:137], v[154:155], off

; #define PG8_STAGE(bufoff, gbase, voff) do { _Pragma("unroll") for (int _i = 0; _i < 2; ++_i) \
;         __builtin_amdgcn_global_load_lds((const unsigned*)((const char*)(gbase) + (voff)[_i]), (LAS unsigned*)(lds + (bufoff) + ldsw + _i * 8192), 16, 0, 0); } while (0)
; #define PG8_LDA(dst, b, h) do { _Pragma("unroll") for (int m = 0; m < 4; ++m) _Pragma("unroll") for (int k = 0; k < 2; ++k) dst[m][k] = *(const LAS bf16x8*)(lds + PG8_SA(b, h) + aoff + m * 2048 + k * 1024); } while (0)
; #define PG8_LDB(dst, b, h) do { _Pragma("unroll") for (int n = 0; n < 2; ++n) _Pragma("unroll") for (int k = 0; k < 2; ++k) dst[n][k] = *(const LAS bf16x8*)(lds + PG8_SB(b, h) + boff + n * 2048 + k * 1024); } while (0)
; #define PG8_MMA(ai, bj, At, Bt) do { __builtin_amdgcn_s_setprio(1); _Pragma("unroll") for (int m = 0; m < 4; ++m) _Pragma("unroll") for (int n = 0; n < 2; ++n) _Pragma("unroll") for (int k = 0; k < 2; ++k) \
;         acc[ai][bj][m][n] = __builtin_amdgcn_mfma_f32_16x16x32_bf16(Bt[n][k], At[m][k], acc[ai][bj][m][n], 0, 0, 0); __builtin_amdgcn_s_setprio(0); } while (0)
; #define PG8_WAIT_L(n) asm volatile("s_waitcnt lgkmcnt(" #n ")" ::: "memory")
; template <int MODE, class EpiT, class Sched>
; __device__ __forceinline__ void gemm_phase(LAS unsigned char* lds, const Gemm g, const Sched& S, const EpiT& E) {
;     ...
;         const bool has_next = S.next(ui + 1, nxt);
;         const char* nA = has_next ? (const char*)g.A + (size_t)nxt.pm * tstep : cA; const char* nB = has_next ? (const char*)g.Bt + (size_t)nxt.pn * tstep : cB;
;         for (int t = 0; t < nt; t += 2) {
;             const bool last = (t == nt - 2);
;             const char* a1 = cA + (size_t)(t + 1) * kstep;
;             const char* a2 = last ? nA : cA + (size_t)(t + 2) * kstep; const char* b2 = last ? nB : cB + (size_t)(t + 2) * kstep;
;             const char* a3 = a2 + kstep; const char* b3 = b2 + kstep;
;             PG8_LDB(B0, 0, 0); PG8_SCHED; PG8_LDA(At, 0, 0); PG8_STAGE(PG8_SA(1, 1), a1 + hstep, voffA);
;             PG8_WAIT_L(8); PG8_BAR; PG8_WAIT_L(0); PG8_MMA(0, 0, At, B0); PG8_BAR; PG8_SCHED;
;             PG8_LDB(B1, 0, 1); PG8_STAGE(PG8_SB(0, 0), b2, voffB);
;             PG8_BAR; PG8_WAIT_L(0); PG8_MMA(0, 1, At, B1); PG8_BAR;
;             PG8_LDA(At, 0, 1); PG8_STAGE(PG8_SA(0, 0), a2, voffA);
;             PG8_BAR; PG8_WAIT_L(0); PG8_MMA(1, 0, At, B0); PG8_BAR; PG8_SCHED;
.LBB0_332:
	s_add_i32 s23, s22, 2
	s_add_u32 s30, s12, s4
	s_addc_u32 s38, s13, s5
	s_add_u32 s44, s10, s4
	s_addc_u32 s45, s11, s5
	s_add_i32 s58, 0, 0x10000
	v_add_u32_e32 v145, s58, v141
	ds_read_b128 v[146:149], v145
	ds_read_b128 v[150:153], v145 offset:1024
	ds_read_b128 v[154:157], v145 offset:2048
	ds_read_b128 v[158:161], v145 offset:3072
	s_cmp_eq_u32 s55, s22
	s_cselect_b32 s39, s29, s38
	s_cselect_b32 s38, s28, s30
	s_cselect_b32 s45, s35, s45
	s_cselect_b32 s44, s34, s44
	v_lshl_add_u64 v[198:199], s[12:13], 0, v[138:139]
	s_add_i32 m0, s47, 0xc000
	ds_read_b128 v[162:165], v144
	ds_read_b128 v[166:169], v144 offset:1024
	ds_read_b128 v[170:173], v144 offset:2048
	ds_read_b128 v[174:177], v144 offset:3072
	ds_read_b128 v[182:185], v144 offset:4096
	ds_read_b128 v[186:189], v144 offset:5120
	ds_read_b128 v[190:193], v144 offset:6144
	ds_read_b128 v[194:197], v144 offset:7168
	global_load_lds_dwordx4 v[198:199], off
	v_lshl_add_u64 v[198:199], s[12:13], 0, v[136:137]
	s_add_i32 m0, s47, 0xe000
	s_nop 0
	global_load_lds_dwordx4 v[198:199], off
	s_waitcnt lgkmcnt(0)
	s_barrier
	v_mfma_f32_16x16x32_bf16 v[126:129], v[146:149], v[162:165], v[126:129]
	v_mfma_f32_16x16x32_bf16 v[122:125], v[154:157], v[162:165], v[122:125]
	v_mfma_f32_16x16x32_bf16 v[118:121], v[146:149], v[170:173], v[118:121]
	v_mfma_f32_16x16x32_bf16 v[114:117], v[154:157], v[170:173], v[114:117]
	v_mfma_f32_16x16x32_bf16 v[110:113], v[146:149], v[182:185], v[110:113]
	v_mfma_f32_16x16x32_bf16 v[106:109], v[154:157], v[182:185], v[106:109]
	v_mfma_f32_16x16x32_bf16 v[102:105], v[146:149], v[190:193], v[102:105]
	v_mfma_f32_16x16x32_bf16 v[98:101], v[154:157], v[190:193], v[98:101]
	v_mfma_f32_16x16x32_bf16 v[126:129], v[150:153], v[166:169], v[126:129]
	v_mfma_f32_16x16x32_bf16 v[122:125], v[158:161], v[166:169], v[122:125]
	v_mfma_f32_16x16x32_bf16 v[118:121], v[150:153], v[174:177], v[118:121]
	v_mfma_f32_16x16x32_bf16 v[114:117], v[158:161], v[174:177], v[114:117]
	v_mfma_f32_16x16x32_bf16 v[110:113], v[150:153], v[186:189], v[110:113]
	v_mfma_f32_16x16x32_bf16 v[106:109], v[158:161], v[186:189], v[106:109]
	v_mfma_f32_16x16x32_bf16 v[102:105], v[150:153], v[194:197], v[102:105]
	v_mfma_f32_16x16x32_bf16 v[98:101], v[158:161], v[194:197], v[98:101]
	s_barrier
	s_add_i32 s22, 0, 0x14000
	s_add_i32 s30, s58, s46
	v_add_u32_e32 v145, s22, v141
	v_lshl_add_u64 v[198:199], s[44:45], 0, v[0:1]
	s_mov_b32 m0, s30
	ds_read_b128 v[220:223], v145
	ds_read_b128 v[224:227], v145 offset:1024
	ds_read_b128 v[228:231], v145 offset:2048
	ds_read_b128 v[232:235], v145 offset:3072
	global_load_lds_dwordx4 v[198:199], off
	v_lshl_add_u64 v[236:237], s[44:45], 0, v[130:131]
	s_add_i32 m0, s30, 0x2000
	s_nop 0
	global_load_lds_dwordx4 v[236:237], off
	s_waitcnt lgkmcnt(0)
	s_barrier
	v_mfma_f32_16x16x32_bf16 v[94:97], v[220:223], v[162:165], v[94:97]
	v_mfma_f32_16x16x32_bf16 v[90:93], v[228:231], v[162:165], v[90:93]
	v_mfma_f32_16x16x32_bf16 v[86:89], v[220:223], v[170:173], v[86:89]
	v_mfma_f32_16x16x32_bf16 v[82:85], v[228:231], v[170:173], v[82:85]
	v_mfma_f32_16x16x32_bf16 v[78:81], v[220:223], v[182:185], v[78:81]
	v_mfma_f32_16x16x32_bf16 v[74:77], v[228:231], v[182:185], v[74:77]
	v_mfma_f32_16x16x32_bf16 v[70:73], v[220:223], v[190:193], v[70:73]
	v_mfma_f32_16x16x32_bf16 v[66:69], v[228:231], v[190:193], v[66:69]
	v_mfma_f32_16x16x32_bf16 v[94:97], v[224:227], v[166:169], v[94:97]
	v_mfma_f32_16x16x32_bf16 v[90:93], v[232:235], v[166:169], v[90:93]
	v_mfma_f32_16x16x32_bf16 v[86:89], v[224:227], v[174:177], v[86:89]
	v_mfma_f32_16x16x32_bf16 v[82:85], v[232:235], v[174:177], v[82:85]
	v_mfma_f32_16x16x32_bf16 v[78:81], v[224:227], v[186:189], v[78:81]
	v_mfma_f32_16x16x32_bf16 v[74:77], v[232:235], v[186:189], v[74:77]
	v_mfma_f32_16x16x32_bf16 v[70:73], v[224:227], v[194:197], v[70:73]
	v_mfma_f32_16x16x32_bf16 v[66:69], v[232:235], v[194:197], v[66:69]
	s_barrier
	s_mov_b32 m0, s47
	v_lshl_add_u64 v[238:239], s[38:39], 0, v[0:1]
	ds_read_b128 v[162:165], v144 offset:16384
	ds_read_b128 v[166:169], v144 offset:17408
	ds_read_b128 v[170:173], v144 offset:18432
	ds_read_b128 v[174:177], v144 offset:19456
	ds_read_b128 v[182:185], v144 offset:20480
	ds_read_b128 v[186:189], v144 offset:21504
	ds_read_b128 v[190:193], v144 offset:22528
	ds_read_b128 v[194:197], v144 offset:23552
	global_load_lds_dwordx4 v[238:239], off
	v_lshl_add_u64 v[240:241], s[38:39], 0, v[130:131]
	s_mov_b32 m0, s50
	s_nop 0
	global_load_lds_dwordx4 v[240:241], off
	s_waitcnt lgkmcnt(0)
	s_barrier
	v_mfma_f32_16x16x32_bf16 v[62:65], v[146:149], v[162:165], v[62:65]
	v_mfma_f32_16x16x32_bf16 v[58:61], v[154:157], v[162:165], v[58:61]
	v_mfma_f32_16x16x32_bf16 v[54:57], v[146:149], v[170:173], v[54:57]
	v_mfma_f32_16x16x32_bf16 v[50:53], v[154:157], v[170:173], v[50:53]
	v_mfma_f32_16x16x32_bf16 v[46:49], v[146:149], v[182:185], v[46:49]
	v_mfma_f32_16x16x32_bf16 v[42:45], v[154:157], v[182:185], v[42:45]
	v_mfma_f32_16x16x32_bf16 v[38:41], v[146:149], v[190:193], v[38:41]
	v_mfma_f32_16x16x32_bf16 v[34:37], v[154:157], v[190:193], v[34:37]
	v_mfma_f32_16x16x32_bf16 v[62:65], v[150:153], v[166:169], v[62:65]
	v_mfma_f32_16x16x32_bf16 v[58:61], v[158:161], v[166:169], v[58:61]
	v_mfma_f32_16x16x32_bf16 v[54:57], v[150:153], v[174:177], v[54:57]
	v_mfma_f32_16x16x32_bf16 v[50:53], v[158:161], v[174:177], v[50:53]
	v_mfma_f32_16x16x32_bf16 v[46:49], v[150:153], v[186:189], v[46:49]
	v_mfma_f32_16x16x32_bf16 v[42:45], v[158:161], v[186:189], v[42:45]
	v_mfma_f32_16x16x32_bf16 v[38:41], v[150:153], v[194:197], v[38:41]
	v_mfma_f32_16x16x32_bf16 v[34:37], v[158:161], v[194:197], v[34:37]
	s_barrier
; #define PG8_STAGE(bufoff, gbase, voff) do { _Pragma("unroll") for (int _i = 0; _i < 2; ++_i) \
;         __builtin_amdgcn_global_load_lds((const unsigned*)((const char*)(gbase) + (voff)[_i]), (LAS unsigned*)(lds + (bufoff) + ldsw + _i * 8192), 16, 0, 0); } while (0)
; #define PG8_LDA(dst, b, h) do { _Pragma("unroll") for (int m = 0; m < 4; ++m) _Pragma("unroll") for (int k = 0; k < 2; ++k) dst[m][k] = *(const LAS bf16x8*)(lds + PG8_SA(b, h) + aoff + m * 2048 + k * 1024); } while (0)
; #define PG8_LDB(dst, b, h) do { _Pragma("unroll") for (int n = 0; n < 2; ++n) _Pragma("unroll") for (int k = 0; k < 2; ++k) dst[n][k] = *(const LAS bf16x8*)(lds + PG8_SB(b, h) + boff + n * 2048 + k * 1024); } while (0)
; #define PG8_MMA(ai, bj, At, Bt) do { __builtin_amdgcn_s_setprio(1); _Pragma("unroll") for (int m = 0; m < 4; ++m) _Pragma("unroll") for (int n = 0; n < 2; ++n) _Pragma("unroll") for (int k = 0; k < 2; ++k) \
;         acc[ai][bj][m][n] = __builtin_amdgcn_mfma_f32_16x16x32_bf16(Bt[n][k], At[m][k], acc[ai][bj][m][n], 0, 0, 0); __builtin_amdgcn_s_setprio(0); } while (0)
; #define PG8_WAIT_V(n) asm volatile("s_waitcnt vmcnt(" #n ")" ::: "memory")
; #define PG8_WAIT_L(n) asm volatile("s_waitcnt lgkmcnt(" #n ")" ::: "memory")
; #define PG8_BAR __builtin_amdgcn_s_barrier()
; #define PG8_SCHED __builtin_amdgcn_sched_barrier(0)
; template <int MODE, class EpiT, class Sched>
; __device__ __forceinline__ void gemm_phase(LAS unsigned char* lds, const Gemm g, const Sched& S, const EpiT& E) {
;     ...
;             PG8_STAGE(PG8_SB(0, 1), b2 + hstep, voffB);
;             PG8_WAIT_V(6); PG8_BAR; PG8_MMA(1, 1, At, B1); PG8_BAR;
;             PG8_LDB(B0, 1, 0); PG8_SCHED; PG8_LDA(At, 1, 0); PG8_STAGE(PG8_SA(0, 1), a2 + hstep, voffA);
;             PG8_WAIT_L(8); PG8_BAR; PG8_WAIT_L(0); PG8_MMA(0, 0, At, B0); PG8_BAR; PG8_SCHED;
;             PG8_LDB(B1, 1, 1); PG8_STAGE(PG8_SB(1, 0), b3, voffB);
;             PG8_BAR; PG8_WAIT_L(0); PG8_MMA(0, 1, At, B1); PG8_BAR;
;             PG8_LDA(At, 1, 1); PG8_STAGE(PG8_SA(1, 0), a3, voffA);
	s_add_u32 s44, s44, s21
	s_addc_u32 s45, s45, 0
	s_add_i32 s22, s22, s46
	v_lshl_add_u64 v[242:243], s[44:45], 0, v[0:1]
	s_mov_b32 m0, s22
	v_lshl_add_u64 v[244:245], s[44:45], 0, v[130:131]
	global_load_lds_dwordx4 v[242:243], off
	s_add_i32 m0, s22, 0x2000
	s_nop 0
	global_load_lds_dwordx4 v[244:245], off
	s_waitcnt vmcnt(6)
	s_barrier
	v_mfma_f32_16x16x32_bf16 v[30:33], v[220:223], v[162:165], v[30:33]
	v_mfma_f32_16x16x32_bf16 v[26:29], v[228:231], v[162:165], v[26:29]
	v_mfma_f32_16x16x32_bf16 v[22:25], v[220:223], v[170:173], v[22:25]
	v_mfma_f32_16x16x32_bf16 v[18:21], v[228:231], v[170:173], v[18:21]
	v_mfma_f32_16x16x32_bf16 v[14:17], v[220:223], v[182:185], v[14:17]
	v_mfma_f32_16x16x32_bf16 v[10:13], v[228:231], v[182:185], v[10:13]
	v_mfma_f32_16x16x32_bf16 v[6:9], v[220:223], v[190:193], v[6:9]
	v_mfma_f32_16x16x32_bf16 v[2:5], v[228:231], v[190:193], v[2:5]
	v_mfma_f32_16x16x32_bf16 v[30:33], v[224:227], v[166:169], v[30:33]
	v_mfma_f32_16x16x32_bf16 v[26:29], v[232:235], v[166:169], v[26:29]
	v_mfma_f32_16x16x32_bf16 v[22:25], v[224:227], v[174:177], v[22:25]
	v_mfma_f32_16x16x32_bf16 v[18:21], v[232:235], v[174:177], v[18:21]
	v_mfma_f32_16x16x32_bf16 v[14:17], v[224:227], v[186:189], v[14:17]
	v_mfma_f32_16x16x32_bf16 v[10:13], v[232:235], v[186:189], v[10:13]
	v_mfma_f32_16x16x32_bf16 v[6:9], v[224:227], v[194:197], v[6:9]
	v_mfma_f32_16x16x32_bf16 v[2:5], v[232:235], v[194:197], v[2:5]
	s_barrier
	s_add_i32 s22, 0, 0x18000
	v_add_u32_e32 v145, s22, v141
	ds_read_b128 v[146:149], v145
	ds_read_b128 v[150:153], v145 offset:1024
	ds_read_b128 v[154:157], v145 offset:2048
	ds_read_b128 v[158:161], v145 offset:3072
	s_add_u32 s38, s38, s21
	s_addc_u32 s39, s39, 0
	s_mov_b32 m0, s51
	v_lshl_add_u64 v[220:221], s[38:39], 0, v[0:1]
	ds_read_b128 v[162:165], v144 offset:32768
	ds_read_b128 v[166:169], v144 offset:33792
	ds_read_b128 v[170:173], v144 offset:34816
	ds_read_b128 v[174:177], v144 offset:35840
	ds_read_b128 v[182:185], v144 offset:36864
	ds_read_b128 v[186:189], v144 offset:37888
	ds_read_b128 v[190:193], v144 offset:38912
	ds_read_b128 v[194:197], v144 offset:39936
	global_load_lds_dwordx4 v[220:221], off
	v_lshl_add_u64 v[220:221], s[38:39], 0, v[130:131]
	s_mov_b32 m0, s52
	s_nop 0
	global_load_lds_dwordx4 v[220:221], off
	s_waitcnt lgkmcnt(0)
	s_barrier
	v_mfma_f32_16x16x32_bf16 v[126:129], v[146:149], v[162:165], v[126:129]
	v_mfma_f32_16x16x32_bf16 v[122:125], v[154:157], v[162:165], v[122:125]
	v_mfma_f32_16x16x32_bf16 v[118:121], v[146:149], v[170:173], v[118:121]
	v_mfma_f32_16x16x32_bf16 v[114:117], v[154:157], v[170:173], v[114:117]
	v_mfma_f32_16x16x32_bf16 v[110:113], v[146:149], v[182:185], v[110:113]
	v_mfma_f32_16x16x32_bf16 v[106:109], v[154:157], v[182:185], v[106:109]
	v_mfma_f32_16x16x32_bf16 v[102:105], v[146:149], v[190:193], v[102:105]
	v_mfma_f32_16x16x32_bf16 v[98:101], v[154:157], v[190:193], v[98:101]
	v_mfma_f32_16x16x32_bf16 v[126:129], v[150:153], v[166:169], v[126:129]
	v_mfma_f32_16x16x32_bf16 v[122:125], v[158:161], v[166:169], v[122:125]
	v_mfma_f32_16x16x32_bf16 v[118:121], v[150:153], v[174:177], v[118:121]
	v_mfma_f32_16x16x32_bf16 v[114:117], v[158:161], v[174:177], v[114:117]
	v_mfma_f32_16x16x32_bf16 v[110:113], v[150:153], v[186:189], v[110:113]
	v_mfma_f32_16x16x32_bf16 v[106:109], v[158:161], v[186:189], v[106:109]
	v_mfma_f32_16x16x32_bf16 v[102:105], v[150:153], v[194:197], v[102:105]
	v_mfma_f32_16x16x32_bf16 v[98:101], v[158:161], v[194:197], v[98:101]
	s_barrier
	s_add_i32 s30, 0, 0x1c000
	s_add_i32 s22, s22, s46
	v_add_u32_e32 v145, s30, v141
	v_lshl_add_u64 v[198:199], v[198:199], 0, s[76:77]
	s_mov_b32 m0, s22
	ds_read_b128 v[220:223], v145
	ds_read_b128 v[224:227], v145 offset:1024
	ds_read_b128 v[228:231], v145 offset:2048
	ds_read_b128 v[232:235], v145 offset:3072
	global_load_lds_dwordx4 v[198:199], off
	v_lshl_add_u64 v[198:199], v[236:237], 0, s[76:77]
	s_add_i32 m0, s22, 0x2000
	s_nop 0
	global_load_lds_dwordx4 v[198:199], off
	s_waitcnt lgkmcnt(0)
	s_barrier
	v_mfma_f32_16x16x32_bf16 v[94:97], v[220:223], v[162:165], v[94:97]
	v_mfma_f32_16x16x32_bf16 v[90:93], v[228:231], v[162:165], v[90:93]
	v_mfma_f32_16x16x32_bf16 v[86:89], v[220:223], v[170:173], v[86:89]
	v_mfma_f32_16x16x32_bf16 v[82:85], v[228:231], v[170:173], v[82:85]
	v_mfma_f32_16x16x32_bf16 v[78:81], v[220:223], v[182:185], v[78:81]
	v_mfma_f32_16x16x32_bf16 v[74:77], v[228:231], v[182:185], v[74:77]
	v_mfma_f32_16x16x32_bf16 v[70:73], v[220:223], v[190:193], v[70:73]
	v_mfma_f32_16x16x32_bf16 v[66:69], v[228:231], v[190:193], v[66:69]
	v_mfma_f32_16x16x32_bf16 v[94:97], v[224:227], v[166:169], v[94:97]
	v_mfma_f32_16x16x32_bf16 v[90:93], v[232:235], v[166:169], v[90:93]
	v_mfma_f32_16x16x32_bf16 v[86:89], v[224:227], v[174:177], v[86:89]
	v_mfma_f32_16x16x32_bf16 v[82:85], v[232:235], v[174:177], v[82:85]
	v_mfma_f32_16x16x32_bf16 v[78:81], v[224:227], v[186:189], v[78:81]
	v_mfma_f32_16x16x32_bf16 v[74:77], v[232:235], v[186:189], v[74:77]
	v_mfma_f32_16x16x32_bf16 v[70:73], v[224:227], v[194:197], v[70:73]
	v_mfma_f32_16x16x32_bf16 v[66:69], v[232:235], v[194:197], v[66:69]
	s_barrier
	s_mov_b32 m0, s53
	v_lshl_add_u64 v[198:199], v[238:239], 0, s[76:77]
	ds_read_b128 v[162:165], v144 offset:49152
	ds_read_b128 v[166:169], v144 offset:50176
	ds_read_b128 v[170:173], v144 offset:51200
	ds_read_b128 v[174:177], v144 offset:52224
	ds_read_b128 v[182:185], v144 offset:53248
	ds_read_b128 v[186:189], v144 offset:54272
	ds_read_b128 v[190:193], v144 offset:55296
	ds_read_b128 v[194:197], v144 offset:56320
	global_load_lds_dwordx4 v[198:199], off
	v_lshl_add_u64 v[198:199], v[240:241], 0, s[76:77]
	s_mov_b32 m0, s54
	s_nop 0
	global_load_lds_dwordx4 v[198:199], off
	s_waitcnt lgkmcnt(0)
	s_barrier
; __device__ __forceinline__ unsigned pk2(float lo, float hi) { unsigned r; asm volatile("v_cvt_pk_bf16_f32 %0, %1, %2" : "=v"(r) : "v"(lo), "v"(hi)); return r; }
; __device__ __forceinline__ float siluf_(float x) { return x * __builtin_amdgcn_rcpf(1.0f + __expf(-x)); }
; #define PG8_STAGE(bufoff, gbase, voff) do { _Pragma("unroll") for (int _i = 0; _i < 2; ++_i) \
;         __builtin_amdgcn_global_load_lds((const unsigned*)((const char*)(gbase) + (voff)[_i]), (LAS unsigned*)(lds + (bufoff) + ldsw + _i * 8192), 16, 0, 0); } while (0)
; #define PG8_MMA(ai, bj, At, Bt) do { __builtin_amdgcn_s_setprio(1); _Pragma("unroll") for (int m = 0; m < 4; ++m) _Pragma("unroll") for (int n = 0; n < 2; ++n) _Pragma("unroll") for (int k = 0; k < 2; ++k) \
;         acc[ai][bj][m][n] = __builtin_amdgcn_mfma_f32_16x16x32_bf16(Bt[n][k], At[m][k], acc[ai][bj][m][n], 0, 0, 0); __builtin_amdgcn_s_setprio(0); } while (0)
; #define PG8_BAR __builtin_amdgcn_s_barrier()
;     template <int mode> __device__ __forceinline__ void run(const f32x4 (&acc)[2][2][4][2], const Unit& u, int wr, int wc, int fr, int fq, const LAS float* sc) const {
;     ...
;         if (mode == 0) {
;             const int col0 = u.pn * HALF + wc * 32 + 8 * fq;
; #pragma unroll
;             for (int ai = 0; ai < 2; ++ai)
; #pragma unroll
;                 for (int m = 0; m < 4; ++m) {
;                     const int row = row0 + ai * HALF + m * 16;
;                     const float s = sc[ai * HALF + wr * 64 + m * 16 + fr];
;                     const f32x4 g0 = acc[ai][0][m][0] * s, u0 = acc[ai][1][m][0] * s, g1 = acc[ai][0][m][1] * s, u1 = acc[ai][1][m][1] * s;
;                     u32x4 w;
;                     w.x = pk2(siluf_(g0[0]) * u0[0], siluf_(g0[1]) * u0[1]); w.y = pk2(siluf_(g0[2]) * u0[2], siluf_(g0[3]) * u0[3]);
;                     w.z = pk2(siluf_(g1[0]) * u1[0], siluf_(g1[1]) * u1[1]); w.w = pk2(siluf_(g1[2]) * u1[2], siluf_(g1[3]) * u1[3]);
;                     *(u32x4*)(ob + (size_t)row * FF + col0) = w;
; template <int MODE, class EpiT, class Sched>
; __device__ __forceinline__ void gemm_phase(LAS unsigned char* lds, const Gemm g, const Sched& S, const EpiT& E) {
;     ...
;             PG8_BAR; PG8_WAIT_L(0); PG8_MMA(1, 0, At, B0); PG8_BAR; PG8_SCHED;
;             PG8_STAGE(PG8_SB(1, 1), b3 + hstep, voffB);
;             PG8_WAIT_V(6); PG8_BAR; PG8_MMA(1, 1, At, B1); PG8_BAR;
;         }
	v_mfma_f32_16x16x32_bf16 v[62:65], v[146:149], v[162:165], v[62:65]
	v_mfma_f32_16x16x32_bf16 v[58:61], v[154:157], v[162:165], v[58:61]
	v_mfma_f32_16x16x32_bf16 v[54:57], v[146:149], v[170:173], v[54:57]
	v_mfma_f32_16x16x32_bf16 v[50:53], v[154:157], v[170:173], v[50:53]
	v_mfma_f32_16x16x32_bf16 v[46:49], v[146:149], v[182:185], v[46:49]
	v_mfma_f32_16x16x32_bf16 v[42:45], v[154:157], v[182:185], v[42:45]
	v_mfma_f32_16x16x32_bf16 v[38:41], v[146:149], v[190:193], v[38:41]
	v_mfma_f32_16x16x32_bf16 v[34:37], v[154:157], v[190:193], v[34:37]
	v_mfma_f32_16x16x32_bf16 v[62:65], v[150:153], v[166:169], v[62:65]
	v_mfma_f32_16x16x32_bf16 v[58:61], v[158:161], v[166:169], v[58:61]
	v_mfma_f32_16x16x32_bf16 v[54:57], v[150:153], v[174:177], v[54:57]
	v_mfma_f32_16x16x32_bf16 v[50:53], v[158:161], v[174:177], v[50:53]
	v_mfma_f32_16x16x32_bf16 v[46:49], v[150:153], v[186:189], v[46:49]
	v_mfma_f32_16x16x32_bf16 v[42:45], v[158:161], v[186:189], v[42:45]
	v_mfma_f32_16x16x32_bf16 v[38:41], v[150:153], v[194:197], v[38:41]
	v_mfma_f32_16x16x32_bf16 v[34:37], v[158:161], v[194:197], v[34:37]
	s_barrier
	s_add_i32 s22, s30, s46
	v_lshl_add_u64 v[146:147], v[242:243], 0, s[76:77]
	s_mov_b32 m0, s22
	s_nop 0
	global_load_lds_dwordx4 v[146:147], off
	v_lshl_add_u64 v[146:147], v[244:245], 0, s[76:77]
	s_add_i32 m0, s22, 0x2000
	s_nop 0
	global_load_lds_dwordx4 v[146:147], off
	s_waitcnt vmcnt(6)
	s_barrier
	v_mfma_f32_16x16x32_bf16 v[30:33], v[220:223], v[162:165], v[30:33]
	v_mfma_f32_16x16x32_bf16 v[26:29], v[228:231], v[162:165], v[26:29]
	v_mfma_f32_16x16x32_bf16 v[22:25], v[220:223], v[170:173], v[22:25]
	v_mfma_f32_16x16x32_bf16 v[18:21], v[228:231], v[170:173], v[18:21]
	v_mfma_f32_16x16x32_bf16 v[14:17], v[220:223], v[182:185], v[14:17]
	v_mfma_f32_16x16x32_bf16 v[10:13], v[228:231], v[182:185], v[10:13]
	v_mfma_f32_16x16x32_bf16 v[6:9], v[220:223], v[190:193], v[6:9]
	v_mfma_f32_16x16x32_bf16 v[2:5], v[228:231], v[190:193], v[2:5]
	v_mfma_f32_16x16x32_bf16 v[30:33], v[224:227], v[166:169], v[30:33]
	v_mfma_f32_16x16x32_bf16 v[26:29], v[232:235], v[166:169], v[26:29]
	v_mfma_f32_16x16x32_bf16 v[22:25], v[224:227], v[174:177], v[22:25]
	v_mfma_f32_16x16x32_bf16 v[18:21], v[232:235], v[174:177], v[18:21]
	v_mfma_f32_16x16x32_bf16 v[14:17], v[224:227], v[186:189], v[14:17]
	v_mfma_f32_16x16x32_bf16 v[10:13], v[232:235], v[186:189], v[10:13]
	v_mfma_f32_16x16x32_bf16 v[6:9], v[224:227], v[194:197], v[6:9]
	v_mfma_f32_16x16x32_bf16 v[2:5], v[232:235], v[194:197], v[2:5]
	s_barrier
	s_add_u32 s4, s4, 0x100
	s_addc_u32 s5, s5, 0
	v_lshl_add_u64 v[138:139], v[138:139], 0, s[80:81]
	v_lshl_add_u64 v[136:137], v[136:137], 0, s[80:81]
	s_cmp_ge_u32 s23, s16
	s_mov_b32 s22, s23
	s_cbranch_scc0 .LBB0_332
	v_lshl_add_u32 v145, s57, 10, v142
	ds_read_b32 v136, v145
	v_lshl_or_b32 v138, s8, 7, v143
	v_lshl_add_u32 v146, s9, 8, v140
	v_ashrrev_i32_e32 v139, 31, v138
	v_lshlrev_b64 v[138:139], 1, v[138:139]
	s_waitcnt lgkmcnt(0)
	v_pk_mul_f32 v[148:149], v[126:127], v[136:137] op_sel_hi:[1,0]
	v_pk_mul_f32 v[154:155], v[94:95], v[136:137] op_sel_hi:[1,0]
	v_mul_f32_e32 v147, 0xbfb8aa3b, v148
	v_exp_f32_e32 v147, v147
	v_pk_mul_f32 v[150:151], v[128:129], v[136:137] op_sel_hi:[1,0]
	v_pk_mul_f32 v[152:153], v[96:97], v[136:137] op_sel_hi:[1,0]
	v_pk_mul_f32 v[158:159], v[122:123], v[136:137] op_sel_hi:[1,0]
	v_add_f32_e32 v147, 1.0, v147
	v_rcp_f32_e32 v147, v147
	v_pk_mul_f32 v[156:157], v[124:125], v[136:137] op_sel_hi:[1,0]
	v_pk_mul_f32 v[160:161], v[92:93], v[136:137] op_sel_hi:[1,0]
	v_pk_mul_f32 v[136:137], v[90:91], v[136:137] op_sel_hi:[1,0]
	v_mul_f32_e32 v147, v148, v147
	v_mul_f32_e32 v148, 0xbfb8aa3b, v149
	v_exp_f32_e32 v148, v148
	v_mul_f32_e32 v147, v154, v147
	s_and_b64 vcc, exec, s[42:43]
	v_add_f32_e32 v148, 1.0, v148
	v_rcp_f32_e32 v148, v148
	s_nop 0
	v_mul_f32_e32 v148, v149, v148
	v_mul_f32_e32 v148, v155, v148
	v_cvt_pk_bf16_f32 v148, v147, v148
	v_mul_f32_e32 v147, 0xbfb8aa3b, v150
	v_mul_f32_e32 v149, 0xbfb8aa3b, v151
	v_exp_f32_e32 v147, v147
	v_exp_f32_e32 v149, v149
	v_add_f32_e32 v147, 1.0, v147
	v_add_f32_e32 v149, 1.0, v149
	v_rcp_f32_e32 v147, v147
	v_rcp_f32_e32 v149, v149
	v_mul_f32_e32 v147, v150, v147
	v_mul_f32_e32 v149, v151, v149
	v_mul_f32_e32 v147, v152, v147
	v_mul_f32_e32 v149, v153, v149
	v_cvt_pk_bf16_f32 v149, v147, v149
	v_mul_f32_e32 v147, 0xbfb8aa3b, v158
	v_exp_f32_e32 v147, v147
	s_nop 0
	v_add_f32_e32 v147, 1.0, v147
	v_rcp_f32_e32 v147, v147
	s_nop 0
	v_mul_f32_e32 v147, v158, v147
	v_mul_f32_e32 v136, v136, v147
	v_mul_f32_e32 v147, 0xbfb8aa3b, v159
	v_exp_f32_e32 v147, v147
	s_nop 0
	v_add_f32_e32 v147, 1.0, v147
	v_rcp_f32_e32 v147, v147
	s_nop 0
	v_mul_f32_e32 v147, v159, v147
	v_mul_f32_e32 v137, v137, v147
	v_cvt_pk_bf16_f32 v150, v136, v137
	v_mul_f32_e32 v136, 0xbfb8aa3b, v156
	v_mul_f32_e32 v137, 0xbfb8aa3b, v157
	v_exp_f32_e32 v136, v136
	v_exp_f32_e32 v137, v137
	v_or_b32_e32 v147, 16, v146
	v_add_f32_e32 v136, 1.0, v136
	v_add_f32_e32 v137, 1.0, v137
	v_rcp_f32_e32 v136, v136
	v_rcp_f32_e32 v137, v137
	v_mul_f32_e32 v136, v156, v136
	v_mul_f32_e32 v137, v157, v137
	v_mul_f32_e32 v136, v160, v136
	v_mul_f32_e32 v137, v161, v137
	v_cvt_pk_bf16_f32 v151, v136, v137
	v_mov_b64_e32 v[136:137], s[6:7]
	v_mad_i64_i32 v[152:153], s[4:5], v146, s33, v[136:137]
	v_lshl_add_u64 v[152:153], v[152:153], 0, v[138:139]
	global_store_dwordx4 v[152:153], v[148:151], off
	ds_read_b32 v148, v145 offset:64
	s_waitcnt lgkmcnt(0)
; __device__ __forceinline__ unsigned pk2(float lo, float hi) { unsigned r; asm volatile("v_cvt_pk_bf16_f32 %0, %1, %2" : "=v"(r) : "v"(lo), "v"(hi)); return r; }
; __device__ __forceinline__ float siluf_(float x) { return x * __builtin_amdgcn_rcpf(1.0f + __expf(-x)); }
;     template <int mode> __device__ __forceinline__ void run(const f32x4 (&acc)[2][2][4][2], const Unit& u, int wr, int wc, int fr, int fq, const LAS float* sc) const {
;     ...
;         if (mode == 0) {
;             const int col0 = u.pn * HALF + wc * 32 + 8 * fq;
; #pragma unroll
;             for (int ai = 0; ai < 2; ++ai)
; #pragma unroll
;                 for (int m = 0; m < 4; ++m) {
;                     const int row = row0 + ai * HALF + m * 16;
;                     const float s = sc[ai * HALF + wr * 64 + m * 16 + fr];
;                     const f32x4 g0 = acc[ai][0][m][0] * s, u0 = acc[ai][1][m][0] * s, g1 = acc[ai][0][m][1] * s, u1 = acc[ai][1][m][1] * s;
;                     u32x4 w;
;                     w.x = pk2(siluf_(g0[0]) * u0[0], siluf_(g0[1]) * u0[1]); w.y = pk2(siluf_(g0[2]) * u0[2], siluf_(g0[3]) * u0[3]);
;                     w.z = pk2(siluf_(g1[0]) * u1[0], siluf_(g1[1]) * u1[1]); w.w = pk2(siluf_(g1[2]) * u1[2], siluf_(g1[3]) * u1[3]);
;                     *(u32x4*)(ob + (size_t)row * FF + col0) = w;
;                 }
	v_pk_mul_f32 v[152:153], v[118:119], v[148:149] op_sel_hi:[1,0]
	v_pk_mul_f32 v[150:151], v[120:121], v[148:149] op_sel_hi:[1,0]
	v_pk_mul_f32 v[154:155], v[88:89], v[148:149] op_sel_hi:[1,0]
	v_pk_mul_f32 v[156:157], v[86:87], v[148:149] op_sel_hi:[1,0]
	v_pk_mul_f32 v[158:159], v[116:117], v[148:149] op_sel_hi:[1,0]
	v_pk_mul_f32 v[160:161], v[114:115], v[148:149] op_sel_hi:[1,0]
	v_pk_mul_f32 v[162:163], v[84:85], v[148:149] op_sel_hi:[1,0]
	v_pk_mul_f32 v[164:165], v[82:83], v[148:149] op_sel_hi:[1,0]
	v_mul_f32_e32 v148, 0xbfb8aa3b, v152
	v_mul_f32_e32 v149, 0xbfb8aa3b, v153
	v_exp_f32_e32 v148, v148
	v_exp_f32_e32 v149, v149
	v_add_f32_e32 v148, 1.0, v148
	v_add_f32_e32 v149, 1.0, v149
	v_rcp_f32_e32 v148, v148
	v_rcp_f32_e32 v149, v149
	v_mul_f32_e32 v148, v152, v148
	v_mul_f32_e32 v149, v153, v149
	v_mul_f32_e32 v148, v156, v148
	v_mul_f32_e32 v149, v157, v149
	v_cvt_pk_bf16_f32 v148, v148, v149
	v_mul_f32_e32 v149, 0xbfb8aa3b, v150
	v_exp_f32_e32 v149, v149
	v_mul_f32_e32 v152, 0xbfb8aa3b, v159
	v_exp_f32_e32 v152, v152
	v_add_f32_e32 v149, 1.0, v149
	v_rcp_f32_e32 v149, v149
	v_add_f32_e32 v152, 1.0, v152
	v_rcp_f32_e32 v152, v152
	v_mul_f32_e32 v149, v150, v149
	v_mul_f32_e32 v150, 0xbfb8aa3b, v151
	v_exp_f32_e32 v150, v150
	v_mul_f32_e32 v149, v154, v149
	v_mul_f32_e32 v152, v159, v152
	v_mul_f32_e32 v152, v163, v152
	v_add_f32_e32 v150, 1.0, v150
	v_rcp_f32_e32 v150, v150
	s_nop 0
	v_mul_f32_e32 v150, v151, v150
	v_mul_f32_e32 v150, v155, v150
	v_cvt_pk_bf16_f32 v149, v149, v150
	v_mul_f32_e32 v150, 0xbfb8aa3b, v160
	v_mul_f32_e32 v151, 0xbfb8aa3b, v161
	v_exp_f32_e32 v150, v150
	v_exp_f32_e32 v151, v151
	v_add_f32_e32 v150, 1.0, v150
	v_add_f32_e32 v151, 1.0, v151
	v_rcp_f32_e32 v150, v150
	v_rcp_f32_e32 v151, v151
	v_mul_f32_e32 v150, v160, v150
	v_mul_f32_e32 v151, v161, v151
	v_mul_f32_e32 v150, v164, v150
	v_mul_f32_e32 v151, v165, v151
	v_cvt_pk_bf16_f32 v150, v150, v151
	v_mul_f32_e32 v151, 0xbfb8aa3b, v158
	v_exp_f32_e32 v151, v151
	s_nop 0
	v_add_f32_e32 v151, 1.0, v151
	v_rcp_f32_e32 v151, v151
	s_nop 0
	v_mul_f32_e32 v151, v158, v151
	v_mul_f32_e32 v151, v162, v151
	v_cvt_pk_bf16_f32 v151, v151, v152
	v_mad_i64_i32 v[152:153], s[4:5], v147, s33, v[136:137]
	v_lshl_add_u64 v[152:153], v[152:153], 0, v[138:139]
	global_store_dwordx4 v[152:153], v[148:151], off
	ds_read_b32 v148, v145 offset:128
	v_or_b32_e32 v147, 32, v146
	s_waitcnt lgkmcnt(0)
	v_pk_mul_f32 v[152:153], v[110:111], v[148:149] op_sel_hi:[1,0]
	v_pk_mul_f32 v[150:151], v[112:113], v[148:149] op_sel_hi:[1,0]
	v_pk_mul_f32 v[154:155], v[80:81], v[148:149] op_sel_hi:[1,0]
	v_pk_mul_f32 v[156:157], v[78:79], v[148:149] op_sel_hi:[1,0]
	v_pk_mul_f32 v[158:159], v[108:109], v[148:149] op_sel_hi:[1,0]
	v_pk_mul_f32 v[160:161], v[106:107], v[148:149] op_sel_hi:[1,0]
	v_pk_mul_f32 v[162:163], v[76:77], v[148:149] op_sel_hi:[1,0]
	v_pk_mul_f32 v[164:165], v[74:75], v[148:149] op_sel_hi:[1,0]
	v_mul_f32_e32 v148, 0xbfb8aa3b, v152
	v_mul_f32_e32 v149, 0xbfb8aa3b, v153
	v_exp_f32_e32 v148, v148
	v_exp_f32_e32 v149, v149
	v_add_f32_e32 v148, 1.0, v148
	v_add_f32_e32 v149, 1.0, v149
	v_rcp_f32_e32 v148, v148
	v_rcp_f32_e32 v149, v149
	v_mul_f32_e32 v148, v152, v148
	v_mul_f32_e32 v149, v153, v149
	v_mul_f32_e32 v148, v156, v148
	v_mul_f32_e32 v149, v157, v149
	v_cvt_pk_bf16_f32 v148, v148, v149
	v_mul_f32_e32 v149, 0xbfb8aa3b, v150
	v_exp_f32_e32 v149, v149
	v_mul_f32_e32 v152, 0xbfb8aa3b, v159
	v_exp_f32_e32 v152, v152
	v_add_f32_e32 v149, 1.0, v149
	v_rcp_f32_e32 v149, v149
	v_add_f32_e32 v152, 1.0, v152
	v_rcp_f32_e32 v152, v152
	v_mul_f32_e32 v149, v150, v149
	v_mul_f32_e32 v150, 0xbfb8aa3b, v151
	v_exp_f32_e32 v150, v150
	v_mul_f32_e32 v149, v154, v149
	v_mul_f32_e32 v152, v159, v152
	v_mul_f32_e32 v152, v163, v152
	v_add_f32_e32 v150, 1.0, v150
	v_rcp_f32_e32 v150, v150
	s_nop 0
	v_mul_f32_e32 v150, v151, v150
	v_mul_f32_e32 v150, v155, v150
	v_cvt_pk_bf16_f32 v149, v149, v150
	v_mul_f32_e32 v150, 0xbfb8aa3b, v160
	v_mul_f32_e32 v151, 0xbfb8aa3b, v161
	v_exp_f32_e32 v150, v150
	v_exp_f32_e32 v151, v151
	v_add_f32_e32 v150, 1.0, v150
	v_add_f32_e32 v151, 1.0, v151
	v_rcp_f32_e32 v150, v150
	v_rcp_f32_e32 v151, v151
	v_mul_f32_e32 v150, v160, v150
	v_mul_f32_e32 v151, v161, v151
	v_mul_f32_e32 v150, v164, v150
	v_mul_f32_e32 v151, v165, v151
	v_cvt_pk_bf16_f32 v150, v150, v151
	v_mul_f32_e32 v151, 0xbfb8aa3b, v158
	v_exp_f32_e32 v151, v151
	s_nop 0
	v_add_f32_e32 v151, 1.0, v151
	v_rcp_f32_e32 v151, v151
	s_nop 0
	v_mul_f32_e32 v151, v158, v151
	v_mul_f32_e32 v151, v162, v151
	v_cvt_pk_bf16_f32 v151, v151, v152
	v_mad_i64_i32 v[152:153], s[4:5], v147, s33, v[136:137]
	v_lshl_add_u64 v[152:153], v[152:153], 0, v[138:139]
	global_store_dwordx4 v[152:153], v[148:151], off
	ds_read_b32 v148, v145 offset:192
	v_or_b32_e32 v147, 48, v146
	s_waitcnt lgkmcnt(0)
; __device__ __forceinline__ unsigned pk2(float lo, float hi) { unsigned r; asm volatile("v_cvt_pk_bf16_f32 %0, %1, %2" : "=v"(r) : "v"(lo), "v"(hi)); return r; }
; __device__ __forceinline__ float siluf_(float x) { return x * __builtin_amdgcn_rcpf(1.0f + __expf(-x)); }
;     template <int mode> __device__ __forceinline__ void run(const f32x4 (&acc)[2][2][4][2], const Unit& u, int wr, int wc, int fr, int fq, const LAS float* sc) const {
;     ...
;         if (mode == 0) {
;             const int col0 = u.pn * HALF + wc * 32 + 8 * fq;
; #pragma unroll
;             for (int ai = 0; ai < 2; ++ai)
; #pragma unroll
;                 for (int m = 0; m < 4; ++m) {
;                     const int row = row0 + ai * HALF + m * 16;
;                     const float s = sc[ai * HALF + wr * 64 + m * 16 + fr];
;                     const f32x4 g0 = acc[ai][0][m][0] * s, u0 = acc[ai][1][m][0] * s, g1 = acc[ai][0][m][1] * s, u1 = acc[ai][1][m][1] * s;
;                     u32x4 w;
;                     w.x = pk2(siluf_(g0[0]) * u0[0], siluf_(g0[1]) * u0[1]); w.y = pk2(siluf_(g0[2]) * u0[2], siluf_(g0[3]) * u0[3]);
;                     w.z = pk2(siluf_(g1[0]) * u1[0], siluf_(g1[1]) * u1[1]); w.w = pk2(siluf_(g1[2]) * u1[2], siluf_(g1[3]) * u1[3]);
;                     *(u32x4*)(ob + (size_t)row * FF + col0) = w;
;                 }
	v_pk_mul_f32 v[152:153], v[102:103], v[148:149] op_sel_hi:[1,0]
	v_pk_mul_f32 v[150:151], v[104:105], v[148:149] op_sel_hi:[1,0]
	v_pk_mul_f32 v[154:155], v[72:73], v[148:149] op_sel_hi:[1,0]
	v_pk_mul_f32 v[156:157], v[70:71], v[148:149] op_sel_hi:[1,0]
	v_pk_mul_f32 v[158:159], v[100:101], v[148:149] op_sel_hi:[1,0]
	v_pk_mul_f32 v[160:161], v[98:99], v[148:149] op_sel_hi:[1,0]
	v_pk_mul_f32 v[162:163], v[68:69], v[148:149] op_sel_hi:[1,0]
	v_pk_mul_f32 v[164:165], v[66:67], v[148:149] op_sel_hi:[1,0]
	v_mul_f32_e32 v148, 0xbfb8aa3b, v152
	v_mul_f32_e32 v149, 0xbfb8aa3b, v153
	v_exp_f32_e32 v148, v148
	v_exp_f32_e32 v149, v149
	v_add_f32_e32 v148, 1.0, v148
	v_add_f32_e32 v149, 1.0, v149
	v_rcp_f32_e32 v148, v148
	v_rcp_f32_e32 v149, v149
	v_mul_f32_e32 v148, v152, v148
	v_mul_f32_e32 v149, v153, v149
	v_mul_f32_e32 v148, v156, v148
	v_mul_f32_e32 v149, v157, v149
	v_cvt_pk_bf16_f32 v148, v148, v149
	v_mul_f32_e32 v149, 0xbfb8aa3b, v150
	v_exp_f32_e32 v149, v149
	v_mul_f32_e32 v152, 0xbfb8aa3b, v159
	v_exp_f32_e32 v152, v152
	v_add_f32_e32 v149, 1.0, v149
	v_rcp_f32_e32 v149, v149
	v_add_f32_e32 v152, 1.0, v152
	v_rcp_f32_e32 v152, v152
	v_mul_f32_e32 v149, v150, v149
	v_mul_f32_e32 v150, 0xbfb8aa3b, v151
	v_exp_f32_e32 v150, v150
	v_mul_f32_e32 v149, v154, v149
	v_mul_f32_e32 v152, v159, v152
	v_mul_f32_e32 v152, v163, v152
	v_add_f32_e32 v150, 1.0, v150
	v_rcp_f32_e32 v150, v150
	s_nop 0
	v_mul_f32_e32 v150, v151, v150
	v_mul_f32_e32 v150, v155, v150
	v_cvt_pk_bf16_f32 v149, v149, v150
	v_mul_f32_e32 v150, 0xbfb8aa3b, v160
	v_mul_f32_e32 v151, 0xbfb8aa3b, v161
	v_exp_f32_e32 v150, v150
	v_exp_f32_e32 v151, v151
	v_add_f32_e32 v150, 1.0, v150
	v_add_f32_e32 v151, 1.0, v151
	v_rcp_f32_e32 v150, v150
	v_rcp_f32_e32 v151, v151
	v_mul_f32_e32 v150, v160, v150
	v_mul_f32_e32 v151, v161, v151
	v_mul_f32_e32 v150, v164, v150
	v_mul_f32_e32 v151, v165, v151
	v_cvt_pk_bf16_f32 v150, v150, v151
	v_mul_f32_e32 v151, 0xbfb8aa3b, v158
	v_exp_f32_e32 v151, v151
	s_nop 0
	v_add_f32_e32 v151, 1.0, v151
	v_rcp_f32_e32 v151, v151
	s_nop 0
	v_mul_f32_e32 v151, v158, v151
	v_mul_f32_e32 v151, v162, v151
	v_cvt_pk_bf16_f32 v151, v151, v152
	v_mad_i64_i32 v[152:153], s[4:5], v147, s33, v[136:137]
	v_lshl_add_u64 v[152:153], v[152:153], 0, v[138:139]
	global_store_dwordx4 v[152:153], v[148:151], off
	ds_read_b32 v148, v145 offset:512
	v_add_u32_e32 v147, 0x80, v146
	s_waitcnt lgkmcnt(0)
	v_pk_mul_f32 v[152:153], v[62:63], v[148:149] op_sel_hi:[1,0]
	v_pk_mul_f32 v[150:151], v[64:65], v[148:149] op_sel_hi:[1,0]
	v_pk_mul_f32 v[154:155], v[32:33], v[148:149] op_sel_hi:[1,0]
	v_pk_mul_f32 v[156:157], v[30:31], v[148:149] op_sel_hi:[1,0]
	v_pk_mul_f32 v[158:159], v[60:61], v[148:149] op_sel_hi:[1,0]
	v_pk_mul_f32 v[160:161], v[58:59], v[148:149] op_sel_hi:[1,0]
	v_pk_mul_f32 v[162:163], v[28:29], v[148:149] op_sel_hi:[1,0]
	v_pk_mul_f32 v[164:165], v[26:27], v[148:149] op_sel_hi:[1,0]
	v_mul_f32_e32 v148, 0xbfb8aa3b, v152
	v_mul_f32_e32 v149, 0xbfb8aa3b, v153
	v_exp_f32_e32 v148, v148
	v_exp_f32_e32 v149, v149
	v_add_f32_e32 v148, 1.0, v148
	v_add_f32_e32 v149, 1.0, v149
	v_rcp_f32_e32 v148, v148
	v_rcp_f32_e32 v149, v149
	v_mul_f32_e32 v148, v152, v148
	v_mul_f32_e32 v149, v153, v149
	v_mul_f32_e32 v148, v156, v148
	v_mul_f32_e32 v149, v157, v149
	v_cvt_pk_bf16_f32 v148, v148, v149
	v_mul_f32_e32 v149, 0xbfb8aa3b, v150
	v_exp_f32_e32 v149, v149
	v_mul_f32_e32 v152, 0xbfb8aa3b, v159
	v_exp_f32_e32 v152, v152
	v_add_f32_e32 v149, 1.0, v149
	v_rcp_f32_e32 v149, v149
	v_add_f32_e32 v152, 1.0, v152
	v_rcp_f32_e32 v152, v152
	v_mul_f32_e32 v149, v150, v149
	v_mul_f32_e32 v150, 0xbfb8aa3b, v151
	v_exp_f32_e32 v150, v150
	v_mul_f32_e32 v149, v154, v149
	v_mul_f32_e32 v152, v159, v152
	v_mul_f32_e32 v152, v163, v152
	v_add_f32_e32 v150, 1.0, v150
	v_rcp_f32_e32 v150, v150
	s_nop 0
	v_mul_f32_e32 v150, v151, v150
	v_mul_f32_e32 v150, v155, v150
	v_cvt_pk_bf16_f32 v149, v149, v150
	v_mul_f32_e32 v150, 0xbfb8aa3b, v160
	v_mul_f32_e32 v151, 0xbfb8aa3b, v161
	v_exp_f32_e32 v150, v150
	v_exp_f32_e32 v151, v151
	v_add_f32_e32 v150, 1.0, v150
	v_add_f32_e32 v151, 1.0, v151
	v_rcp_f32_e32 v150, v150
	v_rcp_f32_e32 v151, v151
	v_mul_f32_e32 v150, v160, v150
	v_mul_f32_e32 v151, v161, v151
	v_mul_f32_e32 v150, v164, v150
	v_mul_f32_e32 v151, v165, v151
	v_cvt_pk_bf16_f32 v150, v150, v151
	v_mul_f32_e32 v151, 0xbfb8aa3b, v158
	v_exp_f32_e32 v151, v151
	s_nop 0
	v_add_f32_e32 v151, 1.0, v151
	v_rcp_f32_e32 v151, v151
	s_nop 0
	v_mul_f32_e32 v151, v158, v151
	v_mul_f32_e32 v151, v162, v151
	v_cvt_pk_bf16_f32 v151, v151, v152
	v_mad_i64_i32 v[152:153], s[4:5], v147, s33, v[136:137]
	v_lshl_add_u64 v[152:153], v[152:153], 0, v[138:139]
	global_store_dwordx4 v[152:153], v[148:151], off
	ds_read_b32 v148, v145 offset:576
	v_add_u32_e32 v147, 0x90, v146
	s_waitcnt lgkmcnt(0)
; __device__ __forceinline__ unsigned pk2(float lo, float hi) { unsigned r; asm volatile("v_cvt_pk_bf16_f32 %0, %1, %2" : "=v"(r) : "v"(lo), "v"(hi)); return r; }
; __device__ __forceinline__ float siluf_(float x) { return x * __builtin_amdgcn_rcpf(1.0f + __expf(-x)); }
;     template <int mode> __device__ __forceinline__ void run(const f32x4 (&acc)[2][2][4][2], const Unit& u, int wr, int wc, int fr, int fq, const LAS float* sc) const {
;     ...
;         if (mode == 0) {
;             const int col0 = u.pn * HALF + wc * 32 + 8 * fq;
; #pragma unroll
;             for (int ai = 0; ai < 2; ++ai)
; #pragma unroll
;                 for (int m = 0; m < 4; ++m) {
;                     const int row = row0 + ai * HALF + m * 16;
;                     const float s = sc[ai * HALF + wr * 64 + m * 16 + fr];
;                     const f32x4 g0 = acc[ai][0][m][0] * s, u0 = acc[ai][1][m][0] * s, g1 = acc[ai][0][m][1] * s, u1 = acc[ai][1][m][1] * s;
;                     u32x4 w;
;                     w.x = pk2(siluf_(g0[0]) * u0[0], siluf_(g0[1]) * u0[1]); w.y = pk2(siluf_(g0[2]) * u0[2], siluf_(g0[3]) * u0[3]);
;                     w.z = pk2(siluf_(g1[0]) * u1[0], siluf_(g1[1]) * u1[1]); w.w = pk2(siluf_(g1[2]) * u1[2], siluf_(g1[3]) * u1[3]);
;                     *(u32x4*)(ob + (size_t)row * FF + col0) = w;
;                 }
	v_pk_mul_f32 v[152:153], v[54:55], v[148:149] op_sel_hi:[1,0]
	v_pk_mul_f32 v[150:151], v[56:57], v[148:149] op_sel_hi:[1,0]
	v_pk_mul_f32 v[154:155], v[24:25], v[148:149] op_sel_hi:[1,0]
	v_pk_mul_f32 v[156:157], v[22:23], v[148:149] op_sel_hi:[1,0]
	v_pk_mul_f32 v[158:159], v[52:53], v[148:149] op_sel_hi:[1,0]
	v_pk_mul_f32 v[160:161], v[50:51], v[148:149] op_sel_hi:[1,0]
	v_pk_mul_f32 v[162:163], v[20:21], v[148:149] op_sel_hi:[1,0]
	v_pk_mul_f32 v[164:165], v[18:19], v[148:149] op_sel_hi:[1,0]
	v_mul_f32_e32 v148, 0xbfb8aa3b, v152
	v_mul_f32_e32 v149, 0xbfb8aa3b, v153
	v_exp_f32_e32 v148, v148
	v_exp_f32_e32 v149, v149
	v_add_f32_e32 v148, 1.0, v148
	v_add_f32_e32 v149, 1.0, v149
	v_rcp_f32_e32 v148, v148
	v_rcp_f32_e32 v149, v149
	v_mul_f32_e32 v148, v152, v148
	v_mul_f32_e32 v149, v153, v149
	v_mul_f32_e32 v148, v156, v148
	v_mul_f32_e32 v149, v157, v149
	v_cvt_pk_bf16_f32 v148, v148, v149
	v_mul_f32_e32 v149, 0xbfb8aa3b, v150
	v_exp_f32_e32 v149, v149
	v_mul_f32_e32 v152, 0xbfb8aa3b, v159
	v_exp_f32_e32 v152, v152
	v_add_f32_e32 v149, 1.0, v149
	v_rcp_f32_e32 v149, v149
	v_add_f32_e32 v152, 1.0, v152
	v_rcp_f32_e32 v152, v152
	v_mul_f32_e32 v149, v150, v149
	v_mul_f32_e32 v150, 0xbfb8aa3b, v151
	v_exp_f32_e32 v150, v150
	v_mul_f32_e32 v149, v154, v149
	v_mul_f32_e32 v152, v159, v152
	v_mul_f32_e32 v152, v163, v152
	v_add_f32_e32 v150, 1.0, v150
	v_rcp_f32_e32 v150, v150
	s_nop 0
	v_mul_f32_e32 v150, v151, v150
	v_mul_f32_e32 v150, v155, v150
	v_cvt_pk_bf16_f32 v149, v149, v150
	v_mul_f32_e32 v150, 0xbfb8aa3b, v160
	v_mul_f32_e32 v151, 0xbfb8aa3b, v161
	v_exp_f32_e32 v150, v150
	v_exp_f32_e32 v151, v151
	v_add_f32_e32 v150, 1.0, v150
	v_add_f32_e32 v151, 1.0, v151
	v_rcp_f32_e32 v150, v150
	v_rcp_f32_e32 v151, v151
	v_mul_f32_e32 v150, v160, v150
	v_mul_f32_e32 v151, v161, v151
	v_mul_f32_e32 v150, v164, v150
	v_mul_f32_e32 v151, v165, v151
	v_cvt_pk_bf16_f32 v150, v150, v151
	v_mul_f32_e32 v151, 0xbfb8aa3b, v158
	v_exp_f32_e32 v151, v151
	s_nop 0
	v_add_f32_e32 v151, 1.0, v151
	v_rcp_f32_e32 v151, v151
	s_nop 0
	v_mul_f32_e32 v151, v158, v151
	v_mul_f32_e32 v151, v162, v151
	v_cvt_pk_bf16_f32 v151, v151, v152
	v_mad_i64_i32 v[152:153], s[4:5], v147, s33, v[136:137]
	v_lshl_add_u64 v[152:153], v[152:153], 0, v[138:139]
	global_store_dwordx4 v[152:153], v[148:151], off
	ds_read_b32 v148, v145 offset:640
	v_add_u32_e32 v147, 0xa0, v146
	s_waitcnt lgkmcnt(0)
	v_pk_mul_f32 v[152:153], v[46:47], v[148:149] op_sel_hi:[1,0]
	v_pk_mul_f32 v[150:151], v[48:49], v[148:149] op_sel_hi:[1,0]
	v_pk_mul_f32 v[154:155], v[16:17], v[148:149] op_sel_hi:[1,0]
	v_pk_mul_f32 v[156:157], v[14:15], v[148:149] op_sel_hi:[1,0]
	v_pk_mul_f32 v[158:159], v[44:45], v[148:149] op_sel_hi:[1,0]
	v_pk_mul_f32 v[160:161], v[42:43], v[148:149] op_sel_hi:[1,0]
	v_pk_mul_f32 v[162:163], v[12:13], v[148:149] op_sel_hi:[1,0]
	v_pk_mul_f32 v[164:165], v[10:11], v[148:149] op_sel_hi:[1,0]
	v_mul_f32_e32 v148, 0xbfb8aa3b, v152
	v_mul_f32_e32 v149, 0xbfb8aa3b, v153
	v_exp_f32_e32 v148, v148
	v_exp_f32_e32 v149, v149
	v_add_f32_e32 v148, 1.0, v148
	v_add_f32_e32 v149, 1.0, v149
	v_rcp_f32_e32 v148, v148
	v_rcp_f32_e32 v149, v149
	v_mul_f32_e32 v148, v152, v148
	v_mul_f32_e32 v149, v153, v149
	v_mul_f32_e32 v148, v156, v148
	v_mul_f32_e32 v149, v157, v149
	v_cvt_pk_bf16_f32 v148, v148, v149
	v_mul_f32_e32 v149, 0xbfb8aa3b, v150
	v_exp_f32_e32 v149, v149
	v_mul_f32_e32 v152, 0xbfb8aa3b, v159
	v_exp_f32_e32 v152, v152
	v_add_f32_e32 v149, 1.0, v149
	v_rcp_f32_e32 v149, v149
	v_add_f32_e32 v152, 1.0, v152
	v_rcp_f32_e32 v152, v152
	v_mul_f32_e32 v149, v150, v149
	v_mul_f32_e32 v150, 0xbfb8aa3b, v151
	v_exp_f32_e32 v150, v150
	v_mul_f32_e32 v149, v154, v149
	v_mul_f32_e32 v152, v159, v152
	v_mul_f32_e32 v152, v163, v152
	v_add_f32_e32 v150, 1.0, v150
	v_rcp_f32_e32 v150, v150
	s_nop 0
	v_mul_f32_e32 v150, v151, v150
	v_mul_f32_e32 v150, v155, v150
	v_cvt_pk_bf16_f32 v149, v149, v150
	v_mul_f32_e32 v150, 0xbfb8aa3b, v160
	v_mul_f32_e32 v151, 0xbfb8aa3b, v161
	v_exp_f32_e32 v150, v150
	v_exp_f32_e32 v151, v151
	v_add_f32_e32 v150, 1.0, v150
	v_add_f32_e32 v151, 1.0, v151
	v_rcp_f32_e32 v150, v150
	v_rcp_f32_e32 v151, v151
	v_mul_f32_e32 v150, v160, v150
	v_mul_f32_e32 v151, v161, v151
	v_mul_f32_e32 v150, v164, v150
	v_mul_f32_e32 v151, v165, v151
	v_cvt_pk_bf16_f32 v150, v150, v151
	v_mul_f32_e32 v151, 0xbfb8aa3b, v158
	v_exp_f32_e32 v151, v151
	v_add_u32_e32 v164, 0xb0, v146
	v_add_f32_e32 v151, 1.0, v151
	v_rcp_f32_e32 v151, v151
	s_nop 0
	v_mul_f32_e32 v151, v158, v151
	v_mul_f32_e32 v151, v162, v151
	v_cvt_pk_bf16_f32 v151, v151, v152
	ds_read_b32 v146, v145 offset:704
	v_mad_i64_i32 v[152:153], s[4:5], v147, s33, v[136:137]
	v_lshl_add_u64 v[152:153], v[152:153], 0, v[138:139]
	global_store_dwordx4 v[152:153], v[148:151], off
	s_waitcnt lgkmcnt(0)
; __device__ __forceinline__ unsigned pk2(float lo, float hi) { unsigned r; asm volatile("v_cvt_pk_bf16_f32 %0, %1, %2" : "=v"(r) : "v"(lo), "v"(hi)); return r; }
; __device__ __forceinline__ float siluf_(float x) { return x * __builtin_amdgcn_rcpf(1.0f + __expf(-x)); }
;     template <int mode> __device__ __forceinline__ void run(const f32x4 (&acc)[2][2][4][2], const Unit& u, int wr, int wc, int fr, int fq, const LAS float* sc) const {
;     ...
;                 for (int m = 0; m < 4; ++m) {
;                     const int row = row0 + ai * HALF + m * 16;
;                     const float s = sc[ai * HALF + wr * 64 + m * 16 + fr];
;                     const f32x4 g0 = acc[ai][0][m][0] * s, u0 = acc[ai][1][m][0] * s, g1 = acc[ai][0][m][1] * s, u1 = acc[ai][1][m][1] * s;
;                     u32x4 w;
;                     w.x = pk2(siluf_(g0[0]) * u0[0], siluf_(g0[1]) * u0[1]); w.y = pk2(siluf_(g0[2]) * u0[2], siluf_(g0[3]) * u0[3]);
;                     w.z = pk2(siluf_(g1[0]) * u1[0], siluf_(g1[1]) * u1[1]); w.w = pk2(siluf_(g1[2]) * u1[2], siluf_(g1[3]) * u1[3]);
;                     *(u32x4*)(ob + (size_t)row * FF + col0) = w;
;                 }
; template <int MODE, class EpiT, class Sched>
; __device__ __forceinline__ void gemm_phase(LAS unsigned char* lds, const Gemm g, const Sched& S, const EpiT& E) {
;     ...
; #pragma unroll
;         for (int a = 0; a < 2; ++a)
; #pragma unroll
;             for (int b = 0; b < 2; ++b)
; #pragma unroll
;                 for (int m = 0; m < 4; ++m)
; #pragma unroll
;                     for (int n = 0; n < 2; ++n) acc[a][b][m][n] = (f32x4){0.f, 0.f, 0.f, 0.f};
;         cur = nxt; cA = nA; cB = nB; ++ui;
	v_pk_mul_f32 v[152:153], v[8:9], v[146:147] op_sel_hi:[1,0]
	v_pk_mul_f32 v[154:155], v[6:7], v[146:147] op_sel_hi:[1,0]
	v_pk_mul_f32 v[150:151], v[38:39], v[146:147] op_sel_hi:[1,0]
	v_pk_mul_f32 v[148:149], v[40:41], v[146:147] op_sel_hi:[1,0]
	v_pk_mul_f32 v[156:157], v[36:37], v[146:147] op_sel_hi:[1,0]
	v_pk_mul_f32 v[158:159], v[34:35], v[146:147] op_sel_hi:[1,0]
	v_pk_mul_f32 v[160:161], v[4:5], v[146:147] op_sel_hi:[1,0]
	v_pk_mul_f32 v[162:163], v[2:3], v[146:147] op_sel_hi:[1,0]
	v_mul_f32_e32 v145, 0xbfb8aa3b, v150
	v_mul_f32_e32 v146, 0xbfb8aa3b, v151
	v_exp_f32_e32 v145, v145
	v_exp_f32_e32 v146, v146
	v_mul_f32_e32 v147, 0xbfb8aa3b, v149
	v_exp_f32_e32 v147, v147
	v_add_f32_e32 v145, 1.0, v145
	v_add_f32_e32 v146, 1.0, v146
	v_rcp_f32_e32 v145, v145
	v_rcp_f32_e32 v146, v146
	v_add_f32_e32 v147, 1.0, v147
	v_rcp_f32_e32 v147, v147
	v_mul_f32_e32 v145, v150, v145
	v_mul_f32_e32 v146, v151, v146
	v_mul_f32_e32 v145, v154, v145
	v_mul_f32_e32 v146, v155, v146
	v_cvt_pk_bf16_f32 v146, v145, v146
	v_mul_f32_e32 v145, 0xbfb8aa3b, v148
	v_exp_f32_e32 v145, v145
	v_mul_f32_e32 v147, v149, v147
	v_mul_f32_e32 v147, v153, v147
	v_mul_f32_e32 v149, 0xbfb8aa3b, v157
	v_add_f32_e32 v145, 1.0, v145
	v_rcp_f32_e32 v145, v145
	v_exp_f32_e32 v149, v149
	v_mad_i64_i32 v[136:137], s[4:5], v164, s33, v[136:137]
	v_mul_f32_e32 v145, v148, v145
	v_mul_f32_e32 v145, v152, v145
	v_cvt_pk_bf16_f32 v147, v145, v147
	v_mul_f32_e32 v145, 0xbfb8aa3b, v158
	v_mul_f32_e32 v148, 0xbfb8aa3b, v159
	v_exp_f32_e32 v145, v145
	v_exp_f32_e32 v148, v148
	v_add_f32_e32 v149, 1.0, v149
	v_rcp_f32_e32 v149, v149
	v_add_f32_e32 v145, 1.0, v145
	v_add_f32_e32 v148, 1.0, v148
	v_rcp_f32_e32 v145, v145
	v_rcp_f32_e32 v148, v148
	v_mul_f32_e32 v149, v157, v149
	v_mul_f32_e32 v149, v161, v149
	v_mul_f32_e32 v145, v158, v145
	v_mul_f32_e32 v148, v159, v148
	v_mul_f32_e32 v145, v162, v145
	v_mul_f32_e32 v148, v163, v148
	v_cvt_pk_bf16_f32 v148, v145, v148
	v_mul_f32_e32 v145, 0xbfb8aa3b, v156
	v_exp_f32_e32 v145, v145
	v_lshl_add_u64 v[136:137], v[136:137], 0, v[138:139]
	v_add_f32_e32 v145, 1.0, v145
	v_rcp_f32_e32 v145, v145
	s_nop 0
	v_mul_f32_e32 v145, v156, v145
	v_mul_f32_e32 v145, v160, v145
	v_cvt_pk_bf16_f32 v149, v145, v149
	global_store_dwordx4 v[136:137], v[146:149], off
	s_cbranch_vccnz .LBB0_324
	v_mov_b32_e32 v2, 0
	s_mov_b32 s9, s61
	s_mov_b32 s8, s60
	s_mov_b64 s[12:13], s[28:29]
	s_mov_b64 s[10:11], s[34:35]
	s_mov_b32 s57, s2
	v_mov_b32_e32 v3, v2
	v_mov_b32_e32 v4, v2
	v_mov_b32_e32 v5, v2
	v_mov_b32_e32 v6, v2
	v_mov_b32_e32 v7, v2
	v_mov_b32_e32 v8, v2
	v_mov_b32_e32 v9, v2
	v_mov_b32_e32 v10, v2
	v_mov_b32_e32 v11, v2
	v_mov_b32_e32 v12, v2
	v_mov_b32_e32 v13, v2
	v_mov_b32_e32 v14, v2
	v_mov_b32_e32 v15, v2
	v_mov_b32_e32 v16, v2
	v_mov_b32_e32 v17, v2
	v_mov_b32_e32 v18, v2
	v_mov_b32_e32 v19, v2
	v_mov_b32_e32 v20, v2
	v_mov_b32_e32 v21, v2
	v_mov_b32_e32 v22, v2
	v_mov_b32_e32 v23, v2
	v_mov_b32_e32 v24, v2
	v_mov_b32_e32 v25, v2
	v_mov_b32_e32 v26, v2
	v_mov_b32_e32 v27, v2
	v_mov_b32_e32 v28, v2
	v_mov_b32_e32 v29, v2
	v_mov_b32_e32 v30, v2
	v_mov_b32_e32 v31, v2
	v_mov_b32_e32 v32, v2
	v_mov_b32_e32 v33, v2
	v_mov_b32_e32 v34, v2
	v_mov_b32_e32 v35, v2
	v_mov_b32_e32 v36, v2
	v_mov_b32_e32 v37, v2
	v_mov_b32_e32 v38, v2
	v_mov_b32_e32 v39, v2
	v_mov_b32_e32 v40, v2
	v_mov_b32_e32 v41, v2
	v_mov_b32_e32 v42, v2
	v_mov_b32_e32 v43, v2
	v_mov_b32_e32 v44, v2
	v_mov_b32_e32 v45, v2
	v_mov_b32_e32 v46, v2
	v_mov_b32_e32 v47, v2
	v_mov_b32_e32 v48, v2
	v_mov_b32_e32 v49, v2
	v_mov_b32_e32 v50, v2
	v_mov_b32_e32 v51, v2
	v_mov_b32_e32 v52, v2
	v_mov_b32_e32 v53, v2
	v_mov_b32_e32 v54, v2
	v_mov_b32_e32 v55, v2
	v_mov_b32_e32 v56, v2
	v_mov_b32_e32 v57, v2
	v_mov_b32_e32 v58, v2
	v_mov_b32_e32 v59, v2
	v_mov_b32_e32 v60, v2
	v_mov_b32_e32 v61, v2
	v_mov_b32_e32 v62, v2
	v_mov_b32_e32 v63, v2
	v_mov_b32_e32 v64, v2
	v_mov_b32_e32 v65, v2
	v_mov_b32_e32 v66, v2
	v_mov_b32_e32 v67, v2
	v_mov_b32_e32 v68, v2
	v_mov_b32_e32 v69, v2
	v_mov_b32_e32 v70, v2
	v_mov_b32_e32 v71, v2
	v_mov_b32_e32 v72, v2
	v_mov_b32_e32 v73, v2
	v_mov_b32_e32 v74, v2
	v_mov_b32_e32 v75, v2
	v_mov_b32_e32 v76, v2
	v_mov_b32_e32 v77, v2
	v_mov_b32_e32 v78, v2
	v_mov_b32_e32 v79, v2
	v_mov_b32_e32 v80, v2
	v_mov_b32_e32 v81, v2
	v_mov_b32_e32 v82, v2
	v_mov_b32_e32 v83, v2
	v_mov_b32_e32 v84, v2
	v_mov_b32_e32 v85, v2
	v_mov_b32_e32 v86, v2
	v_mov_b32_e32 v87, v2
	v_mov_b32_e32 v88, v2
	v_mov_b32_e32 v89, v2
	v_mov_b32_e32 v90, v2
	v_mov_b32_e32 v91, v2
	v_mov_b32_e32 v92, v2
	v_mov_b32_e32 v93, v2
	v_mov_b32_e32 v94, v2
	v_mov_b32_e32 v95, v2
	v_mov_b32_e32 v96, v2
	v_mov_b32_e32 v97, v2
	v_mov_b32_e32 v98, v2
	v_mov_b32_e32 v99, v2
	v_mov_b32_e32 v100, v2
	v_mov_b32_e32 v101, v2
	v_mov_b32_e32 v102, v2
	v_mov_b32_e32 v103, v2
	v_mov_b32_e32 v104, v2
	v_mov_b32_e32 v105, v2
	v_mov_b32_e32 v106, v2
	v_mov_b32_e32 v107, v2
	v_mov_b32_e32 v108, v2
	v_mov_b32_e32 v109, v2
	v_mov_b32_e32 v110, v2
	v_mov_b32_e32 v111, v2
	v_mov_b32_e32 v112, v2
	v_mov_b32_e32 v113, v2
	v_mov_b32_e32 v114, v2
	v_mov_b32_e32 v115, v2
	v_mov_b32_e32 v116, v2
	v_mov_b32_e32 v117, v2
	v_mov_b32_e32 v118, v2
	v_mov_b32_e32 v119, v2
	v_mov_b32_e32 v120, v2
	v_mov_b32_e32 v121, v2
	v_mov_b32_e32 v122, v2
	v_mov_b32_e32 v123, v2
	v_mov_b32_e32 v124, v2
	v_mov_b32_e32 v125, v2
	v_mov_b32_e32 v126, v2
	v_mov_b32_e32 v127, v2
	v_mov_b32_e32 v128, v2
	v_mov_b32_e32 v129, v2
	s_branch .LBB0_324
